# nt (streaming) hint on hid stores in UP epilogues (P4/P9) to keep GEMM operands in L2
# baseline (speedup 1.0000x reference)
.LBB0_338:
	s_lshr_b32 s8, s13, 2
	s_and_b32 s10, s16, 56
	s_and_b32 s8, s8, 0x1ffffc0
	s_or_b32 s10, s10, s3
	s_or_b32 s8, s10, s8
	s_lshl_b32 s8, s8, 7
	s_lshl_b64 s[24:25], s[8:9], 11
	v_lshl_add_u64 v[78:79], v[68:69], 0, s[24:25]
	v_add_co_u32_e32 v80, vcc, s18, v78
	s_and_b32 s10, s14, 0xf80
	s_nop 0
	v_addc_co_u32_e32 v81, vcc, 0, v79, vcc
	s_lshl_b32 s26, s10, 11
	s_mov_b32 s27, s9
	v_add_co_u32_e32 v82, vcc, s19, v78
	v_lshl_add_u64 v[76:77], v[70:71], 0, s[26:27]
	s_nop 0
	v_addc_co_u32_e32 v83, vcc, 0, v79, vcc
	v_add_co_u32_e32 v84, vcc, s18, v76
	global_load_dwordx4 v[2:5], v[78:79], off
	global_load_dwordx4 v[6:9], v[80:81], off
	v_addc_co_u32_e32 v85, vcc, 0, v77, vcc
	v_add_co_u32_e32 v86, vcc, s19, v76
	global_load_dwordx4 v[10:13], v[82:83], off
	global_load_dwordx4 v[14:17], v[76:77], off
	v_addc_co_u32_e32 v87, vcc, 0, v77, vcc
	global_load_dwordx4 v[18:21], v[84:85], off
	global_load_dwordx4 v[22:25], v[86:87], off
	v_add_co_u32_e32 v88, vcc, s20, v76
	s_nop 1
	v_addc_co_u32_e32 v89, vcc, 0, v77, vcc
	global_load_dwordx4 v[26:29], v[88:89], off
	v_add_co_u32_e32 v90, vcc, s20, v78
	s_nop 1
	v_addc_co_u32_e32 v91, vcc, 0, v79, vcc
	global_load_dwordx4 v[30:33], v[90:91], off
	global_load_dwordx4 v[148:151], v[76:77], off offset:128
	global_load_dwordx4 v[152:155], v[84:85], off offset:128
	global_load_dwordx4 v[156:159], v[86:87], off offset:128
	global_load_dwordx4 v[160:163], v[88:89], off offset:128
	global_load_dwordx4 v[164:167], v[78:79], off offset:128
	global_load_dwordx4 v[168:171], v[80:81], off offset:128
	global_load_dwordx4 v[172:175], v[82:83], off offset:128
	global_load_dwordx4 v[176:179], v[90:91], off offset:128
	s_waitcnt vmcnt(12)
	ds_write_b128 v1, v[14:17] offset:36864
	s_waitcnt vmcnt(11)
	ds_write_b128 v1, v[18:21] offset:41472
	s_waitcnt vmcnt(10)
	ds_write_b128 v1, v[22:25] offset:46080
	s_waitcnt vmcnt(9)
	ds_write_b128 v1, v[26:29] offset:50688
	ds_write_b128 v1, v[2:5]
	ds_write_b128 v1, v[6:9] offset:4608
	ds_write_b128 v1, v[10:13] offset:9216
	s_waitcnt vmcnt(8)
	ds_write_b128 v1, v[30:33] offset:13824
	s_waitcnt lgkmcnt(0)
	s_barrier
	global_load_dwordx4 v[180:183], v[80:81], off offset:256
	global_load_dwordx4 v[184:187], v[82:83], off offset:256
	global_load_dwordx4 v[188:191], v[78:79], off offset:256
	global_load_dwordx4 v[192:195], v[76:77], off offset:256
	global_load_dwordx4 v[196:199], v[90:91], off offset:256
	global_load_dwordx4 v[200:203], v[84:85], off offset:256
	global_load_dwordx4 v[204:207], v[86:87], off offset:256
	global_load_dwordx4 v[208:211], v[88:89], off offset:256
	ds_read_b128 v[18:21], v72
	ds_read_b128 v[34:37], v73 offset:36864
	ds_read_b128 v[212:215], v72 offset:32
	ds_read_b128 v[216:219], v73 offset:36896
	ds_read_b128 v[50:53], v73 offset:41472
	ds_read_b128 v[220:223], v73 offset:41504
	ds_read_b128 v[54:57], v72 offset:4608
	ds_read_b128 v[224:227], v72 offset:4640
	s_waitcnt lgkmcnt(6)
	v_mfma_f32_32x32x16_bf16 v[2:17], v[18:21], v[34:37], 0
	s_waitcnt lgkmcnt(3)
	v_mfma_f32_32x32x16_bf16 v[18:33], v[18:21], v[50:53], 0
	s_waitcnt lgkmcnt(1)
	v_mfma_f32_32x32x16_bf16 v[34:49], v[54:57], v[34:37], 0
	v_mfma_f32_32x32x16_bf16 v[50:65], v[54:57], v[50:53], 0
	v_mfma_f32_32x32x16_bf16 v[2:17], v[212:215], v[216:219], v[2:17]
	v_mfma_f32_32x32x16_bf16 v[18:33], v[212:215], v[220:223], v[18:33]
	s_waitcnt lgkmcnt(0)
	v_mfma_f32_32x32x16_bf16 v[34:49], v[224:227], v[216:219], v[34:49]
	v_mfma_f32_32x32x16_bf16 v[50:65], v[224:227], v[220:223], v[50:65]
	ds_read_b128 v[212:215], v72 offset:64
	ds_read_b128 v[216:219], v73 offset:36928
	ds_read_b128 v[220:223], v72 offset:96
	ds_read_b128 v[224:227], v73 offset:36960
	ds_read_b128 v[228:231], v73 offset:41536
	ds_read_b128 v[232:235], v73 offset:41568
	s_waitcnt lgkmcnt(4)
	v_mfma_f32_32x32x16_bf16 v[2:17], v[212:215], v[216:219], v[2:17]
	s_waitcnt lgkmcnt(1)
	v_mfma_f32_32x32x16_bf16 v[18:33], v[212:215], v[228:231], v[18:33]
	ds_read_b128 v[212:215], v72 offset:4672
	ds_read_b128 v[236:239], v72 offset:4704
	s_waitcnt vmcnt(11)
	ds_write_b128 v1, v[164:167] offset:18432
	s_waitcnt vmcnt(10)
	ds_write_b128 v1, v[168:171] offset:23040
	s_waitcnt vmcnt(9)
	ds_write_b128 v1, v[172:175] offset:27648
	s_waitcnt vmcnt(8)
	ds_write_b128 v1, v[176:179] offset:32256
	ds_write_b128 v1, v[148:151] offset:55296
	ds_write_b128 v1, v[152:155] offset:59904
	ds_write_b128 v1, v[156:159] offset:64512
	ds_write_b128 v92, v[160:163] offset:32256
	global_load_dwordx4 v[148:151], v[80:81], off offset:384
	global_load_dwordx4 v[152:155], v[82:83], off offset:384
	global_load_dwordx4 v[156:159], v[78:79], off offset:384
	global_load_dwordx4 v[160:163], v[76:77], off offset:384
	global_load_dwordx4 v[164:167], v[90:91], off offset:384
	global_load_dwordx4 v[168:171], v[84:85], off offset:384
	global_load_dwordx4 v[172:175], v[86:87], off offset:384
	global_load_dwordx4 v[176:179], v[88:89], off offset:384
	s_waitcnt lgkmcnt(0)
	s_barrier
	v_mfma_f32_32x32x16_bf16 v[34:49], v[212:215], v[216:219], v[34:49]
	v_mfma_f32_32x32x16_bf16 v[50:65], v[212:215], v[228:231], v[50:65]
	v_mfma_f32_32x32x16_bf16 v[2:17], v[220:223], v[224:227], v[2:17]
	v_mfma_f32_32x32x16_bf16 v[18:33], v[220:223], v[232:235], v[18:33]
	v_mfma_f32_32x32x16_bf16 v[34:49], v[236:239], v[224:227], v[34:49]
	v_mfma_f32_32x32x16_bf16 v[50:65], v[236:239], v[232:235], v[50:65]
	ds_read_b128 v[212:215], v72 offset:18432
	ds_read_b128 v[216:219], v73 offset:55296
	ds_read_b128 v[220:223], v72 offset:18464
	ds_read_b128 v[224:227], v73 offset:55328
	ds_read_b128 v[228:231], v73 offset:59904
	ds_read_b128 v[232:235], v73 offset:59936
	s_waitcnt lgkmcnt(4)
	v_mfma_f32_32x32x16_bf16 v[2:17], v[212:215], v[216:219], v[2:17]
	s_waitcnt lgkmcnt(1)
	v_mfma_f32_32x32x16_bf16 v[18:33], v[212:215], v[228:231], v[18:33]
	ds_read_b128 v[212:215], v72 offset:23040
	ds_read_b128 v[236:239], v72 offset:23072
	s_waitcnt lgkmcnt(1)
	v_mfma_f32_32x32x16_bf16 v[34:49], v[212:215], v[216:219], v[34:49]
	v_mfma_f32_32x32x16_bf16 v[50:65], v[212:215], v[228:231], v[50:65]
	v_mfma_f32_32x32x16_bf16 v[2:17], v[220:223], v[224:227], v[2:17]
	v_mfma_f32_32x32x16_bf16 v[18:33], v[220:223], v[232:235], v[18:33]
	s_waitcnt lgkmcnt(0)
	v_mfma_f32_32x32x16_bf16 v[34:49], v[236:239], v[224:227], v[34:49]
	ds_read_b128 v[212:215], v72 offset:18496
	ds_read_b128 v[216:219], v73 offset:55360
	ds_read_b128 v[220:223], v72 offset:18528
	ds_read_b128 v[224:227], v73 offset:55392
	v_mfma_f32_32x32x16_bf16 v[50:65], v[236:239], v[232:235], v[50:65]
	ds_read_b128 v[228:231], v73 offset:59968
	ds_read_b128 v[232:235], v73 offset:60000
	s_waitcnt lgkmcnt(4)
	v_mfma_f32_32x32x16_bf16 v[2:17], v[212:215], v[216:219], v[2:17]
	s_waitcnt lgkmcnt(1)
	v_mfma_f32_32x32x16_bf16 v[18:33], v[212:215], v[228:231], v[18:33]
	ds_read_b128 v[212:215], v72 offset:23104
	ds_read_b128 v[236:239], v72 offset:23136
	s_waitcnt vmcnt(13)
	ds_write_b128 v1, v[188:191]
	ds_write_b128 v1, v[180:183] offset:4608
	ds_write_b128 v1, v[184:187] offset:9216
	s_waitcnt vmcnt(11)
	ds_write_b128 v1, v[196:199] offset:13824
	ds_write_b128 v1, v[192:195] offset:36864
	s_waitcnt vmcnt(10)
	ds_write_b128 v1, v[200:203] offset:41472
	s_waitcnt vmcnt(9)
	ds_write_b128 v1, v[204:207] offset:46080
	s_waitcnt vmcnt(8)
	ds_write_b128 v1, v[208:211] offset:50688
	global_load_dwordx4 v[180:183], v[80:81], off offset:512
	global_load_dwordx4 v[184:187], v[82:83], off offset:512
	global_load_dwordx4 v[188:191], v[78:79], off offset:512
	global_load_dwordx4 v[192:195], v[76:77], off offset:512
	global_load_dwordx4 v[196:199], v[90:91], off offset:512
	global_load_dwordx4 v[200:203], v[84:85], off offset:512
	global_load_dwordx4 v[204:207], v[86:87], off offset:512
	global_load_dwordx4 v[208:211], v[88:89], off offset:512
	s_waitcnt lgkmcnt(0)
	s_barrier
	v_mfma_f32_32x32x16_bf16 v[34:49], v[212:215], v[216:219], v[34:49]
	v_mfma_f32_32x32x16_bf16 v[50:65], v[212:215], v[228:231], v[50:65]
	v_mfma_f32_32x32x16_bf16 v[2:17], v[220:223], v[224:227], v[2:17]
	v_mfma_f32_32x32x16_bf16 v[18:33], v[220:223], v[232:235], v[18:33]
	v_mfma_f32_32x32x16_bf16 v[34:49], v[236:239], v[224:227], v[34:49]
	v_mfma_f32_32x32x16_bf16 v[50:65], v[236:239], v[232:235], v[50:65]
	ds_read_b128 v[212:215], v72
	ds_read_b128 v[216:219], v73 offset:36864
	ds_read_b128 v[220:223], v72 offset:32
	ds_read_b128 v[224:227], v73 offset:36896
	ds_read_b128 v[228:231], v73 offset:41472
	ds_read_b128 v[232:235], v73 offset:41504
	s_waitcnt lgkmcnt(4)
	v_mfma_f32_32x32x16_bf16 v[2:17], v[212:215], v[216:219], v[2:17]
	s_waitcnt lgkmcnt(1)
	v_mfma_f32_32x32x16_bf16 v[18:33], v[212:215], v[228:231], v[18:33]
	ds_read_b128 v[212:215], v72 offset:4608
	ds_read_b128 v[236:239], v72 offset:4640
	s_waitcnt lgkmcnt(1)
	v_mfma_f32_32x32x16_bf16 v[34:49], v[212:215], v[216:219], v[34:49]
	v_mfma_f32_32x32x16_bf16 v[50:65], v[212:215], v[228:231], v[50:65]
	v_mfma_f32_32x32x16_bf16 v[2:17], v[220:223], v[224:227], v[2:17]
	v_mfma_f32_32x32x16_bf16 v[18:33], v[220:223], v[232:235], v[18:33]
	s_waitcnt lgkmcnt(0)
	v_mfma_f32_32x32x16_bf16 v[34:49], v[236:239], v[224:227], v[34:49]
	ds_read_b128 v[212:215], v72 offset:64
	ds_read_b128 v[216:219], v73 offset:36928
	ds_read_b128 v[220:223], v72 offset:96
	ds_read_b128 v[224:227], v73 offset:36960
	v_mfma_f32_32x32x16_bf16 v[50:65], v[236:239], v[232:235], v[50:65]
	ds_read_b128 v[228:231], v73 offset:41536
	ds_read_b128 v[232:235], v73 offset:41568
	s_waitcnt lgkmcnt(4)
	v_mfma_f32_32x32x16_bf16 v[2:17], v[212:215], v[216:219], v[2:17]
	s_waitcnt lgkmcnt(1)
	v_mfma_f32_32x32x16_bf16 v[18:33], v[212:215], v[228:231], v[18:33]
	ds_read_b128 v[212:215], v72 offset:4672
	ds_read_b128 v[236:239], v72 offset:4704
	s_waitcnt vmcnt(13)
	ds_write_b128 v1, v[156:159] offset:18432
	ds_write_b128 v1, v[148:151] offset:23040
	ds_write_b128 v1, v[152:155] offset:27648
	s_waitcnt vmcnt(11)
	ds_write_b128 v1, v[164:167] offset:32256
	ds_write_b128 v1, v[160:163] offset:55296
	s_waitcnt vmcnt(10)
	ds_write_b128 v1, v[168:171] offset:59904
	s_waitcnt vmcnt(9)
	ds_write_b128 v1, v[172:175] offset:64512
	s_waitcnt vmcnt(8)
	ds_write_b128 v92, v[176:179] offset:32256
	global_load_dwordx4 v[148:151], v[80:81], off offset:640
	global_load_dwordx4 v[152:155], v[82:83], off offset:640
	global_load_dwordx4 v[156:159], v[78:79], off offset:640
	global_load_dwordx4 v[160:163], v[76:77], off offset:640
	global_load_dwordx4 v[164:167], v[90:91], off offset:640
	global_load_dwordx4 v[168:171], v[84:85], off offset:640
	global_load_dwordx4 v[172:175], v[86:87], off offset:640
	global_load_dwordx4 v[176:179], v[88:89], off offset:640
	s_waitcnt lgkmcnt(0)
	s_barrier
	v_mfma_f32_32x32x16_bf16 v[34:49], v[212:215], v[216:219], v[34:49]
	v_mfma_f32_32x32x16_bf16 v[50:65], v[212:215], v[228:231], v[50:65]
	v_mfma_f32_32x32x16_bf16 v[2:17], v[220:223], v[224:227], v[2:17]
	v_mfma_f32_32x32x16_bf16 v[18:33], v[220:223], v[232:235], v[18:33]
	v_mfma_f32_32x32x16_bf16 v[34:49], v[236:239], v[224:227], v[34:49]
	v_mfma_f32_32x32x16_bf16 v[50:65], v[236:239], v[232:235], v[50:65]
	ds_read_b128 v[212:215], v72 offset:18432
	ds_read_b128 v[216:219], v73 offset:55296
	ds_read_b128 v[220:223], v72 offset:18464
	ds_read_b128 v[224:227], v73 offset:55328
	ds_read_b128 v[228:231], v73 offset:59904
	ds_read_b128 v[232:235], v73 offset:59936
	s_waitcnt lgkmcnt(4)
	v_mfma_f32_32x32x16_bf16 v[2:17], v[212:215], v[216:219], v[2:17]
	s_waitcnt lgkmcnt(1)
	v_mfma_f32_32x32x16_bf16 v[18:33], v[212:215], v[228:231], v[18:33]
	ds_read_b128 v[212:215], v72 offset:23040
	ds_read_b128 v[236:239], v72 offset:23072
	s_waitcnt lgkmcnt(1)
	v_mfma_f32_32x32x16_bf16 v[34:49], v[212:215], v[216:219], v[34:49]
	v_mfma_f32_32x32x16_bf16 v[50:65], v[212:215], v[228:231], v[50:65]
	v_mfma_f32_32x32x16_bf16 v[2:17], v[220:223], v[224:227], v[2:17]
	v_mfma_f32_32x32x16_bf16 v[18:33], v[220:223], v[232:235], v[18:33]
	s_waitcnt lgkmcnt(0)
	v_mfma_f32_32x32x16_bf16 v[34:49], v[236:239], v[224:227], v[34:49]
	ds_read_b128 v[212:215], v72 offset:18496
	ds_read_b128 v[216:219], v73 offset:55360
	ds_read_b128 v[220:223], v72 offset:18528
	ds_read_b128 v[224:227], v73 offset:55392
	v_mfma_f32_32x32x16_bf16 v[50:65], v[236:239], v[232:235], v[50:65]
	ds_read_b128 v[228:231], v73 offset:59968
	ds_read_b128 v[232:235], v73 offset:60000
	s_waitcnt lgkmcnt(4)
	v_mfma_f32_32x32x16_bf16 v[2:17], v[212:215], v[216:219], v[2:17]
	s_waitcnt lgkmcnt(1)
	v_mfma_f32_32x32x16_bf16 v[18:33], v[212:215], v[228:231], v[18:33]
	ds_read_b128 v[212:215], v72 offset:23104
	ds_read_b128 v[236:239], v72 offset:23136
	s_waitcnt vmcnt(13)
	ds_write_b128 v1, v[188:191]
	ds_write_b128 v1, v[180:183] offset:4608
	ds_write_b128 v1, v[184:187] offset:9216
	s_waitcnt vmcnt(11)
	ds_write_b128 v1, v[196:199] offset:13824
	ds_write_b128 v1, v[192:195] offset:36864
	s_waitcnt vmcnt(10)
	ds_write_b128 v1, v[200:203] offset:41472
	s_waitcnt vmcnt(9)
	ds_write_b128 v1, v[204:207] offset:46080
	s_waitcnt vmcnt(8)
	ds_write_b128 v1, v[208:211] offset:50688
	global_load_dwordx4 v[180:183], v[80:81], off offset:768
	global_load_dwordx4 v[184:187], v[82:83], off offset:768
	global_load_dwordx4 v[188:191], v[78:79], off offset:768
	global_load_dwordx4 v[192:195], v[76:77], off offset:768
	global_load_dwordx4 v[196:199], v[90:91], off offset:768
	global_load_dwordx4 v[200:203], v[84:85], off offset:768
	global_load_dwordx4 v[204:207], v[86:87], off offset:768
	global_load_dwordx4 v[208:211], v[88:89], off offset:768
	s_waitcnt lgkmcnt(0)
	s_barrier
	v_mfma_f32_32x32x16_bf16 v[34:49], v[212:215], v[216:219], v[34:49]
	v_mfma_f32_32x32x16_bf16 v[50:65], v[212:215], v[228:231], v[50:65]
	v_mfma_f32_32x32x16_bf16 v[2:17], v[220:223], v[224:227], v[2:17]
	v_mfma_f32_32x32x16_bf16 v[18:33], v[220:223], v[232:235], v[18:33]
	v_mfma_f32_32x32x16_bf16 v[34:49], v[236:239], v[224:227], v[34:49]
	v_mfma_f32_32x32x16_bf16 v[50:65], v[236:239], v[232:235], v[50:65]
	ds_read_b128 v[212:215], v72
	ds_read_b128 v[216:219], v73 offset:36864
	ds_read_b128 v[220:223], v72 offset:32
	ds_read_b128 v[224:227], v73 offset:36896
	ds_read_b128 v[228:231], v73 offset:41472
	ds_read_b128 v[232:235], v73 offset:41504
	s_waitcnt lgkmcnt(4)
	v_mfma_f32_32x32x16_bf16 v[2:17], v[212:215], v[216:219], v[2:17]
	s_waitcnt lgkmcnt(1)
	v_mfma_f32_32x32x16_bf16 v[18:33], v[212:215], v[228:231], v[18:33]
	ds_read_b128 v[212:215], v72 offset:4608
	ds_read_b128 v[236:239], v72 offset:4640
	s_waitcnt lgkmcnt(1)
	v_mfma_f32_32x32x16_bf16 v[34:49], v[212:215], v[216:219], v[34:49]
	v_mfma_f32_32x32x16_bf16 v[50:65], v[212:215], v[228:231], v[50:65]
	v_mfma_f32_32x32x16_bf16 v[2:17], v[220:223], v[224:227], v[2:17]
	v_mfma_f32_32x32x16_bf16 v[18:33], v[220:223], v[232:235], v[18:33]
	s_waitcnt lgkmcnt(0)
	v_mfma_f32_32x32x16_bf16 v[34:49], v[236:239], v[224:227], v[34:49]
	ds_read_b128 v[212:215], v72 offset:64
	ds_read_b128 v[216:219], v73 offset:36928
	ds_read_b128 v[220:223], v72 offset:96
	ds_read_b128 v[224:227], v73 offset:36960
	v_mfma_f32_32x32x16_bf16 v[50:65], v[236:239], v[232:235], v[50:65]
	ds_read_b128 v[228:231], v73 offset:41536
	ds_read_b128 v[232:235], v73 offset:41568
	s_waitcnt lgkmcnt(4)
	v_mfma_f32_32x32x16_bf16 v[2:17], v[212:215], v[216:219], v[2:17]
	s_waitcnt lgkmcnt(1)
	v_mfma_f32_32x32x16_bf16 v[18:33], v[212:215], v[228:231], v[18:33]
	ds_read_b128 v[212:215], v72 offset:4672
	ds_read_b128 v[236:239], v72 offset:4704
	s_waitcnt vmcnt(13)
	ds_write_b128 v1, v[156:159] offset:18432
	ds_write_b128 v1, v[148:151] offset:23040
	ds_write_b128 v1, v[152:155] offset:27648
	s_waitcnt vmcnt(11)
	ds_write_b128 v1, v[164:167] offset:32256
	ds_write_b128 v1, v[160:163] offset:55296
	s_waitcnt vmcnt(10)
	ds_write_b128 v1, v[168:171] offset:59904
	s_waitcnt vmcnt(9)
	ds_write_b128 v1, v[172:175] offset:64512
	s_waitcnt vmcnt(8)
	ds_write_b128 v92, v[176:179] offset:32256
	global_load_dwordx4 v[148:151], v[80:81], off offset:896
	global_load_dwordx4 v[152:155], v[82:83], off offset:896
	global_load_dwordx4 v[156:159], v[78:79], off offset:896
	global_load_dwordx4 v[160:163], v[76:77], off offset:896
	global_load_dwordx4 v[164:167], v[90:91], off offset:896
	global_load_dwordx4 v[168:171], v[84:85], off offset:896
	global_load_dwordx4 v[172:175], v[86:87], off offset:896
	global_load_dwordx4 v[176:179], v[88:89], off offset:896
	s_waitcnt lgkmcnt(0)
	s_barrier
	v_mfma_f32_32x32x16_bf16 v[34:49], v[212:215], v[216:219], v[34:49]
	v_mfma_f32_32x32x16_bf16 v[50:65], v[212:215], v[228:231], v[50:65]
	v_mfma_f32_32x32x16_bf16 v[2:17], v[220:223], v[224:227], v[2:17]
	v_mfma_f32_32x32x16_bf16 v[18:33], v[220:223], v[232:235], v[18:33]
	v_mfma_f32_32x32x16_bf16 v[34:49], v[236:239], v[224:227], v[34:49]
	v_mfma_f32_32x32x16_bf16 v[50:65], v[236:239], v[232:235], v[50:65]
	ds_read_b128 v[212:215], v72 offset:18432
	ds_read_b128 v[216:219], v73 offset:55296
	ds_read_b128 v[220:223], v72 offset:18464
	ds_read_b128 v[224:227], v73 offset:55328
	ds_read_b128 v[228:231], v73 offset:59904
	ds_read_b128 v[232:235], v73 offset:59936
	s_waitcnt lgkmcnt(4)
	v_mfma_f32_32x32x16_bf16 v[2:17], v[212:215], v[216:219], v[2:17]
	s_waitcnt lgkmcnt(1)
	v_mfma_f32_32x32x16_bf16 v[18:33], v[212:215], v[228:231], v[18:33]
	ds_read_b128 v[212:215], v72 offset:23040
	ds_read_b128 v[236:239], v72 offset:23072
	s_waitcnt lgkmcnt(1)
	v_mfma_f32_32x32x16_bf16 v[34:49], v[212:215], v[216:219], v[34:49]
	v_mfma_f32_32x32x16_bf16 v[50:65], v[212:215], v[228:231], v[50:65]
	v_mfma_f32_32x32x16_bf16 v[2:17], v[220:223], v[224:227], v[2:17]
	v_mfma_f32_32x32x16_bf16 v[18:33], v[220:223], v[232:235], v[18:33]
	s_waitcnt lgkmcnt(0)
	v_mfma_f32_32x32x16_bf16 v[34:49], v[236:239], v[224:227], v[34:49]
	ds_read_b128 v[212:215], v72 offset:18496
	ds_read_b128 v[216:219], v73 offset:55360
	ds_read_b128 v[220:223], v72 offset:18528
	ds_read_b128 v[224:227], v73 offset:55392
	v_mfma_f32_32x32x16_bf16 v[50:65], v[236:239], v[232:235], v[50:65]
	ds_read_b128 v[228:231], v73 offset:59968
	ds_read_b128 v[232:235], v73 offset:60000
	s_waitcnt lgkmcnt(4)
	v_mfma_f32_32x32x16_bf16 v[2:17], v[212:215], v[216:219], v[2:17]
	s_waitcnt lgkmcnt(1)
	v_mfma_f32_32x32x16_bf16 v[18:33], v[212:215], v[228:231], v[18:33]
	ds_read_b128 v[212:215], v72 offset:23104
	ds_read_b128 v[236:239], v72 offset:23136
	s_waitcnt vmcnt(13)
	ds_write_b128 v1, v[188:191]
	ds_write_b128 v1, v[180:183] offset:4608
	ds_write_b128 v1, v[184:187] offset:9216
	s_waitcnt vmcnt(11)
	ds_write_b128 v1, v[196:199] offset:13824
	ds_write_b128 v1, v[192:195] offset:36864
	s_waitcnt vmcnt(10)
	ds_write_b128 v1, v[200:203] offset:41472
	s_waitcnt vmcnt(9)
	ds_write_b128 v1, v[204:207] offset:46080
	s_waitcnt vmcnt(8)
	ds_write_b128 v1, v[208:211] offset:50688
	global_load_dwordx4 v[180:183], v[80:81], off offset:1024
	global_load_dwordx4 v[184:187], v[82:83], off offset:1024
	global_load_dwordx4 v[188:191], v[78:79], off offset:1024
	global_load_dwordx4 v[192:195], v[76:77], off offset:1024
	global_load_dwordx4 v[196:199], v[90:91], off offset:1024
	global_load_dwordx4 v[200:203], v[84:85], off offset:1024
	global_load_dwordx4 v[204:207], v[86:87], off offset:1024
	global_load_dwordx4 v[208:211], v[88:89], off offset:1024
	s_waitcnt lgkmcnt(0)
	s_barrier
	v_mfma_f32_32x32x16_bf16 v[34:49], v[212:215], v[216:219], v[34:49]
	v_mfma_f32_32x32x16_bf16 v[50:65], v[212:215], v[228:231], v[50:65]
	v_mfma_f32_32x32x16_bf16 v[2:17], v[220:223], v[224:227], v[2:17]
	v_mfma_f32_32x32x16_bf16 v[18:33], v[220:223], v[232:235], v[18:33]
	v_mfma_f32_32x32x16_bf16 v[34:49], v[236:239], v[224:227], v[34:49]
	v_mfma_f32_32x32x16_bf16 v[50:65], v[236:239], v[232:235], v[50:65]
	ds_read_b128 v[212:215], v72
	ds_read_b128 v[216:219], v73 offset:36864
	ds_read_b128 v[220:223], v72 offset:32
	ds_read_b128 v[224:227], v73 offset:36896
	ds_read_b128 v[228:231], v73 offset:41472
	ds_read_b128 v[232:235], v73 offset:41504
	s_waitcnt lgkmcnt(4)
	v_mfma_f32_32x32x16_bf16 v[2:17], v[212:215], v[216:219], v[2:17]
	s_waitcnt lgkmcnt(1)
	v_mfma_f32_32x32x16_bf16 v[18:33], v[212:215], v[228:231], v[18:33]
	ds_read_b128 v[212:215], v72 offset:4608
	ds_read_b128 v[236:239], v72 offset:4640
	s_waitcnt lgkmcnt(1)
	v_mfma_f32_32x32x16_bf16 v[34:49], v[212:215], v[216:219], v[34:49]
	v_mfma_f32_32x32x16_bf16 v[50:65], v[212:215], v[228:231], v[50:65]
	v_mfma_f32_32x32x16_bf16 v[2:17], v[220:223], v[224:227], v[2:17]
	v_mfma_f32_32x32x16_bf16 v[18:33], v[220:223], v[232:235], v[18:33]
	s_waitcnt lgkmcnt(0)
	v_mfma_f32_32x32x16_bf16 v[34:49], v[236:239], v[224:227], v[34:49]
	ds_read_b128 v[212:215], v72 offset:64
	ds_read_b128 v[216:219], v73 offset:36928
	ds_read_b128 v[220:223], v72 offset:96
	ds_read_b128 v[224:227], v73 offset:36960
	v_mfma_f32_32x32x16_bf16 v[50:65], v[236:239], v[232:235], v[50:65]
	ds_read_b128 v[228:231], v73 offset:41536
	ds_read_b128 v[232:235], v73 offset:41568
	s_waitcnt lgkmcnt(4)
	v_mfma_f32_32x32x16_bf16 v[2:17], v[212:215], v[216:219], v[2:17]
	s_waitcnt lgkmcnt(1)
	v_mfma_f32_32x32x16_bf16 v[18:33], v[212:215], v[228:231], v[18:33]
	ds_read_b128 v[212:215], v72 offset:4672
	ds_read_b128 v[236:239], v72 offset:4704
	s_waitcnt vmcnt(13)
	ds_write_b128 v1, v[156:159] offset:18432
	ds_write_b128 v1, v[148:151] offset:23040
	ds_write_b128 v1, v[152:155] offset:27648
	s_waitcnt vmcnt(11)
	ds_write_b128 v1, v[164:167] offset:32256
	ds_write_b128 v1, v[160:163] offset:55296
	s_waitcnt vmcnt(10)
	ds_write_b128 v1, v[168:171] offset:59904
	s_waitcnt vmcnt(9)
	ds_write_b128 v1, v[172:175] offset:64512
	s_waitcnt vmcnt(8)
	ds_write_b128 v92, v[176:179] offset:32256
	global_load_dwordx4 v[148:151], v[80:81], off offset:1152
	global_load_dwordx4 v[152:155], v[82:83], off offset:1152
	global_load_dwordx4 v[156:159], v[78:79], off offset:1152
	global_load_dwordx4 v[160:163], v[76:77], off offset:1152
	global_load_dwordx4 v[164:167], v[90:91], off offset:1152
	global_load_dwordx4 v[168:171], v[84:85], off offset:1152
	global_load_dwordx4 v[172:175], v[86:87], off offset:1152
	global_load_dwordx4 v[176:179], v[88:89], off offset:1152
	s_waitcnt lgkmcnt(0)
	s_barrier
	v_mfma_f32_32x32x16_bf16 v[34:49], v[212:215], v[216:219], v[34:49]
	v_mfma_f32_32x32x16_bf16 v[50:65], v[212:215], v[228:231], v[50:65]
	v_mfma_f32_32x32x16_bf16 v[2:17], v[220:223], v[224:227], v[2:17]
	v_mfma_f32_32x32x16_bf16 v[18:33], v[220:223], v[232:235], v[18:33]
	v_mfma_f32_32x32x16_bf16 v[34:49], v[236:239], v[224:227], v[34:49]
	v_mfma_f32_32x32x16_bf16 v[50:65], v[236:239], v[232:235], v[50:65]
	ds_read_b128 v[212:215], v72 offset:18432
	ds_read_b128 v[216:219], v73 offset:55296
	ds_read_b128 v[220:223], v72 offset:18464
	ds_read_b128 v[224:227], v73 offset:55328
	ds_read_b128 v[228:231], v73 offset:59904
	ds_read_b128 v[232:235], v73 offset:59936
	s_waitcnt lgkmcnt(4)
	v_mfma_f32_32x32x16_bf16 v[2:17], v[212:215], v[216:219], v[2:17]
	s_waitcnt lgkmcnt(1)
	v_mfma_f32_32x32x16_bf16 v[18:33], v[212:215], v[228:231], v[18:33]
	ds_read_b128 v[212:215], v72 offset:23040
	ds_read_b128 v[236:239], v72 offset:23072
	s_waitcnt lgkmcnt(1)
	v_mfma_f32_32x32x16_bf16 v[34:49], v[212:215], v[216:219], v[34:49]
	v_mfma_f32_32x32x16_bf16 v[50:65], v[212:215], v[228:231], v[50:65]
	v_mfma_f32_32x32x16_bf16 v[2:17], v[220:223], v[224:227], v[2:17]
	v_mfma_f32_32x32x16_bf16 v[18:33], v[220:223], v[232:235], v[18:33]
	s_waitcnt lgkmcnt(0)
	v_mfma_f32_32x32x16_bf16 v[34:49], v[236:239], v[224:227], v[34:49]
	ds_read_b128 v[212:215], v72 offset:18496
	ds_read_b128 v[216:219], v73 offset:55360
	ds_read_b128 v[220:223], v72 offset:18528
	ds_read_b128 v[224:227], v73 offset:55392
	v_mfma_f32_32x32x16_bf16 v[50:65], v[236:239], v[232:235], v[50:65]
	ds_read_b128 v[228:231], v73 offset:59968
	ds_read_b128 v[232:235], v73 offset:60000
	s_waitcnt lgkmcnt(4)
	v_mfma_f32_32x32x16_bf16 v[2:17], v[212:215], v[216:219], v[2:17]
	s_waitcnt lgkmcnt(1)
	v_mfma_f32_32x32x16_bf16 v[18:33], v[212:215], v[228:231], v[18:33]
	ds_read_b128 v[212:215], v72 offset:23104
	ds_read_b128 v[236:239], v72 offset:23136
	s_waitcnt vmcnt(13)
	ds_write_b128 v1, v[188:191]
	ds_write_b128 v1, v[180:183] offset:4608
	ds_write_b128 v1, v[184:187] offset:9216
	s_waitcnt vmcnt(11)
	ds_write_b128 v1, v[196:199] offset:13824
	ds_write_b128 v1, v[192:195] offset:36864
	s_waitcnt vmcnt(10)
	ds_write_b128 v1, v[200:203] offset:41472
	s_waitcnt vmcnt(9)
	ds_write_b128 v1, v[204:207] offset:46080
	s_waitcnt vmcnt(8)
	ds_write_b128 v1, v[208:211] offset:50688
	global_load_dwordx4 v[180:183], v[80:81], off offset:1280
	global_load_dwordx4 v[184:187], v[82:83], off offset:1280
	global_load_dwordx4 v[188:191], v[78:79], off offset:1280
	global_load_dwordx4 v[192:195], v[76:77], off offset:1280
	global_load_dwordx4 v[196:199], v[90:91], off offset:1280
	global_load_dwordx4 v[200:203], v[84:85], off offset:1280
	global_load_dwordx4 v[204:207], v[86:87], off offset:1280
	global_load_dwordx4 v[208:211], v[88:89], off offset:1280
	s_waitcnt lgkmcnt(0)
	s_barrier
	v_mfma_f32_32x32x16_bf16 v[34:49], v[212:215], v[216:219], v[34:49]
	v_mfma_f32_32x32x16_bf16 v[50:65], v[212:215], v[228:231], v[50:65]
	v_mfma_f32_32x32x16_bf16 v[2:17], v[220:223], v[224:227], v[2:17]
	v_mfma_f32_32x32x16_bf16 v[18:33], v[220:223], v[232:235], v[18:33]
	v_mfma_f32_32x32x16_bf16 v[34:49], v[236:239], v[224:227], v[34:49]
	v_mfma_f32_32x32x16_bf16 v[50:65], v[236:239], v[232:235], v[50:65]
	ds_read_b128 v[212:215], v72
	ds_read_b128 v[216:219], v73 offset:36864
	ds_read_b128 v[220:223], v72 offset:32
	ds_read_b128 v[224:227], v73 offset:36896
	ds_read_b128 v[228:231], v73 offset:41472
	ds_read_b128 v[232:235], v73 offset:41504
	s_waitcnt lgkmcnt(4)
	v_mfma_f32_32x32x16_bf16 v[2:17], v[212:215], v[216:219], v[2:17]
	s_waitcnt lgkmcnt(1)
	v_mfma_f32_32x32x16_bf16 v[18:33], v[212:215], v[228:231], v[18:33]
	ds_read_b128 v[212:215], v72 offset:4608
	ds_read_b128 v[236:239], v72 offset:4640
	s_waitcnt lgkmcnt(1)
	v_mfma_f32_32x32x16_bf16 v[34:49], v[212:215], v[216:219], v[34:49]
	v_mfma_f32_32x32x16_bf16 v[50:65], v[212:215], v[228:231], v[50:65]
	v_mfma_f32_32x32x16_bf16 v[2:17], v[220:223], v[224:227], v[2:17]
	v_mfma_f32_32x32x16_bf16 v[18:33], v[220:223], v[232:235], v[18:33]
	s_waitcnt lgkmcnt(0)
	v_mfma_f32_32x32x16_bf16 v[34:49], v[236:239], v[224:227], v[34:49]
	ds_read_b128 v[212:215], v72 offset:64
	ds_read_b128 v[216:219], v73 offset:36928
	ds_read_b128 v[220:223], v72 offset:96
	ds_read_b128 v[224:227], v73 offset:36960
	v_mfma_f32_32x32x16_bf16 v[50:65], v[236:239], v[232:235], v[50:65]
	ds_read_b128 v[228:231], v73 offset:41536
	ds_read_b128 v[232:235], v73 offset:41568
	s_waitcnt lgkmcnt(4)
	v_mfma_f32_32x32x16_bf16 v[2:17], v[212:215], v[216:219], v[2:17]
	s_waitcnt lgkmcnt(1)
	v_mfma_f32_32x32x16_bf16 v[18:33], v[212:215], v[228:231], v[18:33]
	ds_read_b128 v[212:215], v72 offset:4672
	ds_read_b128 v[236:239], v72 offset:4704
	s_waitcnt vmcnt(13)
	ds_write_b128 v1, v[156:159] offset:18432
	ds_write_b128 v1, v[148:151] offset:23040
	ds_write_b128 v1, v[152:155] offset:27648
	s_waitcnt vmcnt(11)
	ds_write_b128 v1, v[164:167] offset:32256
	ds_write_b128 v1, v[160:163] offset:55296
	s_waitcnt vmcnt(10)
	ds_write_b128 v1, v[168:171] offset:59904
	s_waitcnt vmcnt(9)
	ds_write_b128 v1, v[172:175] offset:64512
	s_waitcnt vmcnt(8)
	ds_write_b128 v92, v[176:179] offset:32256
	global_load_dwordx4 v[148:151], v[80:81], off offset:1408
	global_load_dwordx4 v[152:155], v[82:83], off offset:1408
	global_load_dwordx4 v[156:159], v[78:79], off offset:1408
	global_load_dwordx4 v[160:163], v[76:77], off offset:1408
	global_load_dwordx4 v[164:167], v[90:91], off offset:1408
	global_load_dwordx4 v[168:171], v[84:85], off offset:1408
	global_load_dwordx4 v[172:175], v[86:87], off offset:1408
	global_load_dwordx4 v[176:179], v[88:89], off offset:1408
	s_waitcnt lgkmcnt(0)
	s_barrier
	v_mfma_f32_32x32x16_bf16 v[34:49], v[212:215], v[216:219], v[34:49]
	v_mfma_f32_32x32x16_bf16 v[50:65], v[212:215], v[228:231], v[50:65]
	v_mfma_f32_32x32x16_bf16 v[2:17], v[220:223], v[224:227], v[2:17]
	v_mfma_f32_32x32x16_bf16 v[18:33], v[220:223], v[232:235], v[18:33]
	v_mfma_f32_32x32x16_bf16 v[34:49], v[236:239], v[224:227], v[34:49]
	v_mfma_f32_32x32x16_bf16 v[50:65], v[236:239], v[232:235], v[50:65]
	ds_read_b128 v[212:215], v72 offset:18432
	ds_read_b128 v[216:219], v73 offset:55296
	ds_read_b128 v[220:223], v72 offset:18464
	ds_read_b128 v[224:227], v73 offset:55328
	ds_read_b128 v[228:231], v73 offset:59904
	ds_read_b128 v[232:235], v73 offset:59936
	s_waitcnt lgkmcnt(4)
	v_mfma_f32_32x32x16_bf16 v[2:17], v[212:215], v[216:219], v[2:17]
	s_waitcnt lgkmcnt(1)
	v_mfma_f32_32x32x16_bf16 v[18:33], v[212:215], v[228:231], v[18:33]
	ds_read_b128 v[212:215], v72 offset:23040
	ds_read_b128 v[236:239], v72 offset:23072
	s_waitcnt lgkmcnt(1)
	v_mfma_f32_32x32x16_bf16 v[34:49], v[212:215], v[216:219], v[34:49]
	v_mfma_f32_32x32x16_bf16 v[50:65], v[212:215], v[228:231], v[50:65]
	v_mfma_f32_32x32x16_bf16 v[2:17], v[220:223], v[224:227], v[2:17]
	v_mfma_f32_32x32x16_bf16 v[18:33], v[220:223], v[232:235], v[18:33]
	s_waitcnt lgkmcnt(0)
	v_mfma_f32_32x32x16_bf16 v[34:49], v[236:239], v[224:227], v[34:49]
	ds_read_b128 v[212:215], v72 offset:18496
	ds_read_b128 v[216:219], v73 offset:55360
	ds_read_b128 v[220:223], v72 offset:18528
	ds_read_b128 v[224:227], v73 offset:55392
	v_mfma_f32_32x32x16_bf16 v[50:65], v[236:239], v[232:235], v[50:65]
	ds_read_b128 v[228:231], v73 offset:59968
	ds_read_b128 v[232:235], v73 offset:60000
	s_waitcnt lgkmcnt(4)
	v_mfma_f32_32x32x16_bf16 v[2:17], v[212:215], v[216:219], v[2:17]
	s_waitcnt lgkmcnt(1)
	v_mfma_f32_32x32x16_bf16 v[18:33], v[212:215], v[228:231], v[18:33]
	ds_read_b128 v[212:215], v72 offset:23104
	ds_read_b128 v[236:239], v72 offset:23136
	s_waitcnt vmcnt(13)
	ds_write_b128 v1, v[188:191]
	ds_write_b128 v1, v[180:183] offset:4608
	ds_write_b128 v1, v[184:187] offset:9216
	s_waitcnt vmcnt(11)
	ds_write_b128 v1, v[196:199] offset:13824
	ds_write_b128 v1, v[192:195] offset:36864
	s_waitcnt vmcnt(10)
	ds_write_b128 v1, v[200:203] offset:41472
	s_waitcnt vmcnt(9)
	ds_write_b128 v1, v[204:207] offset:46080
	s_waitcnt vmcnt(8)
	ds_write_b128 v1, v[208:211] offset:50688
	global_load_dwordx4 v[180:183], v[80:81], off offset:1536
	global_load_dwordx4 v[184:187], v[82:83], off offset:1536
	global_load_dwordx4 v[188:191], v[78:79], off offset:1536
	global_load_dwordx4 v[192:195], v[76:77], off offset:1536
	global_load_dwordx4 v[196:199], v[90:91], off offset:1536
	global_load_dwordx4 v[200:203], v[84:85], off offset:1536
	global_load_dwordx4 v[204:207], v[86:87], off offset:1536
	global_load_dwordx4 v[208:211], v[88:89], off offset:1536
	s_waitcnt lgkmcnt(0)
	s_barrier
	v_mfma_f32_32x32x16_bf16 v[34:49], v[212:215], v[216:219], v[34:49]
	v_mfma_f32_32x32x16_bf16 v[50:65], v[212:215], v[228:231], v[50:65]
	v_mfma_f32_32x32x16_bf16 v[2:17], v[220:223], v[224:227], v[2:17]
	v_mfma_f32_32x32x16_bf16 v[18:33], v[220:223], v[232:235], v[18:33]
	v_mfma_f32_32x32x16_bf16 v[34:49], v[236:239], v[224:227], v[34:49]
	v_mfma_f32_32x32x16_bf16 v[50:65], v[236:239], v[232:235], v[50:65]
	ds_read_b128 v[212:215], v72
	ds_read_b128 v[216:219], v73 offset:36864
	ds_read_b128 v[220:223], v72 offset:32
	ds_read_b128 v[224:227], v73 offset:36896
	ds_read_b128 v[228:231], v73 offset:41472
	ds_read_b128 v[232:235], v73 offset:41504
	s_waitcnt lgkmcnt(4)
	v_mfma_f32_32x32x16_bf16 v[2:17], v[212:215], v[216:219], v[2:17]
	s_waitcnt lgkmcnt(1)
	v_mfma_f32_32x32x16_bf16 v[18:33], v[212:215], v[228:231], v[18:33]
	ds_read_b128 v[212:215], v72 offset:4608
	ds_read_b128 v[236:239], v72 offset:4640
	s_waitcnt lgkmcnt(1)
	v_mfma_f32_32x32x16_bf16 v[34:49], v[212:215], v[216:219], v[34:49]
	v_mfma_f32_32x32x16_bf16 v[50:65], v[212:215], v[228:231], v[50:65]
	v_mfma_f32_32x32x16_bf16 v[2:17], v[220:223], v[224:227], v[2:17]
	v_mfma_f32_32x32x16_bf16 v[18:33], v[220:223], v[232:235], v[18:33]
	s_waitcnt lgkmcnt(0)
	v_mfma_f32_32x32x16_bf16 v[34:49], v[236:239], v[224:227], v[34:49]
	ds_read_b128 v[212:215], v72 offset:64
	ds_read_b128 v[216:219], v73 offset:36928
	ds_read_b128 v[220:223], v72 offset:96
	ds_read_b128 v[224:227], v73 offset:36960
	v_mfma_f32_32x32x16_bf16 v[50:65], v[236:239], v[232:235], v[50:65]
	ds_read_b128 v[228:231], v73 offset:41536
	ds_read_b128 v[232:235], v73 offset:41568
	s_waitcnt lgkmcnt(4)
	v_mfma_f32_32x32x16_bf16 v[2:17], v[212:215], v[216:219], v[2:17]
	s_waitcnt lgkmcnt(1)
	v_mfma_f32_32x32x16_bf16 v[18:33], v[212:215], v[228:231], v[18:33]
	ds_read_b128 v[212:215], v72 offset:4672
	ds_read_b128 v[236:239], v72 offset:4704
	s_waitcnt vmcnt(13)
	ds_write_b128 v1, v[156:159] offset:18432
	ds_write_b128 v1, v[148:151] offset:23040
	ds_write_b128 v1, v[152:155] offset:27648
	s_waitcnt vmcnt(11)
	ds_write_b128 v1, v[164:167] offset:32256
	ds_write_b128 v1, v[160:163] offset:55296
	s_waitcnt vmcnt(10)
	ds_write_b128 v1, v[168:171] offset:59904
	s_waitcnt vmcnt(9)
	ds_write_b128 v1, v[172:175] offset:64512
	s_waitcnt vmcnt(8)
	ds_write_b128 v92, v[176:179] offset:32256
	global_load_dwordx4 v[148:151], v[80:81], off offset:1664
	global_load_dwordx4 v[152:155], v[82:83], off offset:1664
	global_load_dwordx4 v[156:159], v[78:79], off offset:1664
	global_load_dwordx4 v[160:163], v[76:77], off offset:1664
	global_load_dwordx4 v[164:167], v[90:91], off offset:1664
	global_load_dwordx4 v[168:171], v[84:85], off offset:1664
	global_load_dwordx4 v[172:175], v[86:87], off offset:1664
	global_load_dwordx4 v[176:179], v[88:89], off offset:1664
	s_waitcnt lgkmcnt(0)
	s_barrier
	v_mfma_f32_32x32x16_bf16 v[34:49], v[212:215], v[216:219], v[34:49]
	v_mfma_f32_32x32x16_bf16 v[50:65], v[212:215], v[228:231], v[50:65]
	v_mfma_f32_32x32x16_bf16 v[2:17], v[220:223], v[224:227], v[2:17]
	v_mfma_f32_32x32x16_bf16 v[18:33], v[220:223], v[232:235], v[18:33]
	v_mfma_f32_32x32x16_bf16 v[34:49], v[236:239], v[224:227], v[34:49]
	v_mfma_f32_32x32x16_bf16 v[50:65], v[236:239], v[232:235], v[50:65]
	ds_read_b128 v[212:215], v72 offset:18432
	ds_read_b128 v[216:219], v73 offset:55296
	ds_read_b128 v[220:223], v72 offset:18464
	ds_read_b128 v[224:227], v73 offset:55328
	ds_read_b128 v[228:231], v73 offset:59904
	ds_read_b128 v[232:235], v73 offset:59936
	s_waitcnt lgkmcnt(4)
	v_mfma_f32_32x32x16_bf16 v[2:17], v[212:215], v[216:219], v[2:17]
	s_waitcnt lgkmcnt(1)
	v_mfma_f32_32x32x16_bf16 v[18:33], v[212:215], v[228:231], v[18:33]
	ds_read_b128 v[212:215], v72 offset:23040
	ds_read_b128 v[236:239], v72 offset:23072
	s_waitcnt lgkmcnt(1)
	v_mfma_f32_32x32x16_bf16 v[34:49], v[212:215], v[216:219], v[34:49]
	v_mfma_f32_32x32x16_bf16 v[50:65], v[212:215], v[228:231], v[50:65]
	v_mfma_f32_32x32x16_bf16 v[2:17], v[220:223], v[224:227], v[2:17]
	v_mfma_f32_32x32x16_bf16 v[18:33], v[220:223], v[232:235], v[18:33]
	s_waitcnt lgkmcnt(0)
	v_mfma_f32_32x32x16_bf16 v[34:49], v[236:239], v[224:227], v[34:49]
	ds_read_b128 v[212:215], v72 offset:18496
	ds_read_b128 v[216:219], v73 offset:55360
	ds_read_b128 v[220:223], v72 offset:18528
	ds_read_b128 v[224:227], v73 offset:55392
	v_mfma_f32_32x32x16_bf16 v[50:65], v[236:239], v[232:235], v[50:65]
	ds_read_b128 v[228:231], v73 offset:59968
	ds_read_b128 v[232:235], v73 offset:60000
	s_waitcnt lgkmcnt(4)
	v_mfma_f32_32x32x16_bf16 v[2:17], v[212:215], v[216:219], v[2:17]
	s_waitcnt lgkmcnt(1)
	v_mfma_f32_32x32x16_bf16 v[18:33], v[212:215], v[228:231], v[18:33]
	ds_read_b128 v[212:215], v72 offset:23104
	ds_read_b128 v[236:239], v72 offset:23136
	s_waitcnt vmcnt(13)
	ds_write_b128 v1, v[188:191]
	ds_write_b128 v1, v[180:183] offset:4608
	ds_write_b128 v1, v[184:187] offset:9216
	s_waitcnt vmcnt(11)
	ds_write_b128 v1, v[196:199] offset:13824
	ds_write_b128 v1, v[192:195] offset:36864
	s_waitcnt vmcnt(10)
	ds_write_b128 v1, v[200:203] offset:41472
	s_waitcnt vmcnt(9)
	ds_write_b128 v1, v[204:207] offset:46080
	s_waitcnt vmcnt(8)
	ds_write_b128 v1, v[208:211] offset:50688
	global_load_dwordx4 v[180:183], v[80:81], off offset:1792
	global_load_dwordx4 v[184:187], v[82:83], off offset:1792
	global_load_dwordx4 v[188:191], v[78:79], off offset:1792
	global_load_dwordx4 v[192:195], v[76:77], off offset:1792
	global_load_dwordx4 v[196:199], v[90:91], off offset:1792
	global_load_dwordx4 v[200:203], v[84:85], off offset:1792
	global_load_dwordx4 v[204:207], v[86:87], off offset:1792
	global_load_dwordx4 v[208:211], v[88:89], off offset:1792
	s_waitcnt lgkmcnt(0)
	s_barrier
	v_mfma_f32_32x32x16_bf16 v[34:49], v[212:215], v[216:219], v[34:49]
	v_mfma_f32_32x32x16_bf16 v[50:65], v[212:215], v[228:231], v[50:65]
	v_mfma_f32_32x32x16_bf16 v[2:17], v[220:223], v[224:227], v[2:17]
	v_mfma_f32_32x32x16_bf16 v[18:33], v[220:223], v[232:235], v[18:33]
	v_mfma_f32_32x32x16_bf16 v[34:49], v[236:239], v[224:227], v[34:49]
	v_mfma_f32_32x32x16_bf16 v[50:65], v[236:239], v[232:235], v[50:65]
	ds_read_b128 v[212:215], v72
	ds_read_b128 v[216:219], v73 offset:36864
	ds_read_b128 v[220:223], v72 offset:32
	ds_read_b128 v[224:227], v73 offset:36896
	ds_read_b128 v[228:231], v73 offset:41472
	ds_read_b128 v[232:235], v73 offset:41504
	s_waitcnt lgkmcnt(4)
	v_mfma_f32_32x32x16_bf16 v[2:17], v[212:215], v[216:219], v[2:17]
	s_waitcnt lgkmcnt(1)
	v_mfma_f32_32x32x16_bf16 v[18:33], v[212:215], v[228:231], v[18:33]
	ds_read_b128 v[212:215], v72 offset:4608
	ds_read_b128 v[236:239], v72 offset:4640
	s_waitcnt lgkmcnt(1)
	v_mfma_f32_32x32x16_bf16 v[34:49], v[212:215], v[216:219], v[34:49]
	v_mfma_f32_32x32x16_bf16 v[50:65], v[212:215], v[228:231], v[50:65]
	v_mfma_f32_32x32x16_bf16 v[2:17], v[220:223], v[224:227], v[2:17]
	v_mfma_f32_32x32x16_bf16 v[18:33], v[220:223], v[232:235], v[18:33]
	s_waitcnt lgkmcnt(0)
	v_mfma_f32_32x32x16_bf16 v[34:49], v[236:239], v[224:227], v[34:49]
	ds_read_b128 v[212:215], v72 offset:64
	ds_read_b128 v[216:219], v73 offset:36928
	ds_read_b128 v[220:223], v72 offset:96
	ds_read_b128 v[224:227], v73 offset:36960
	v_mfma_f32_32x32x16_bf16 v[50:65], v[236:239], v[232:235], v[50:65]
	ds_read_b128 v[228:231], v73 offset:41536
	ds_read_b128 v[232:235], v73 offset:41568
	s_waitcnt lgkmcnt(4)
	v_mfma_f32_32x32x16_bf16 v[2:17], v[212:215], v[216:219], v[2:17]
	s_waitcnt lgkmcnt(1)
	v_mfma_f32_32x32x16_bf16 v[18:33], v[212:215], v[228:231], v[18:33]
	ds_read_b128 v[212:215], v72 offset:4672
	ds_read_b128 v[236:239], v72 offset:4704
	s_waitcnt vmcnt(13)
	ds_write_b128 v1, v[156:159] offset:18432
	ds_write_b128 v1, v[148:151] offset:23040
	ds_write_b128 v1, v[152:155] offset:27648
	s_waitcnt vmcnt(11)
	ds_write_b128 v1, v[164:167] offset:32256
	ds_write_b128 v1, v[160:163] offset:55296
	s_waitcnt vmcnt(10)
	ds_write_b128 v1, v[168:171] offset:59904
	s_waitcnt vmcnt(9)
	ds_write_b128 v1, v[172:175] offset:64512
	s_waitcnt vmcnt(8)
	ds_write_b128 v92, v[176:179] offset:32256
	s_waitcnt lgkmcnt(0)
	s_barrier
	global_load_dwordx4 v[148:151], v[80:81], off offset:1920
	s_nop 0
	global_load_dwordx4 v[80:83], v[82:83], off offset:1920
	s_nop 0
	global_load_dwordx4 v[152:155], v[78:79], off offset:1920
	s_nop 0
	global_load_dwordx4 v[76:79], v[76:77], off offset:1920
	s_nop 0
	global_load_dwordx4 v[156:159], v[90:91], off offset:1920
	global_load_dwordx4 v[160:163], v[84:85], off offset:1920
	s_nop 0
	global_load_dwordx4 v[84:87], v[86:87], off offset:1920
	s_nop 0
	global_load_dwordx4 v[88:91], v[88:89], off offset:1920
	v_mfma_f32_32x32x16_bf16 v[34:49], v[212:215], v[216:219], v[34:49]
	v_mfma_f32_32x32x16_bf16 v[50:65], v[212:215], v[228:231], v[50:65]
	v_mfma_f32_32x32x16_bf16 v[2:17], v[220:223], v[224:227], v[2:17]
	v_mfma_f32_32x32x16_bf16 v[18:33], v[220:223], v[232:235], v[18:33]
	v_mfma_f32_32x32x16_bf16 v[34:49], v[236:239], v[224:227], v[34:49]
	v_mfma_f32_32x32x16_bf16 v[50:65], v[236:239], v[232:235], v[50:65]
	ds_read_b128 v[164:167], v72 offset:18432
	ds_read_b128 v[168:171], v73 offset:55296
	ds_read_b128 v[172:175], v72 offset:18464
	ds_read_b128 v[176:179], v73 offset:55328
	ds_read_b128 v[212:215], v73 offset:59904
	ds_read_b128 v[216:219], v73 offset:59936
	s_waitcnt lgkmcnt(4)
	v_mfma_f32_32x32x16_bf16 v[2:17], v[164:167], v[168:171], v[2:17]
	s_waitcnt lgkmcnt(1)
	v_mfma_f32_32x32x16_bf16 v[18:33], v[164:167], v[212:215], v[18:33]
	ds_read_b128 v[164:167], v72 offset:23040
	ds_read_b128 v[220:223], v72 offset:23072
	s_waitcnt lgkmcnt(1)
	v_mfma_f32_32x32x16_bf16 v[34:49], v[164:167], v[168:171], v[34:49]
	v_mfma_f32_32x32x16_bf16 v[50:65], v[164:167], v[212:215], v[50:65]
	v_mfma_f32_32x32x16_bf16 v[2:17], v[172:175], v[176:179], v[2:17]
	v_mfma_f32_32x32x16_bf16 v[18:33], v[172:175], v[216:219], v[18:33]
	s_waitcnt lgkmcnt(0)
	v_mfma_f32_32x32x16_bf16 v[34:49], v[220:223], v[176:179], v[34:49]
	ds_read_b128 v[164:167], v72 offset:18496
	ds_read_b128 v[168:171], v73 offset:55360
	ds_read_b128 v[172:175], v72 offset:18528
	ds_read_b128 v[176:179], v73 offset:55392
	v_mfma_f32_32x32x16_bf16 v[50:65], v[220:223], v[216:219], v[50:65]
	ds_read_b128 v[212:215], v73 offset:59968
	ds_read_b128 v[216:219], v73 offset:60000
	s_waitcnt lgkmcnt(4)
	v_mfma_f32_32x32x16_bf16 v[2:17], v[164:167], v[168:171], v[2:17]
	s_waitcnt lgkmcnt(1)
	v_mfma_f32_32x32x16_bf16 v[18:33], v[164:167], v[212:215], v[18:33]
	ds_read_b128 v[164:167], v72 offset:23104
	ds_read_b128 v[220:223], v72 offset:23136
	s_waitcnt vmcnt(13)
	ds_write_b128 v1, v[188:191]
	ds_write_b128 v1, v[180:183] offset:4608
	ds_write_b128 v1, v[184:187] offset:9216
	s_waitcnt vmcnt(11)
	ds_write_b128 v1, v[196:199] offset:13824
	ds_write_b128 v1, v[192:195] offset:36864
	s_waitcnt vmcnt(10)
	ds_write_b128 v1, v[200:203] offset:41472
	s_waitcnt vmcnt(9)
	ds_write_b128 v1, v[204:207] offset:46080
	s_waitcnt vmcnt(8)
	ds_write_b128 v1, v[208:211] offset:50688
	s_waitcnt lgkmcnt(0)
	s_barrier
	v_mfma_f32_32x32x16_bf16 v[34:49], v[164:167], v[168:171], v[34:49]
	v_mfma_f32_32x32x16_bf16 v[50:65], v[164:167], v[212:215], v[50:65]
	v_mfma_f32_32x32x16_bf16 v[2:17], v[172:175], v[176:179], v[2:17]
	v_mfma_f32_32x32x16_bf16 v[18:33], v[172:175], v[216:219], v[18:33]
	v_mfma_f32_32x32x16_bf16 v[34:49], v[220:223], v[176:179], v[34:49]
	v_mfma_f32_32x32x16_bf16 v[50:65], v[220:223], v[216:219], v[50:65]
	ds_read_b128 v[164:167], v72
	ds_read_b128 v[168:171], v73 offset:36864
	ds_read_b128 v[172:175], v72 offset:32
	ds_read_b128 v[176:179], v73 offset:36896
	ds_read_b128 v[180:183], v73 offset:41472
	ds_read_b128 v[184:187], v73 offset:41504
	s_waitcnt lgkmcnt(4)
	v_mfma_f32_32x32x16_bf16 v[2:17], v[164:167], v[168:171], v[2:17]
	s_waitcnt lgkmcnt(1)
	v_mfma_f32_32x32x16_bf16 v[18:33], v[164:167], v[180:183], v[18:33]
	ds_read_b128 v[164:167], v72 offset:4608
	ds_read_b128 v[188:191], v72 offset:4640
	s_waitcnt lgkmcnt(1)
	v_mfma_f32_32x32x16_bf16 v[34:49], v[164:167], v[168:171], v[34:49]
	v_mfma_f32_32x32x16_bf16 v[50:65], v[164:167], v[180:183], v[50:65]
	v_mfma_f32_32x32x16_bf16 v[2:17], v[172:175], v[176:179], v[2:17]
	v_mfma_f32_32x32x16_bf16 v[18:33], v[172:175], v[184:187], v[18:33]
	s_waitcnt lgkmcnt(0)
	v_mfma_f32_32x32x16_bf16 v[34:49], v[188:191], v[176:179], v[34:49]
	ds_read_b128 v[164:167], v72 offset:64
	ds_read_b128 v[168:171], v73 offset:36928
	ds_read_b128 v[172:175], v72 offset:96
	ds_read_b128 v[176:179], v73 offset:36960
	v_mfma_f32_32x32x16_bf16 v[50:65], v[188:191], v[184:187], v[50:65]
	ds_read_b128 v[180:183], v73 offset:41536
	ds_read_b128 v[184:187], v73 offset:41568
	s_waitcnt lgkmcnt(4)
	v_mfma_f32_32x32x16_bf16 v[2:17], v[164:167], v[168:171], v[2:17]
	s_waitcnt lgkmcnt(1)
	v_mfma_f32_32x32x16_bf16 v[18:33], v[164:167], v[180:183], v[18:33]
	ds_read_b128 v[164:167], v72 offset:4672
	ds_read_b128 v[188:191], v72 offset:4704
	s_waitcnt vmcnt(5)
	ds_write_b128 v1, v[152:155] offset:18432
	ds_write_b128 v1, v[148:151] offset:23040
	ds_write_b128 v1, v[80:83] offset:27648
	s_waitcnt vmcnt(3)
	ds_write_b128 v1, v[156:159] offset:32256
	ds_write_b128 v1, v[76:79] offset:55296
	s_waitcnt vmcnt(2)
	ds_write_b128 v1, v[160:163] offset:59904
	s_waitcnt vmcnt(1)
	ds_write_b128 v1, v[84:87] offset:64512
	s_waitcnt vmcnt(0)
	ds_write_b128 v92, v[88:91] offset:32256
	s_waitcnt lgkmcnt(0)
	s_barrier
	v_mfma_f32_32x32x16_bf16 v[34:49], v[164:167], v[168:171], v[34:49]
	v_mfma_f32_32x32x16_bf16 v[50:65], v[164:167], v[180:183], v[50:65]
	v_mfma_f32_32x32x16_bf16 v[2:17], v[172:175], v[176:179], v[2:17]
	v_mfma_f32_32x32x16_bf16 v[18:33], v[172:175], v[184:187], v[18:33]
	v_mfma_f32_32x32x16_bf16 v[34:49], v[188:191], v[176:179], v[34:49]
	v_mfma_f32_32x32x16_bf16 v[50:65], v[188:191], v[184:187], v[50:65]
	ds_read_b128 v[76:79], v72 offset:18432
	ds_read_b128 v[80:83], v73 offset:55296
	ds_read_b128 v[84:87], v72 offset:18464
	ds_read_b128 v[88:91], v73 offset:55328
	ds_read_b128 v[148:151], v73 offset:59904
	ds_read_b128 v[152:155], v73 offset:59936
	v_or_b32_e32 v66, s8, v93
	s_waitcnt lgkmcnt(4)
	v_mfma_f32_32x32x16_bf16 v[2:17], v[76:79], v[80:83], v[2:17]
	s_lshl_b32 s10, s10, 1
	s_mov_b32 s11, s9
	s_add_i32 s13, s13, s12
	s_add_i32 s14, s14, s15
	s_add_i32 s16, s16, s17
	s_cmpk_lt_u32 s13, 0x400
	s_waitcnt lgkmcnt(1)
	v_mfma_f32_32x32x16_bf16 v[18:33], v[76:79], v[148:151], v[18:33]
	ds_read_b128 v[76:79], v72 offset:23040
	ds_read_b128 v[156:159], v72 offset:23072
	s_waitcnt lgkmcnt(1)
	v_mfma_f32_32x32x16_bf16 v[34:49], v[76:79], v[80:83], v[34:49]
	v_mfma_f32_32x32x16_bf16 v[50:65], v[76:79], v[148:151], v[50:65]
	v_mfma_f32_32x32x16_bf16 v[2:17], v[84:87], v[88:91], v[2:17]
	v_mfma_f32_32x32x16_bf16 v[18:33], v[84:87], v[152:155], v[18:33]
	s_waitcnt lgkmcnt(0)
	v_mfma_f32_32x32x16_bf16 v[34:49], v[156:159], v[88:91], v[34:49]
	ds_read_b128 v[76:79], v72 offset:18496
	ds_read_b128 v[80:83], v73 offset:55360
	ds_read_b128 v[84:87], v72 offset:18528
	ds_read_b128 v[88:91], v73 offset:55392
	v_mfma_f32_32x32x16_bf16 v[50:65], v[156:159], v[152:155], v[50:65]
	ds_read_b128 v[148:151], v73 offset:59968
	ds_read_b128 v[152:155], v73 offset:60000
	s_waitcnt lgkmcnt(4)
	v_mfma_f32_32x32x16_bf16 v[2:17], v[76:79], v[80:83], v[2:17]
	s_waitcnt lgkmcnt(1)
	v_mfma_f32_32x32x16_bf16 v[18:33], v[76:79], v[148:151], v[18:33]
	ds_read_b128 v[76:79], v72 offset:23104
	ds_read_b128 v[156:159], v72 offset:23136
	s_waitcnt lgkmcnt(0)
	s_barrier
	v_mfma_f32_32x32x16_bf16 v[34:49], v[76:79], v[80:83], v[34:49]
	v_mfma_f32_32x32x16_bf16 v[50:65], v[76:79], v[148:151], v[50:65]
	v_mfma_f32_32x32x16_bf16 v[2:17], v[84:87], v[88:91], v[2:17]
	v_mfma_f32_32x32x16_bf16 v[18:33], v[84:87], v[152:155], v[18:33]
	v_mfma_f32_32x32x16_bf16 v[34:49], v[156:159], v[88:91], v[34:49]
	s_nop 10
	ds_write2_b32 v101, v2, v18 offset1:32
	v_mfma_f32_32x32x16_bf16 v[50:65], v[156:159], v[152:155], v[50:65]
	s_nop 11
	ds_write2_b32 v132, v34, v50 offset0:32 offset1:64
	ds_write2_b32 v101, v3, v19 offset0:129 offset1:161
	ds_write2_b32 v132, v35, v51 offset0:161 offset1:193
	ds_write2_b32 v133, v4, v20 offset0:2 offset1:34
	ds_write2_b32 v134, v36, v52 offset0:34 offset1:66
	ds_write2_b32 v133, v5, v21 offset0:131 offset1:163
	ds_write2_b32 v134, v37, v53 offset0:163 offset1:195
	ds_write2_b32 v135, v6, v22 offset0:8 offset1:40
	ds_write2_b32 v136, v38, v54 offset0:40 offset1:72
	ds_write2_b32 v135, v7, v23 offset0:137 offset1:169
	ds_write2_b32 v136, v39, v55 offset0:169 offset1:201
	ds_write2_b32 v137, v8, v24 offset0:10 offset1:42
	ds_write2_b32 v138, v40, v56 offset0:42 offset1:74
	ds_write2_b32 v137, v9, v25 offset0:139 offset1:171
	ds_write2_b32 v138, v41, v57 offset0:171 offset1:203
	ds_write2_b32 v139, v10, v26 offset0:16 offset1:48
	ds_write2_b32 v140, v42, v58 offset0:48 offset1:80
	ds_write2_b32 v139, v11, v27 offset0:145 offset1:177
	ds_write2_b32 v140, v43, v59 offset0:177 offset1:209
	ds_write2_b32 v141, v12, v28 offset0:18 offset1:50
	ds_write2_b32 v142, v44, v60 offset0:50 offset1:82
	ds_write2_b32 v141, v13, v29 offset0:147 offset1:179
	ds_write2_b32 v142, v45, v61 offset0:179 offset1:211
	ds_write2_b32 v143, v14, v30 offset0:24 offset1:56
	ds_write2_b32 v144, v46, v62 offset0:56 offset1:88
	ds_write2_b32 v143, v15, v31 offset0:153 offset1:185
	ds_write2_b32 v144, v47, v63 offset0:185 offset1:217
	ds_write2_b32 v145, v16, v32 offset0:26 offset1:58
	ds_write2_b32 v146, v48, v64 offset0:58 offset1:90
	ds_write2_b32 v145, v17, v33 offset0:155 offset1:187
	ds_write2_b32 v146, v49, v65 offset0:187 offset1:219
	v_lshl_add_u64 v[2:3], v[66:67], 2, s[6:7]
	s_waitcnt lgkmcnt(0)
	s_barrier
	v_mov_b32_e32 v2, v66
	v_lshlrev_b32_e32 v3, 2, v2
	global_load_dword v5, v3, s[6:7]
	global_load_dword v6, v3, s[6:7] offset:64
	global_load_dword v7, v3, s[6:7] offset:128
	global_load_dword v8, v3, s[6:7] offset:192
	global_load_dword v9, v3, s[6:7] offset:256
	global_load_dword v10, v3, s[6:7] offset:320
	global_load_dword v11, v3, s[6:7] offset:384
	global_load_dword v12, v3, s[6:7] offset:448
	v_lshlrev_b32_e32 v4, 13, v2
	v_add3_u32 v4, v4, v74, s10
	s_movk_i32 s24, 0x7fff
	v_mov_b32_e32 v59, 1
	v_mov_b32_e32 v13, 0x358637bd
	ds_read2_b32 v[14:15], v103 offset0:0 offset1:1
	ds_read2_b32 v[16:17], v103 offset0:2 offset1:3
	ds_read2_b32 v[18:19], v103 offset0:4 offset1:5
	ds_read2_b32 v[20:21], v103 offset0:6 offset1:7
	v_add_u32_e32 v56, 0x2040, v103
	ds_read2_b32 v[22:23], v56 offset0:0 offset1:1
	ds_read2_b32 v[24:25], v56 offset0:2 offset1:3
	ds_read2_b32 v[26:27], v56 offset0:4 offset1:5
	ds_read2_b32 v[28:29], v56 offset0:6 offset1:7
	s_waitcnt vmcnt(7) lgkmcnt(4)
	v_fmamk_f32 v54, v5, 0x3a800000, v13
	v_rsq_f32_e32 v54, v54
	s_nop 0
	v_mul_f32_e32 v14, v14, v54
	v_mul_f32_e32 v15, v15, v54
	v_mul_f32_e32 v16, v16, v54
	v_mul_f32_e32 v17, v17, v54
	v_mul_f32_e32 v18, v18, v54
	v_mul_f32_e32 v19, v19, v54
	v_mul_f32_e32 v20, v20, v54
	v_mul_f32_e32 v21, v21, v54
	v_max_f32_e32 v14, 0, v14
	v_max_f32_e32 v15, 0, v15
	v_max_f32_e32 v16, 0, v16
	v_max_f32_e32 v17, 0, v17
	v_max_f32_e32 v18, 0, v18
	v_max_f32_e32 v19, 0, v19
	v_max_f32_e32 v20, 0, v20
	v_max_f32_e32 v21, 0, v21
	v_pk_mul_f32 v[14:15], v[14:15], v[14:15]
	v_pk_mul_f32 v[16:17], v[16:17], v[16:17]
	v_pk_mul_f32 v[18:19], v[18:19], v[18:19]
	v_pk_mul_f32 v[20:21], v[20:21], v[20:21]
	v_and_b32_sdwa v46, v14, v59 dst_sel:DWORD dst_unused:UNUSED_PAD src0_sel:WORD_1 src1_sel:DWORD
	v_and_b32_sdwa v47, v15, v59 dst_sel:DWORD dst_unused:UNUSED_PAD src0_sel:WORD_1 src1_sel:DWORD
	v_and_b32_sdwa v48, v16, v59 dst_sel:DWORD dst_unused:UNUSED_PAD src0_sel:WORD_1 src1_sel:DWORD
	v_and_b32_sdwa v49, v17, v59 dst_sel:DWORD dst_unused:UNUSED_PAD src0_sel:WORD_1 src1_sel:DWORD
	v_and_b32_sdwa v50, v18, v59 dst_sel:DWORD dst_unused:UNUSED_PAD src0_sel:WORD_1 src1_sel:DWORD
	v_and_b32_sdwa v51, v19, v59 dst_sel:DWORD dst_unused:UNUSED_PAD src0_sel:WORD_1 src1_sel:DWORD
	v_and_b32_sdwa v52, v20, v59 dst_sel:DWORD dst_unused:UNUSED_PAD src0_sel:WORD_1 src1_sel:DWORD
	v_and_b32_sdwa v53, v21, v59 dst_sel:DWORD dst_unused:UNUSED_PAD src0_sel:WORD_1 src1_sel:DWORD
	v_add3_u32 v14, v14, v46, s24
	v_add3_u32 v15, v15, v47, s24
	v_add3_u32 v16, v16, v48, s24
	v_add3_u32 v17, v17, v49, s24
	v_add3_u32 v18, v18, v50, s24
	v_add3_u32 v19, v19, v51, s24
	v_add3_u32 v20, v20, v52, s24
	v_add3_u32 v21, v21, v53, s24
	v_and_b32_e32 v15, 0xffff0000, v15
	v_and_b32_e32 v17, 0xffff0000, v17
	v_and_b32_e32 v19, 0xffff0000, v19
	v_and_b32_e32 v21, 0xffff0000, v21
	v_or_b32_sdwa v60, v15, v14 dst_sel:DWORD dst_unused:UNUSED_PAD src0_sel:DWORD src1_sel:WORD_1
	v_or_b32_sdwa v61, v17, v16 dst_sel:DWORD dst_unused:UNUSED_PAD src0_sel:DWORD src1_sel:WORD_1
	v_or_b32_sdwa v62, v19, v18 dst_sel:DWORD dst_unused:UNUSED_PAD src0_sel:DWORD src1_sel:WORD_1
	v_or_b32_sdwa v63, v21, v20 dst_sel:DWORD dst_unused:UNUSED_PAD src0_sel:DWORD src1_sel:WORD_1
	global_store_dwordx4 v4, v[60:63], s[56:57] nt
	v_add_u32_e32 v55, 0x4080, v103
	ds_read2_b32 v[30:31], v55 offset0:0 offset1:1
	ds_read2_b32 v[32:33], v55 offset0:2 offset1:3
	ds_read2_b32 v[34:35], v55 offset0:4 offset1:5
	ds_read2_b32 v[36:37], v55 offset0:6 offset1:7
	v_add_u32_e32 v56, 0x60c0, v103
	ds_read2_b32 v[38:39], v56 offset0:0 offset1:1
	ds_read2_b32 v[40:41], v56 offset0:2 offset1:3
	ds_read2_b32 v[42:43], v56 offset0:4 offset1:5
	ds_read2_b32 v[44:45], v56 offset0:6 offset1:7
	s_waitcnt vmcnt(7) lgkmcnt(8)
	v_fmamk_f32 v54, v6, 0x3a800000, v13
	v_rsq_f32_e32 v54, v54
	v_add_u32_e32 v58, 0x20000, v4
	v_mul_f32_e32 v22, v22, v54
	v_mul_f32_e32 v23, v23, v54
	v_mul_f32_e32 v24, v24, v54
	v_mul_f32_e32 v25, v25, v54
	v_mul_f32_e32 v26, v26, v54
	v_mul_f32_e32 v27, v27, v54
	v_mul_f32_e32 v28, v28, v54
	v_mul_f32_e32 v29, v29, v54
	v_max_f32_e32 v22, 0, v22
	v_max_f32_e32 v23, 0, v23
	v_max_f32_e32 v24, 0, v24
	v_max_f32_e32 v25, 0, v25
	v_max_f32_e32 v26, 0, v26
	v_max_f32_e32 v27, 0, v27
	v_max_f32_e32 v28, 0, v28
	v_max_f32_e32 v29, 0, v29
	v_pk_mul_f32 v[22:23], v[22:23], v[22:23]
	v_pk_mul_f32 v[24:25], v[24:25], v[24:25]
	v_pk_mul_f32 v[26:27], v[26:27], v[26:27]
	v_pk_mul_f32 v[28:29], v[28:29], v[28:29]
	v_and_b32_sdwa v46, v22, v59 dst_sel:DWORD dst_unused:UNUSED_PAD src0_sel:WORD_1 src1_sel:DWORD
	v_and_b32_sdwa v47, v23, v59 dst_sel:DWORD dst_unused:UNUSED_PAD src0_sel:WORD_1 src1_sel:DWORD
	v_and_b32_sdwa v48, v24, v59 dst_sel:DWORD dst_unused:UNUSED_PAD src0_sel:WORD_1 src1_sel:DWORD
	v_and_b32_sdwa v49, v25, v59 dst_sel:DWORD dst_unused:UNUSED_PAD src0_sel:WORD_1 src1_sel:DWORD
	v_and_b32_sdwa v50, v26, v59 dst_sel:DWORD dst_unused:UNUSED_PAD src0_sel:WORD_1 src1_sel:DWORD
	v_and_b32_sdwa v51, v27, v59 dst_sel:DWORD dst_unused:UNUSED_PAD src0_sel:WORD_1 src1_sel:DWORD
	v_and_b32_sdwa v52, v28, v59 dst_sel:DWORD dst_unused:UNUSED_PAD src0_sel:WORD_1 src1_sel:DWORD
	v_and_b32_sdwa v53, v29, v59 dst_sel:DWORD dst_unused:UNUSED_PAD src0_sel:WORD_1 src1_sel:DWORD
	v_add3_u32 v22, v22, v46, s24
	v_add3_u32 v23, v23, v47, s24
	v_add3_u32 v24, v24, v48, s24
	v_add3_u32 v25, v25, v49, s24
	v_add3_u32 v26, v26, v50, s24
	v_add3_u32 v27, v27, v51, s24
	v_add3_u32 v28, v28, v52, s24
	v_add3_u32 v29, v29, v53, s24
	v_and_b32_e32 v23, 0xffff0000, v23
	v_and_b32_e32 v25, 0xffff0000, v25
	v_and_b32_e32 v27, 0xffff0000, v27
	v_and_b32_e32 v29, 0xffff0000, v29
	v_or_b32_sdwa v76, v23, v22 dst_sel:DWORD dst_unused:UNUSED_PAD src0_sel:DWORD src1_sel:WORD_1
	v_or_b32_sdwa v77, v25, v24 dst_sel:DWORD dst_unused:UNUSED_PAD src0_sel:DWORD src1_sel:WORD_1
	v_or_b32_sdwa v78, v27, v26 dst_sel:DWORD dst_unused:UNUSED_PAD src0_sel:DWORD src1_sel:WORD_1
	v_or_b32_sdwa v79, v29, v28 dst_sel:DWORD dst_unused:UNUSED_PAD src0_sel:DWORD src1_sel:WORD_1
	global_store_dwordx4 v58, v[76:79], s[56:57] nt
	s_waitcnt vmcnt(7) lgkmcnt(4)
	v_fmamk_f32 v54, v7, 0x3a800000, v13
	v_rsq_f32_e32 v54, v54
	v_add_u32_e32 v57, 0x40000, v4
	v_mul_f32_e32 v30, v30, v54
	v_mul_f32_e32 v31, v31, v54
	v_mul_f32_e32 v32, v32, v54
	v_mul_f32_e32 v33, v33, v54
	v_mul_f32_e32 v34, v34, v54
	v_mul_f32_e32 v35, v35, v54
	v_mul_f32_e32 v36, v36, v54
	v_mul_f32_e32 v37, v37, v54
	v_max_f32_e32 v30, 0, v30
	v_max_f32_e32 v31, 0, v31
	v_max_f32_e32 v32, 0, v32
	v_max_f32_e32 v33, 0, v33
	v_max_f32_e32 v34, 0, v34
	v_max_f32_e32 v35, 0, v35
	v_max_f32_e32 v36, 0, v36
	v_max_f32_e32 v37, 0, v37
	v_pk_mul_f32 v[30:31], v[30:31], v[30:31]
	v_pk_mul_f32 v[32:33], v[32:33], v[32:33]
	v_pk_mul_f32 v[34:35], v[34:35], v[34:35]
	v_pk_mul_f32 v[36:37], v[36:37], v[36:37]
	v_and_b32_sdwa v46, v30, v59 dst_sel:DWORD dst_unused:UNUSED_PAD src0_sel:WORD_1 src1_sel:DWORD
	v_and_b32_sdwa v47, v31, v59 dst_sel:DWORD dst_unused:UNUSED_PAD src0_sel:WORD_1 src1_sel:DWORD
	v_and_b32_sdwa v48, v32, v59 dst_sel:DWORD dst_unused:UNUSED_PAD src0_sel:WORD_1 src1_sel:DWORD
	v_and_b32_sdwa v49, v33, v59 dst_sel:DWORD dst_unused:UNUSED_PAD src0_sel:WORD_1 src1_sel:DWORD
	v_and_b32_sdwa v50, v34, v59 dst_sel:DWORD dst_unused:UNUSED_PAD src0_sel:WORD_1 src1_sel:DWORD
	v_and_b32_sdwa v51, v35, v59 dst_sel:DWORD dst_unused:UNUSED_PAD src0_sel:WORD_1 src1_sel:DWORD
	v_and_b32_sdwa v52, v36, v59 dst_sel:DWORD dst_unused:UNUSED_PAD src0_sel:WORD_1 src1_sel:DWORD
	v_and_b32_sdwa v53, v37, v59 dst_sel:DWORD dst_unused:UNUSED_PAD src0_sel:WORD_1 src1_sel:DWORD
	v_add3_u32 v30, v30, v46, s24
	v_add3_u32 v31, v31, v47, s24
	v_add3_u32 v32, v32, v48, s24
	v_add3_u32 v33, v33, v49, s24
	v_add3_u32 v34, v34, v50, s24
	v_add3_u32 v35, v35, v51, s24
	v_add3_u32 v36, v36, v52, s24
	v_add3_u32 v37, v37, v53, s24
	v_and_b32_e32 v31, 0xffff0000, v31
	v_and_b32_e32 v33, 0xffff0000, v33
	v_and_b32_e32 v35, 0xffff0000, v35
	v_and_b32_e32 v37, 0xffff0000, v37
	v_or_b32_sdwa v60, v31, v30 dst_sel:DWORD dst_unused:UNUSED_PAD src0_sel:DWORD src1_sel:WORD_1
	v_or_b32_sdwa v61, v33, v32 dst_sel:DWORD dst_unused:UNUSED_PAD src0_sel:DWORD src1_sel:WORD_1
	v_or_b32_sdwa v62, v35, v34 dst_sel:DWORD dst_unused:UNUSED_PAD src0_sel:DWORD src1_sel:WORD_1
	v_or_b32_sdwa v63, v37, v36 dst_sel:DWORD dst_unused:UNUSED_PAD src0_sel:DWORD src1_sel:WORD_1
	global_store_dwordx4 v57, v[60:63], s[56:57] nt
	v_add_u32_e32 v55, 0x8100, v103
	ds_read2_b32 v[14:15], v55 offset0:0 offset1:1
	ds_read2_b32 v[16:17], v55 offset0:2 offset1:3
	ds_read2_b32 v[18:19], v55 offset0:4 offset1:5
	ds_read2_b32 v[20:21], v55 offset0:6 offset1:7
	v_add_u32_e32 v56, 0xa140, v103
	ds_read2_b32 v[22:23], v56 offset0:0 offset1:1
	ds_read2_b32 v[24:25], v56 offset0:2 offset1:3
	ds_read2_b32 v[26:27], v56 offset0:4 offset1:5
	ds_read2_b32 v[28:29], v56 offset0:6 offset1:7
	s_waitcnt vmcnt(7) lgkmcnt(8)
	v_fmamk_f32 v54, v8, 0x3a800000, v13
	v_rsq_f32_e32 v54, v54
	v_add_u32_e32 v58, 0x60000, v4
	v_mul_f32_e32 v38, v38, v54
	v_mul_f32_e32 v39, v39, v54
	v_mul_f32_e32 v40, v40, v54
	v_mul_f32_e32 v41, v41, v54
	v_mul_f32_e32 v42, v42, v54
	v_mul_f32_e32 v43, v43, v54
	v_mul_f32_e32 v44, v44, v54
	v_mul_f32_e32 v45, v45, v54
	v_max_f32_e32 v38, 0, v38
	v_max_f32_e32 v39, 0, v39
	v_max_f32_e32 v40, 0, v40
	v_max_f32_e32 v41, 0, v41
	v_max_f32_e32 v42, 0, v42
	v_max_f32_e32 v43, 0, v43
	v_max_f32_e32 v44, 0, v44
	v_max_f32_e32 v45, 0, v45
	v_pk_mul_f32 v[38:39], v[38:39], v[38:39]
	v_pk_mul_f32 v[40:41], v[40:41], v[40:41]
	v_pk_mul_f32 v[42:43], v[42:43], v[42:43]
	v_pk_mul_f32 v[44:45], v[44:45], v[44:45]
	v_and_b32_sdwa v46, v38, v59 dst_sel:DWORD dst_unused:UNUSED_PAD src0_sel:WORD_1 src1_sel:DWORD
	v_and_b32_sdwa v47, v39, v59 dst_sel:DWORD dst_unused:UNUSED_PAD src0_sel:WORD_1 src1_sel:DWORD
	v_and_b32_sdwa v48, v40, v59 dst_sel:DWORD dst_unused:UNUSED_PAD src0_sel:WORD_1 src1_sel:DWORD
	v_and_b32_sdwa v49, v41, v59 dst_sel:DWORD dst_unused:UNUSED_PAD src0_sel:WORD_1 src1_sel:DWORD
	v_and_b32_sdwa v50, v42, v59 dst_sel:DWORD dst_unused:UNUSED_PAD src0_sel:WORD_1 src1_sel:DWORD
	v_and_b32_sdwa v51, v43, v59 dst_sel:DWORD dst_unused:UNUSED_PAD src0_sel:WORD_1 src1_sel:DWORD
	v_and_b32_sdwa v52, v44, v59 dst_sel:DWORD dst_unused:UNUSED_PAD src0_sel:WORD_1 src1_sel:DWORD
	v_and_b32_sdwa v53, v45, v59 dst_sel:DWORD dst_unused:UNUSED_PAD src0_sel:WORD_1 src1_sel:DWORD
	v_add3_u32 v38, v38, v46, s24
	v_add3_u32 v39, v39, v47, s24
	v_add3_u32 v40, v40, v48, s24
	v_add3_u32 v41, v41, v49, s24
	v_add3_u32 v42, v42, v50, s24
	v_add3_u32 v43, v43, v51, s24
	v_add3_u32 v44, v44, v52, s24
	v_add3_u32 v45, v45, v53, s24
	v_and_b32_e32 v39, 0xffff0000, v39
	v_and_b32_e32 v41, 0xffff0000, v41
	v_and_b32_e32 v43, 0xffff0000, v43
	v_and_b32_e32 v45, 0xffff0000, v45
	v_or_b32_sdwa v76, v39, v38 dst_sel:DWORD dst_unused:UNUSED_PAD src0_sel:DWORD src1_sel:WORD_1
	v_or_b32_sdwa v77, v41, v40 dst_sel:DWORD dst_unused:UNUSED_PAD src0_sel:DWORD src1_sel:WORD_1
	v_or_b32_sdwa v78, v43, v42 dst_sel:DWORD dst_unused:UNUSED_PAD src0_sel:DWORD src1_sel:WORD_1
	v_or_b32_sdwa v79, v45, v44 dst_sel:DWORD dst_unused:UNUSED_PAD src0_sel:DWORD src1_sel:WORD_1
	global_store_dwordx4 v58, v[76:79], s[56:57] nt
	s_waitcnt vmcnt(7) lgkmcnt(4)
	v_fmamk_f32 v54, v9, 0x3a800000, v13
	v_rsq_f32_e32 v54, v54
	v_add_u32_e32 v57, 0x80000, v4
	v_mul_f32_e32 v14, v14, v54
	v_mul_f32_e32 v15, v15, v54
	v_mul_f32_e32 v16, v16, v54
	v_mul_f32_e32 v17, v17, v54
	v_mul_f32_e32 v18, v18, v54
	v_mul_f32_e32 v19, v19, v54
	v_mul_f32_e32 v20, v20, v54
	v_mul_f32_e32 v21, v21, v54
	v_max_f32_e32 v14, 0, v14
	v_max_f32_e32 v15, 0, v15
	v_max_f32_e32 v16, 0, v16
	v_max_f32_e32 v17, 0, v17
	v_max_f32_e32 v18, 0, v18
	v_max_f32_e32 v19, 0, v19
	v_max_f32_e32 v20, 0, v20
	v_max_f32_e32 v21, 0, v21
	v_pk_mul_f32 v[14:15], v[14:15], v[14:15]
	v_pk_mul_f32 v[16:17], v[16:17], v[16:17]
	v_pk_mul_f32 v[18:19], v[18:19], v[18:19]
	v_pk_mul_f32 v[20:21], v[20:21], v[20:21]
	v_and_b32_sdwa v46, v14, v59 dst_sel:DWORD dst_unused:UNUSED_PAD src0_sel:WORD_1 src1_sel:DWORD
	v_and_b32_sdwa v47, v15, v59 dst_sel:DWORD dst_unused:UNUSED_PAD src0_sel:WORD_1 src1_sel:DWORD
	v_and_b32_sdwa v48, v16, v59 dst_sel:DWORD dst_unused:UNUSED_PAD src0_sel:WORD_1 src1_sel:DWORD
	v_and_b32_sdwa v49, v17, v59 dst_sel:DWORD dst_unused:UNUSED_PAD src0_sel:WORD_1 src1_sel:DWORD
	v_and_b32_sdwa v50, v18, v59 dst_sel:DWORD dst_unused:UNUSED_PAD src0_sel:WORD_1 src1_sel:DWORD
	v_and_b32_sdwa v51, v19, v59 dst_sel:DWORD dst_unused:UNUSED_PAD src0_sel:WORD_1 src1_sel:DWORD
	v_and_b32_sdwa v52, v20, v59 dst_sel:DWORD dst_unused:UNUSED_PAD src0_sel:WORD_1 src1_sel:DWORD
	v_and_b32_sdwa v53, v21, v59 dst_sel:DWORD dst_unused:UNUSED_PAD src0_sel:WORD_1 src1_sel:DWORD
	v_add3_u32 v14, v14, v46, s24
	v_add3_u32 v15, v15, v47, s24
	v_add3_u32 v16, v16, v48, s24
	v_add3_u32 v17, v17, v49, s24
	v_add3_u32 v18, v18, v50, s24
	v_add3_u32 v19, v19, v51, s24
	v_add3_u32 v20, v20, v52, s24
	v_add3_u32 v21, v21, v53, s24
	v_and_b32_e32 v15, 0xffff0000, v15
	v_and_b32_e32 v17, 0xffff0000, v17
	v_and_b32_e32 v19, 0xffff0000, v19
	v_and_b32_e32 v21, 0xffff0000, v21
	v_or_b32_sdwa v60, v15, v14 dst_sel:DWORD dst_unused:UNUSED_PAD src0_sel:DWORD src1_sel:WORD_1
	v_or_b32_sdwa v61, v17, v16 dst_sel:DWORD dst_unused:UNUSED_PAD src0_sel:DWORD src1_sel:WORD_1
	v_or_b32_sdwa v62, v19, v18 dst_sel:DWORD dst_unused:UNUSED_PAD src0_sel:DWORD src1_sel:WORD_1
	v_or_b32_sdwa v63, v21, v20 dst_sel:DWORD dst_unused:UNUSED_PAD src0_sel:DWORD src1_sel:WORD_1
	global_store_dwordx4 v57, v[60:63], s[56:57] nt
	v_add_u32_e32 v55, 0xc180, v103
	ds_read2_b32 v[30:31], v55 offset0:0 offset1:1
	ds_read2_b32 v[32:33], v55 offset0:2 offset1:3
	ds_read2_b32 v[34:35], v55 offset0:4 offset1:5
	ds_read2_b32 v[36:37], v55 offset0:6 offset1:7
	v_add_u32_e32 v56, 0xe1c0, v103
	ds_read2_b32 v[38:39], v56 offset0:0 offset1:1
	ds_read2_b32 v[40:41], v56 offset0:2 offset1:3
	ds_read2_b32 v[42:43], v56 offset0:4 offset1:5
	ds_read2_b32 v[44:45], v56 offset0:6 offset1:7
	s_waitcnt vmcnt(7) lgkmcnt(8)
	v_fmamk_f32 v54, v10, 0x3a800000, v13
	v_rsq_f32_e32 v54, v54
	v_add_u32_e32 v58, 0xa0000, v4
	v_mul_f32_e32 v22, v22, v54
	v_mul_f32_e32 v23, v23, v54
	v_mul_f32_e32 v24, v24, v54
	v_mul_f32_e32 v25, v25, v54
	v_mul_f32_e32 v26, v26, v54
	v_mul_f32_e32 v27, v27, v54
	v_mul_f32_e32 v28, v28, v54
	v_mul_f32_e32 v29, v29, v54
	v_max_f32_e32 v22, 0, v22
	v_max_f32_e32 v23, 0, v23
	v_max_f32_e32 v24, 0, v24
	v_max_f32_e32 v25, 0, v25
	v_max_f32_e32 v26, 0, v26
	v_max_f32_e32 v27, 0, v27
	v_max_f32_e32 v28, 0, v28
	v_max_f32_e32 v29, 0, v29
	v_pk_mul_f32 v[22:23], v[22:23], v[22:23]
	v_pk_mul_f32 v[24:25], v[24:25], v[24:25]
	v_pk_mul_f32 v[26:27], v[26:27], v[26:27]
	v_pk_mul_f32 v[28:29], v[28:29], v[28:29]
	v_and_b32_sdwa v46, v22, v59 dst_sel:DWORD dst_unused:UNUSED_PAD src0_sel:WORD_1 src1_sel:DWORD
	v_and_b32_sdwa v47, v23, v59 dst_sel:DWORD dst_unused:UNUSED_PAD src0_sel:WORD_1 src1_sel:DWORD
	v_and_b32_sdwa v48, v24, v59 dst_sel:DWORD dst_unused:UNUSED_PAD src0_sel:WORD_1 src1_sel:DWORD
	v_and_b32_sdwa v49, v25, v59 dst_sel:DWORD dst_unused:UNUSED_PAD src0_sel:WORD_1 src1_sel:DWORD
	v_and_b32_sdwa v50, v26, v59 dst_sel:DWORD dst_unused:UNUSED_PAD src0_sel:WORD_1 src1_sel:DWORD
	v_and_b32_sdwa v51, v27, v59 dst_sel:DWORD dst_unused:UNUSED_PAD src0_sel:WORD_1 src1_sel:DWORD
	v_and_b32_sdwa v52, v28, v59 dst_sel:DWORD dst_unused:UNUSED_PAD src0_sel:WORD_1 src1_sel:DWORD
	v_and_b32_sdwa v53, v29, v59 dst_sel:DWORD dst_unused:UNUSED_PAD src0_sel:WORD_1 src1_sel:DWORD
	v_add3_u32 v22, v22, v46, s24
	v_add3_u32 v23, v23, v47, s24
	v_add3_u32 v24, v24, v48, s24
	v_add3_u32 v25, v25, v49, s24
	v_add3_u32 v26, v26, v50, s24
	v_add3_u32 v27, v27, v51, s24
	v_add3_u32 v28, v28, v52, s24
	v_add3_u32 v29, v29, v53, s24
	v_and_b32_e32 v23, 0xffff0000, v23
	v_and_b32_e32 v25, 0xffff0000, v25
	v_and_b32_e32 v27, 0xffff0000, v27
	v_and_b32_e32 v29, 0xffff0000, v29
	v_or_b32_sdwa v76, v23, v22 dst_sel:DWORD dst_unused:UNUSED_PAD src0_sel:DWORD src1_sel:WORD_1
	v_or_b32_sdwa v77, v25, v24 dst_sel:DWORD dst_unused:UNUSED_PAD src0_sel:DWORD src1_sel:WORD_1
	v_or_b32_sdwa v78, v27, v26 dst_sel:DWORD dst_unused:UNUSED_PAD src0_sel:DWORD src1_sel:WORD_1
	v_or_b32_sdwa v79, v29, v28 dst_sel:DWORD dst_unused:UNUSED_PAD src0_sel:DWORD src1_sel:WORD_1
	global_store_dwordx4 v58, v[76:79], s[56:57] nt
	s_waitcnt vmcnt(7) lgkmcnt(4)
	v_fmamk_f32 v54, v11, 0x3a800000, v13
	v_rsq_f32_e32 v54, v54
	v_add_u32_e32 v57, 0xc0000, v4
	v_mul_f32_e32 v30, v30, v54
	v_mul_f32_e32 v31, v31, v54
	v_mul_f32_e32 v32, v32, v54
	v_mul_f32_e32 v33, v33, v54
	v_mul_f32_e32 v34, v34, v54
	v_mul_f32_e32 v35, v35, v54
	v_mul_f32_e32 v36, v36, v54
	v_mul_f32_e32 v37, v37, v54
	v_max_f32_e32 v30, 0, v30
	v_max_f32_e32 v31, 0, v31
	v_max_f32_e32 v32, 0, v32
	v_max_f32_e32 v33, 0, v33
	v_max_f32_e32 v34, 0, v34
	v_max_f32_e32 v35, 0, v35
	v_max_f32_e32 v36, 0, v36
	v_max_f32_e32 v37, 0, v37
	v_pk_mul_f32 v[30:31], v[30:31], v[30:31]
	v_pk_mul_f32 v[32:33], v[32:33], v[32:33]
	v_pk_mul_f32 v[34:35], v[34:35], v[34:35]
	v_pk_mul_f32 v[36:37], v[36:37], v[36:37]
	v_and_b32_sdwa v46, v30, v59 dst_sel:DWORD dst_unused:UNUSED_PAD src0_sel:WORD_1 src1_sel:DWORD
	v_and_b32_sdwa v47, v31, v59 dst_sel:DWORD dst_unused:UNUSED_PAD src0_sel:WORD_1 src1_sel:DWORD
	v_and_b32_sdwa v48, v32, v59 dst_sel:DWORD dst_unused:UNUSED_PAD src0_sel:WORD_1 src1_sel:DWORD
	v_and_b32_sdwa v49, v33, v59 dst_sel:DWORD dst_unused:UNUSED_PAD src0_sel:WORD_1 src1_sel:DWORD
	v_and_b32_sdwa v50, v34, v59 dst_sel:DWORD dst_unused:UNUSED_PAD src0_sel:WORD_1 src1_sel:DWORD
	v_and_b32_sdwa v51, v35, v59 dst_sel:DWORD dst_unused:UNUSED_PAD src0_sel:WORD_1 src1_sel:DWORD
	v_and_b32_sdwa v52, v36, v59 dst_sel:DWORD dst_unused:UNUSED_PAD src0_sel:WORD_1 src1_sel:DWORD
	v_and_b32_sdwa v53, v37, v59 dst_sel:DWORD dst_unused:UNUSED_PAD src0_sel:WORD_1 src1_sel:DWORD
	v_add3_u32 v30, v30, v46, s24
	v_add3_u32 v31, v31, v47, s24
	v_add3_u32 v32, v32, v48, s24
	v_add3_u32 v33, v33, v49, s24
	v_add3_u32 v34, v34, v50, s24
	v_add3_u32 v35, v35, v51, s24
	v_add3_u32 v36, v36, v52, s24
	v_add3_u32 v37, v37, v53, s24
	v_and_b32_e32 v31, 0xffff0000, v31
	v_and_b32_e32 v33, 0xffff0000, v33
	v_and_b32_e32 v35, 0xffff0000, v35
	v_and_b32_e32 v37, 0xffff0000, v37
	v_or_b32_sdwa v60, v31, v30 dst_sel:DWORD dst_unused:UNUSED_PAD src0_sel:DWORD src1_sel:WORD_1
	v_or_b32_sdwa v61, v33, v32 dst_sel:DWORD dst_unused:UNUSED_PAD src0_sel:DWORD src1_sel:WORD_1
	v_or_b32_sdwa v62, v35, v34 dst_sel:DWORD dst_unused:UNUSED_PAD src0_sel:DWORD src1_sel:WORD_1
	v_or_b32_sdwa v63, v37, v36 dst_sel:DWORD dst_unused:UNUSED_PAD src0_sel:DWORD src1_sel:WORD_1
	global_store_dwordx4 v57, v[60:63], s[56:57] nt
	s_waitcnt vmcnt(7) lgkmcnt(0)
	v_fmamk_f32 v54, v12, 0x3a800000, v13
	v_rsq_f32_e32 v54, v54
	v_add_u32_e32 v58, 0xe0000, v4
	v_mul_f32_e32 v38, v38, v54
	v_mul_f32_e32 v39, v39, v54
	v_mul_f32_e32 v40, v40, v54
	v_mul_f32_e32 v41, v41, v54
	v_mul_f32_e32 v42, v42, v54
	v_mul_f32_e32 v43, v43, v54
	v_mul_f32_e32 v44, v44, v54
	v_mul_f32_e32 v45, v45, v54
	v_max_f32_e32 v38, 0, v38
	v_max_f32_e32 v39, 0, v39
	v_max_f32_e32 v40, 0, v40
	v_max_f32_e32 v41, 0, v41
	v_max_f32_e32 v42, 0, v42
	v_max_f32_e32 v43, 0, v43
	v_max_f32_e32 v44, 0, v44
	v_max_f32_e32 v45, 0, v45
	v_pk_mul_f32 v[38:39], v[38:39], v[38:39]
	v_pk_mul_f32 v[40:41], v[40:41], v[40:41]
	v_pk_mul_f32 v[42:43], v[42:43], v[42:43]
	v_pk_mul_f32 v[44:45], v[44:45], v[44:45]
	v_and_b32_sdwa v46, v38, v59 dst_sel:DWORD dst_unused:UNUSED_PAD src0_sel:WORD_1 src1_sel:DWORD
	v_and_b32_sdwa v47, v39, v59 dst_sel:DWORD dst_unused:UNUSED_PAD src0_sel:WORD_1 src1_sel:DWORD
	v_and_b32_sdwa v48, v40, v59 dst_sel:DWORD dst_unused:UNUSED_PAD src0_sel:WORD_1 src1_sel:DWORD
	v_and_b32_sdwa v49, v41, v59 dst_sel:DWORD dst_unused:UNUSED_PAD src0_sel:WORD_1 src1_sel:DWORD
	v_and_b32_sdwa v50, v42, v59 dst_sel:DWORD dst_unused:UNUSED_PAD src0_sel:WORD_1 src1_sel:DWORD
	v_and_b32_sdwa v51, v43, v59 dst_sel:DWORD dst_unused:UNUSED_PAD src0_sel:WORD_1 src1_sel:DWORD
	v_and_b32_sdwa v52, v44, v59 dst_sel:DWORD dst_unused:UNUSED_PAD src0_sel:WORD_1 src1_sel:DWORD
	v_and_b32_sdwa v53, v45, v59 dst_sel:DWORD dst_unused:UNUSED_PAD src0_sel:WORD_1 src1_sel:DWORD
	v_add3_u32 v38, v38, v46, s24
	v_add3_u32 v39, v39, v47, s24
	v_add3_u32 v40, v40, v48, s24
	v_add3_u32 v41, v41, v49, s24
	v_add3_u32 v42, v42, v50, s24
	v_add3_u32 v43, v43, v51, s24
	v_add3_u32 v44, v44, v52, s24
	v_add3_u32 v45, v45, v53, s24
	v_and_b32_e32 v39, 0xffff0000, v39
	v_and_b32_e32 v41, 0xffff0000, v41
	v_and_b32_e32 v43, 0xffff0000, v43
	v_and_b32_e32 v45, 0xffff0000, v45
	v_or_b32_sdwa v76, v39, v38 dst_sel:DWORD dst_unused:UNUSED_PAD src0_sel:DWORD src1_sel:WORD_1
	v_or_b32_sdwa v77, v41, v40 dst_sel:DWORD dst_unused:UNUSED_PAD src0_sel:DWORD src1_sel:WORD_1
	v_or_b32_sdwa v78, v43, v42 dst_sel:DWORD dst_unused:UNUSED_PAD src0_sel:DWORD src1_sel:WORD_1
	v_or_b32_sdwa v79, v45, v44 dst_sel:DWORD dst_unused:UNUSED_PAD src0_sel:DWORD src1_sel:WORD_1
	global_store_dwordx4 v58, v[76:79], s[56:57] nt
	s_cmpk_lt_u32 s13, 0x400
	s_barrier
	s_cbranch_scc1 .LBB0_338

.LBB0_590:
	s_lshr_b32 s8, s12, 2
	s_and_b32 s10, s16, 56
	s_and_b32 s8, s8, 0x1ffffc0
	s_or_b32 s10, s10, s3
	s_or_b32 s8, s10, s8
	s_lshl_b32 s8, s8, 7
	s_lshl_b64 s[24:25], s[8:9], 11
	v_lshl_add_u64 v[78:79], v[70:71], 0, s[24:25]
	v_add_co_u32_e32 v80, vcc, s18, v78
	s_and_b32 s10, s14, 0xf80
	s_nop 0
	v_addc_co_u32_e32 v81, vcc, 0, v79, vcc
	s_lshl_b32 s26, s10, 11
	s_mov_b32 s27, s9
	v_add_co_u32_e32 v82, vcc, s19, v78
	v_lshl_add_u64 v[76:77], v[72:73], 0, s[26:27]
	s_nop 0
	v_addc_co_u32_e32 v83, vcc, 0, v79, vcc
	v_add_co_u32_e32 v84, vcc, s18, v76
	global_load_dwordx4 v[2:5], v[78:79], off
	global_load_dwordx4 v[6:9], v[80:81], off
	v_addc_co_u32_e32 v85, vcc, 0, v77, vcc
	v_add_co_u32_e32 v86, vcc, s19, v76
	global_load_dwordx4 v[10:13], v[82:83], off
	global_load_dwordx4 v[14:17], v[76:77], off
	v_addc_co_u32_e32 v87, vcc, 0, v77, vcc
	global_load_dwordx4 v[18:21], v[84:85], off
	global_load_dwordx4 v[22:25], v[86:87], off
	v_add_co_u32_e32 v88, vcc, s20, v76
	s_nop 1
	v_addc_co_u32_e32 v89, vcc, 0, v77, vcc
	global_load_dwordx4 v[26:29], v[88:89], off
	v_add_co_u32_e32 v90, vcc, s20, v78
	s_nop 1
	v_addc_co_u32_e32 v91, vcc, 0, v79, vcc
	global_load_dwordx4 v[30:33], v[90:91], off
	global_load_dwordx4 v[148:151], v[76:77], off offset:128
	global_load_dwordx4 v[152:155], v[84:85], off offset:128
	global_load_dwordx4 v[156:159], v[86:87], off offset:128
	global_load_dwordx4 v[160:163], v[88:89], off offset:128
	global_load_dwordx4 v[164:167], v[78:79], off offset:128
	global_load_dwordx4 v[168:171], v[80:81], off offset:128
	global_load_dwordx4 v[172:175], v[82:83], off offset:128
	global_load_dwordx4 v[176:179], v[90:91], off offset:128
	s_waitcnt vmcnt(12)
	ds_write_b128 v1, v[14:17] offset:36864
	s_waitcnt vmcnt(11)
	ds_write_b128 v1, v[18:21] offset:41472
	s_waitcnt vmcnt(10)
	ds_write_b128 v1, v[22:25] offset:46080
	s_waitcnt vmcnt(9)
	ds_write_b128 v1, v[26:29] offset:50688
	ds_write_b128 v1, v[2:5]
	ds_write_b128 v1, v[6:9] offset:4608
	ds_write_b128 v1, v[10:13] offset:9216
	s_waitcnt vmcnt(8)
	ds_write_b128 v1, v[30:33] offset:13824
	s_waitcnt lgkmcnt(0)
	s_barrier
	global_load_dwordx4 v[180:183], v[80:81], off offset:256
	global_load_dwordx4 v[184:187], v[82:83], off offset:256
	global_load_dwordx4 v[188:191], v[78:79], off offset:256
	global_load_dwordx4 v[192:195], v[76:77], off offset:256
	global_load_dwordx4 v[196:199], v[90:91], off offset:256
	global_load_dwordx4 v[200:203], v[84:85], off offset:256
	global_load_dwordx4 v[204:207], v[86:87], off offset:256
	global_load_dwordx4 v[208:211], v[88:89], off offset:256
	ds_read_b128 v[18:21], v66
	ds_read_b128 v[34:37], v67 offset:36864
	ds_read_b128 v[212:215], v66 offset:32
	ds_read_b128 v[216:219], v67 offset:36896
	ds_read_b128 v[50:53], v67 offset:41472
	ds_read_b128 v[220:223], v67 offset:41504
	ds_read_b128 v[54:57], v66 offset:4608
	ds_read_b128 v[224:227], v66 offset:4640
	s_waitcnt lgkmcnt(6)
	v_mfma_f32_32x32x16_bf16 v[2:17], v[18:21], v[34:37], 0
	s_waitcnt lgkmcnt(3)
	v_mfma_f32_32x32x16_bf16 v[18:33], v[18:21], v[50:53], 0
	s_waitcnt lgkmcnt(1)
	v_mfma_f32_32x32x16_bf16 v[34:49], v[54:57], v[34:37], 0
	v_mfma_f32_32x32x16_bf16 v[50:65], v[54:57], v[50:53], 0
	v_mfma_f32_32x32x16_bf16 v[2:17], v[212:215], v[216:219], v[2:17]
	v_mfma_f32_32x32x16_bf16 v[18:33], v[212:215], v[220:223], v[18:33]
	s_waitcnt lgkmcnt(0)
	v_mfma_f32_32x32x16_bf16 v[34:49], v[224:227], v[216:219], v[34:49]
	v_mfma_f32_32x32x16_bf16 v[50:65], v[224:227], v[220:223], v[50:65]
	ds_read_b128 v[212:215], v66 offset:64
	ds_read_b128 v[216:219], v67 offset:36928
	ds_read_b128 v[220:223], v66 offset:96
	ds_read_b128 v[224:227], v67 offset:36960
	ds_read_b128 v[228:231], v67 offset:41536
	ds_read_b128 v[232:235], v67 offset:41568
	s_waitcnt lgkmcnt(4)
	v_mfma_f32_32x32x16_bf16 v[2:17], v[212:215], v[216:219], v[2:17]
	s_waitcnt lgkmcnt(1)
	v_mfma_f32_32x32x16_bf16 v[18:33], v[212:215], v[228:231], v[18:33]
	ds_read_b128 v[212:215], v66 offset:4672
	ds_read_b128 v[236:239], v66 offset:4704
	s_waitcnt vmcnt(11)
	ds_write_b128 v1, v[164:167] offset:18432
	s_waitcnt vmcnt(10)
	ds_write_b128 v1, v[168:171] offset:23040
	s_waitcnt vmcnt(9)
	ds_write_b128 v1, v[172:175] offset:27648
	s_waitcnt vmcnt(8)
	ds_write_b128 v1, v[176:179] offset:32256
	ds_write_b128 v1, v[148:151] offset:55296
	ds_write_b128 v1, v[152:155] offset:59904
	ds_write_b128 v1, v[156:159] offset:64512
	ds_write_b128 v92, v[160:163] offset:32256
	global_load_dwordx4 v[148:151], v[80:81], off offset:384
	global_load_dwordx4 v[152:155], v[82:83], off offset:384
	global_load_dwordx4 v[156:159], v[78:79], off offset:384
	global_load_dwordx4 v[160:163], v[76:77], off offset:384
	global_load_dwordx4 v[164:167], v[90:91], off offset:384
	global_load_dwordx4 v[168:171], v[84:85], off offset:384
	global_load_dwordx4 v[172:175], v[86:87], off offset:384
	global_load_dwordx4 v[176:179], v[88:89], off offset:384
	s_waitcnt lgkmcnt(0)
	s_barrier
	v_mfma_f32_32x32x16_bf16 v[34:49], v[212:215], v[216:219], v[34:49]
	v_mfma_f32_32x32x16_bf16 v[50:65], v[212:215], v[228:231], v[50:65]
	v_mfma_f32_32x32x16_bf16 v[2:17], v[220:223], v[224:227], v[2:17]
	v_mfma_f32_32x32x16_bf16 v[18:33], v[220:223], v[232:235], v[18:33]
	v_mfma_f32_32x32x16_bf16 v[34:49], v[236:239], v[224:227], v[34:49]
	v_mfma_f32_32x32x16_bf16 v[50:65], v[236:239], v[232:235], v[50:65]
	ds_read_b128 v[212:215], v66 offset:18432
	ds_read_b128 v[216:219], v67 offset:55296
	ds_read_b128 v[220:223], v66 offset:18464
	ds_read_b128 v[224:227], v67 offset:55328
	ds_read_b128 v[228:231], v67 offset:59904
	ds_read_b128 v[232:235], v67 offset:59936
	s_waitcnt lgkmcnt(4)
	v_mfma_f32_32x32x16_bf16 v[2:17], v[212:215], v[216:219], v[2:17]
	s_waitcnt lgkmcnt(1)
	v_mfma_f32_32x32x16_bf16 v[18:33], v[212:215], v[228:231], v[18:33]
	ds_read_b128 v[212:215], v66 offset:23040
	ds_read_b128 v[236:239], v66 offset:23072
	s_waitcnt lgkmcnt(1)
	v_mfma_f32_32x32x16_bf16 v[34:49], v[212:215], v[216:219], v[34:49]
	v_mfma_f32_32x32x16_bf16 v[50:65], v[212:215], v[228:231], v[50:65]
	v_mfma_f32_32x32x16_bf16 v[2:17], v[220:223], v[224:227], v[2:17]
	v_mfma_f32_32x32x16_bf16 v[18:33], v[220:223], v[232:235], v[18:33]
	s_waitcnt lgkmcnt(0)
	v_mfma_f32_32x32x16_bf16 v[34:49], v[236:239], v[224:227], v[34:49]
	ds_read_b128 v[212:215], v66 offset:18496
	ds_read_b128 v[216:219], v67 offset:55360
	ds_read_b128 v[220:223], v66 offset:18528
	ds_read_b128 v[224:227], v67 offset:55392
	v_mfma_f32_32x32x16_bf16 v[50:65], v[236:239], v[232:235], v[50:65]
	ds_read_b128 v[228:231], v67 offset:59968
	ds_read_b128 v[232:235], v67 offset:60000
	s_waitcnt lgkmcnt(4)
	v_mfma_f32_32x32x16_bf16 v[2:17], v[212:215], v[216:219], v[2:17]
	s_waitcnt lgkmcnt(1)
	v_mfma_f32_32x32x16_bf16 v[18:33], v[212:215], v[228:231], v[18:33]
	ds_read_b128 v[212:215], v66 offset:23104
	ds_read_b128 v[236:239], v66 offset:23136
	s_waitcnt vmcnt(13)
	ds_write_b128 v1, v[188:191]
	ds_write_b128 v1, v[180:183] offset:4608
	ds_write_b128 v1, v[184:187] offset:9216
	s_waitcnt vmcnt(11)
	ds_write_b128 v1, v[196:199] offset:13824
	ds_write_b128 v1, v[192:195] offset:36864
	s_waitcnt vmcnt(10)
	ds_write_b128 v1, v[200:203] offset:41472
	s_waitcnt vmcnt(9)
	ds_write_b128 v1, v[204:207] offset:46080
	s_waitcnt vmcnt(8)
	ds_write_b128 v1, v[208:211] offset:50688
	global_load_dwordx4 v[180:183], v[80:81], off offset:512
	global_load_dwordx4 v[184:187], v[82:83], off offset:512
	global_load_dwordx4 v[188:191], v[78:79], off offset:512
	global_load_dwordx4 v[192:195], v[76:77], off offset:512
	global_load_dwordx4 v[196:199], v[90:91], off offset:512
	global_load_dwordx4 v[200:203], v[84:85], off offset:512
	global_load_dwordx4 v[204:207], v[86:87], off offset:512
	global_load_dwordx4 v[208:211], v[88:89], off offset:512
	s_waitcnt lgkmcnt(0)
	s_barrier
	v_mfma_f32_32x32x16_bf16 v[34:49], v[212:215], v[216:219], v[34:49]
	v_mfma_f32_32x32x16_bf16 v[50:65], v[212:215], v[228:231], v[50:65]
	v_mfma_f32_32x32x16_bf16 v[2:17], v[220:223], v[224:227], v[2:17]
	v_mfma_f32_32x32x16_bf16 v[18:33], v[220:223], v[232:235], v[18:33]
	v_mfma_f32_32x32x16_bf16 v[34:49], v[236:239], v[224:227], v[34:49]
	v_mfma_f32_32x32x16_bf16 v[50:65], v[236:239], v[232:235], v[50:65]
	ds_read_b128 v[212:215], v66
	ds_read_b128 v[216:219], v67 offset:36864
	ds_read_b128 v[220:223], v66 offset:32
	ds_read_b128 v[224:227], v67 offset:36896
	ds_read_b128 v[228:231], v67 offset:41472
	ds_read_b128 v[232:235], v67 offset:41504
	s_waitcnt lgkmcnt(4)
	v_mfma_f32_32x32x16_bf16 v[2:17], v[212:215], v[216:219], v[2:17]
	s_waitcnt lgkmcnt(1)
	v_mfma_f32_32x32x16_bf16 v[18:33], v[212:215], v[228:231], v[18:33]
	ds_read_b128 v[212:215], v66 offset:4608
	ds_read_b128 v[236:239], v66 offset:4640
	s_waitcnt lgkmcnt(1)
	v_mfma_f32_32x32x16_bf16 v[34:49], v[212:215], v[216:219], v[34:49]
	v_mfma_f32_32x32x16_bf16 v[50:65], v[212:215], v[228:231], v[50:65]
	v_mfma_f32_32x32x16_bf16 v[2:17], v[220:223], v[224:227], v[2:17]
	v_mfma_f32_32x32x16_bf16 v[18:33], v[220:223], v[232:235], v[18:33]
	s_waitcnt lgkmcnt(0)
	v_mfma_f32_32x32x16_bf16 v[34:49], v[236:239], v[224:227], v[34:49]
	ds_read_b128 v[212:215], v66 offset:64
	ds_read_b128 v[216:219], v67 offset:36928
	ds_read_b128 v[220:223], v66 offset:96
	ds_read_b128 v[224:227], v67 offset:36960
	v_mfma_f32_32x32x16_bf16 v[50:65], v[236:239], v[232:235], v[50:65]
	ds_read_b128 v[228:231], v67 offset:41536
	ds_read_b128 v[232:235], v67 offset:41568
	s_waitcnt lgkmcnt(4)
	v_mfma_f32_32x32x16_bf16 v[2:17], v[212:215], v[216:219], v[2:17]
	s_waitcnt lgkmcnt(1)
	v_mfma_f32_32x32x16_bf16 v[18:33], v[212:215], v[228:231], v[18:33]
	ds_read_b128 v[212:215], v66 offset:4672
	ds_read_b128 v[236:239], v66 offset:4704
	s_waitcnt vmcnt(13)
	ds_write_b128 v1, v[156:159] offset:18432
	ds_write_b128 v1, v[148:151] offset:23040
	ds_write_b128 v1, v[152:155] offset:27648
	s_waitcnt vmcnt(11)
	ds_write_b128 v1, v[164:167] offset:32256
	ds_write_b128 v1, v[160:163] offset:55296
	s_waitcnt vmcnt(10)
	ds_write_b128 v1, v[168:171] offset:59904
	s_waitcnt vmcnt(9)
	ds_write_b128 v1, v[172:175] offset:64512
	s_waitcnt vmcnt(8)
	ds_write_b128 v92, v[176:179] offset:32256
	global_load_dwordx4 v[148:151], v[80:81], off offset:640
	global_load_dwordx4 v[152:155], v[82:83], off offset:640
	global_load_dwordx4 v[156:159], v[78:79], off offset:640
	global_load_dwordx4 v[160:163], v[76:77], off offset:640
	global_load_dwordx4 v[164:167], v[90:91], off offset:640
	global_load_dwordx4 v[168:171], v[84:85], off offset:640
	global_load_dwordx4 v[172:175], v[86:87], off offset:640
	global_load_dwordx4 v[176:179], v[88:89], off offset:640
	s_waitcnt lgkmcnt(0)
	s_barrier
	v_mfma_f32_32x32x16_bf16 v[34:49], v[212:215], v[216:219], v[34:49]
	v_mfma_f32_32x32x16_bf16 v[50:65], v[212:215], v[228:231], v[50:65]
	v_mfma_f32_32x32x16_bf16 v[2:17], v[220:223], v[224:227], v[2:17]
	v_mfma_f32_32x32x16_bf16 v[18:33], v[220:223], v[232:235], v[18:33]
	v_mfma_f32_32x32x16_bf16 v[34:49], v[236:239], v[224:227], v[34:49]
	v_mfma_f32_32x32x16_bf16 v[50:65], v[236:239], v[232:235], v[50:65]
	ds_read_b128 v[212:215], v66 offset:18432
	ds_read_b128 v[216:219], v67 offset:55296
	ds_read_b128 v[220:223], v66 offset:18464
	ds_read_b128 v[224:227], v67 offset:55328
	ds_read_b128 v[228:231], v67 offset:59904
	ds_read_b128 v[232:235], v67 offset:59936
	s_waitcnt lgkmcnt(4)
	v_mfma_f32_32x32x16_bf16 v[2:17], v[212:215], v[216:219], v[2:17]
	s_waitcnt lgkmcnt(1)
	v_mfma_f32_32x32x16_bf16 v[18:33], v[212:215], v[228:231], v[18:33]
	ds_read_b128 v[212:215], v66 offset:23040
	ds_read_b128 v[236:239], v66 offset:23072
	s_waitcnt lgkmcnt(1)
	v_mfma_f32_32x32x16_bf16 v[34:49], v[212:215], v[216:219], v[34:49]
	v_mfma_f32_32x32x16_bf16 v[50:65], v[212:215], v[228:231], v[50:65]
	v_mfma_f32_32x32x16_bf16 v[2:17], v[220:223], v[224:227], v[2:17]
	v_mfma_f32_32x32x16_bf16 v[18:33], v[220:223], v[232:235], v[18:33]
	s_waitcnt lgkmcnt(0)
	v_mfma_f32_32x32x16_bf16 v[34:49], v[236:239], v[224:227], v[34:49]
	ds_read_b128 v[212:215], v66 offset:18496
	ds_read_b128 v[216:219], v67 offset:55360
	ds_read_b128 v[220:223], v66 offset:18528
	ds_read_b128 v[224:227], v67 offset:55392
	v_mfma_f32_32x32x16_bf16 v[50:65], v[236:239], v[232:235], v[50:65]
	ds_read_b128 v[228:231], v67 offset:59968
	ds_read_b128 v[232:235], v67 offset:60000
	s_waitcnt lgkmcnt(4)
	v_mfma_f32_32x32x16_bf16 v[2:17], v[212:215], v[216:219], v[2:17]
	s_waitcnt lgkmcnt(1)
	v_mfma_f32_32x32x16_bf16 v[18:33], v[212:215], v[228:231], v[18:33]
	ds_read_b128 v[212:215], v66 offset:23104
	ds_read_b128 v[236:239], v66 offset:23136
	s_waitcnt vmcnt(13)
	ds_write_b128 v1, v[188:191]
	ds_write_b128 v1, v[180:183] offset:4608
	ds_write_b128 v1, v[184:187] offset:9216
	s_waitcnt vmcnt(11)
	ds_write_b128 v1, v[196:199] offset:13824
	ds_write_b128 v1, v[192:195] offset:36864
	s_waitcnt vmcnt(10)
	ds_write_b128 v1, v[200:203] offset:41472
	s_waitcnt vmcnt(9)
	ds_write_b128 v1, v[204:207] offset:46080
	s_waitcnt vmcnt(8)
	ds_write_b128 v1, v[208:211] offset:50688
	global_load_dwordx4 v[180:183], v[80:81], off offset:768
	global_load_dwordx4 v[184:187], v[82:83], off offset:768
	global_load_dwordx4 v[188:191], v[78:79], off offset:768
	global_load_dwordx4 v[192:195], v[76:77], off offset:768
	global_load_dwordx4 v[196:199], v[90:91], off offset:768
	global_load_dwordx4 v[200:203], v[84:85], off offset:768
	global_load_dwordx4 v[204:207], v[86:87], off offset:768
	global_load_dwordx4 v[208:211], v[88:89], off offset:768
	s_waitcnt lgkmcnt(0)
	s_barrier
	v_mfma_f32_32x32x16_bf16 v[34:49], v[212:215], v[216:219], v[34:49]
	v_mfma_f32_32x32x16_bf16 v[50:65], v[212:215], v[228:231], v[50:65]
	v_mfma_f32_32x32x16_bf16 v[2:17], v[220:223], v[224:227], v[2:17]
	v_mfma_f32_32x32x16_bf16 v[18:33], v[220:223], v[232:235], v[18:33]
	v_mfma_f32_32x32x16_bf16 v[34:49], v[236:239], v[224:227], v[34:49]
	v_mfma_f32_32x32x16_bf16 v[50:65], v[236:239], v[232:235], v[50:65]
	ds_read_b128 v[212:215], v66
	ds_read_b128 v[216:219], v67 offset:36864
	ds_read_b128 v[220:223], v66 offset:32
	ds_read_b128 v[224:227], v67 offset:36896
	ds_read_b128 v[228:231], v67 offset:41472
	ds_read_b128 v[232:235], v67 offset:41504
	s_waitcnt lgkmcnt(4)
	v_mfma_f32_32x32x16_bf16 v[2:17], v[212:215], v[216:219], v[2:17]
	s_waitcnt lgkmcnt(1)
	v_mfma_f32_32x32x16_bf16 v[18:33], v[212:215], v[228:231], v[18:33]
	ds_read_b128 v[212:215], v66 offset:4608
	ds_read_b128 v[236:239], v66 offset:4640
	s_waitcnt lgkmcnt(1)
	v_mfma_f32_32x32x16_bf16 v[34:49], v[212:215], v[216:219], v[34:49]
	v_mfma_f32_32x32x16_bf16 v[50:65], v[212:215], v[228:231], v[50:65]
	v_mfma_f32_32x32x16_bf16 v[2:17], v[220:223], v[224:227], v[2:17]
	v_mfma_f32_32x32x16_bf16 v[18:33], v[220:223], v[232:235], v[18:33]
	s_waitcnt lgkmcnt(0)
	v_mfma_f32_32x32x16_bf16 v[34:49], v[236:239], v[224:227], v[34:49]
	ds_read_b128 v[212:215], v66 offset:64
	ds_read_b128 v[216:219], v67 offset:36928
	ds_read_b128 v[220:223], v66 offset:96
	ds_read_b128 v[224:227], v67 offset:36960
	v_mfma_f32_32x32x16_bf16 v[50:65], v[236:239], v[232:235], v[50:65]
	ds_read_b128 v[228:231], v67 offset:41536
	ds_read_b128 v[232:235], v67 offset:41568
	s_waitcnt lgkmcnt(4)
	v_mfma_f32_32x32x16_bf16 v[2:17], v[212:215], v[216:219], v[2:17]
	s_waitcnt lgkmcnt(1)
	v_mfma_f32_32x32x16_bf16 v[18:33], v[212:215], v[228:231], v[18:33]
	ds_read_b128 v[212:215], v66 offset:4672
	ds_read_b128 v[236:239], v66 offset:4704
	s_waitcnt vmcnt(13)
	ds_write_b128 v1, v[156:159] offset:18432
	ds_write_b128 v1, v[148:151] offset:23040
	ds_write_b128 v1, v[152:155] offset:27648
	s_waitcnt vmcnt(11)
	ds_write_b128 v1, v[164:167] offset:32256
	ds_write_b128 v1, v[160:163] offset:55296
	s_waitcnt vmcnt(10)
	ds_write_b128 v1, v[168:171] offset:59904
	s_waitcnt vmcnt(9)
	ds_write_b128 v1, v[172:175] offset:64512
	s_waitcnt vmcnt(8)
	ds_write_b128 v92, v[176:179] offset:32256
	global_load_dwordx4 v[148:151], v[80:81], off offset:896
	global_load_dwordx4 v[152:155], v[82:83], off offset:896
	global_load_dwordx4 v[156:159], v[78:79], off offset:896
	global_load_dwordx4 v[160:163], v[76:77], off offset:896
	global_load_dwordx4 v[164:167], v[90:91], off offset:896
	global_load_dwordx4 v[168:171], v[84:85], off offset:896
	global_load_dwordx4 v[172:175], v[86:87], off offset:896
	global_load_dwordx4 v[176:179], v[88:89], off offset:896
	s_waitcnt lgkmcnt(0)
	s_barrier
	v_mfma_f32_32x32x16_bf16 v[34:49], v[212:215], v[216:219], v[34:49]
	v_mfma_f32_32x32x16_bf16 v[50:65], v[212:215], v[228:231], v[50:65]
	v_mfma_f32_32x32x16_bf16 v[2:17], v[220:223], v[224:227], v[2:17]
	v_mfma_f32_32x32x16_bf16 v[18:33], v[220:223], v[232:235], v[18:33]
	v_mfma_f32_32x32x16_bf16 v[34:49], v[236:239], v[224:227], v[34:49]
	v_mfma_f32_32x32x16_bf16 v[50:65], v[236:239], v[232:235], v[50:65]
	ds_read_b128 v[212:215], v66 offset:18432
	ds_read_b128 v[216:219], v67 offset:55296
	ds_read_b128 v[220:223], v66 offset:18464
	ds_read_b128 v[224:227], v67 offset:55328
	ds_read_b128 v[228:231], v67 offset:59904
	ds_read_b128 v[232:235], v67 offset:59936
	s_waitcnt lgkmcnt(4)
	v_mfma_f32_32x32x16_bf16 v[2:17], v[212:215], v[216:219], v[2:17]
	s_waitcnt lgkmcnt(1)
	v_mfma_f32_32x32x16_bf16 v[18:33], v[212:215], v[228:231], v[18:33]
	ds_read_b128 v[212:215], v66 offset:23040
	ds_read_b128 v[236:239], v66 offset:23072
	s_waitcnt lgkmcnt(1)
	v_mfma_f32_32x32x16_bf16 v[34:49], v[212:215], v[216:219], v[34:49]
	v_mfma_f32_32x32x16_bf16 v[50:65], v[212:215], v[228:231], v[50:65]
	v_mfma_f32_32x32x16_bf16 v[2:17], v[220:223], v[224:227], v[2:17]
	v_mfma_f32_32x32x16_bf16 v[18:33], v[220:223], v[232:235], v[18:33]
	s_waitcnt lgkmcnt(0)
	v_mfma_f32_32x32x16_bf16 v[34:49], v[236:239], v[224:227], v[34:49]
	ds_read_b128 v[212:215], v66 offset:18496
	ds_read_b128 v[216:219], v67 offset:55360
	ds_read_b128 v[220:223], v66 offset:18528
	ds_read_b128 v[224:227], v67 offset:55392
	v_mfma_f32_32x32x16_bf16 v[50:65], v[236:239], v[232:235], v[50:65]
	ds_read_b128 v[228:231], v67 offset:59968
	ds_read_b128 v[232:235], v67 offset:60000
	s_waitcnt lgkmcnt(4)
	v_mfma_f32_32x32x16_bf16 v[2:17], v[212:215], v[216:219], v[2:17]
	s_waitcnt lgkmcnt(1)
	v_mfma_f32_32x32x16_bf16 v[18:33], v[212:215], v[228:231], v[18:33]
	ds_read_b128 v[212:215], v66 offset:23104
	ds_read_b128 v[236:239], v66 offset:23136
	s_waitcnt vmcnt(13)
	ds_write_b128 v1, v[188:191]
	ds_write_b128 v1, v[180:183] offset:4608
	ds_write_b128 v1, v[184:187] offset:9216
	s_waitcnt vmcnt(11)
	ds_write_b128 v1, v[196:199] offset:13824
	ds_write_b128 v1, v[192:195] offset:36864
	s_waitcnt vmcnt(10)
	ds_write_b128 v1, v[200:203] offset:41472
	s_waitcnt vmcnt(9)
	ds_write_b128 v1, v[204:207] offset:46080
	s_waitcnt vmcnt(8)
	ds_write_b128 v1, v[208:211] offset:50688
	global_load_dwordx4 v[180:183], v[80:81], off offset:1024
	global_load_dwordx4 v[184:187], v[82:83], off offset:1024
	global_load_dwordx4 v[188:191], v[78:79], off offset:1024
	global_load_dwordx4 v[192:195], v[76:77], off offset:1024
	global_load_dwordx4 v[196:199], v[90:91], off offset:1024
	global_load_dwordx4 v[200:203], v[84:85], off offset:1024
	global_load_dwordx4 v[204:207], v[86:87], off offset:1024
	global_load_dwordx4 v[208:211], v[88:89], off offset:1024
	s_waitcnt lgkmcnt(0)
	s_barrier
	v_mfma_f32_32x32x16_bf16 v[34:49], v[212:215], v[216:219], v[34:49]
	v_mfma_f32_32x32x16_bf16 v[50:65], v[212:215], v[228:231], v[50:65]
	v_mfma_f32_32x32x16_bf16 v[2:17], v[220:223], v[224:227], v[2:17]
	v_mfma_f32_32x32x16_bf16 v[18:33], v[220:223], v[232:235], v[18:33]
	v_mfma_f32_32x32x16_bf16 v[34:49], v[236:239], v[224:227], v[34:49]
	v_mfma_f32_32x32x16_bf16 v[50:65], v[236:239], v[232:235], v[50:65]
	ds_read_b128 v[212:215], v66
	ds_read_b128 v[216:219], v67 offset:36864
	ds_read_b128 v[220:223], v66 offset:32
	ds_read_b128 v[224:227], v67 offset:36896
	ds_read_b128 v[228:231], v67 offset:41472
	ds_read_b128 v[232:235], v67 offset:41504
	s_waitcnt lgkmcnt(4)
	v_mfma_f32_32x32x16_bf16 v[2:17], v[212:215], v[216:219], v[2:17]
	s_waitcnt lgkmcnt(1)
	v_mfma_f32_32x32x16_bf16 v[18:33], v[212:215], v[228:231], v[18:33]
	ds_read_b128 v[212:215], v66 offset:4608
	ds_read_b128 v[236:239], v66 offset:4640
	s_waitcnt lgkmcnt(1)
	v_mfma_f32_32x32x16_bf16 v[34:49], v[212:215], v[216:219], v[34:49]
	v_mfma_f32_32x32x16_bf16 v[50:65], v[212:215], v[228:231], v[50:65]
	v_mfma_f32_32x32x16_bf16 v[2:17], v[220:223], v[224:227], v[2:17]
	v_mfma_f32_32x32x16_bf16 v[18:33], v[220:223], v[232:235], v[18:33]
	s_waitcnt lgkmcnt(0)
	v_mfma_f32_32x32x16_bf16 v[34:49], v[236:239], v[224:227], v[34:49]
	ds_read_b128 v[212:215], v66 offset:64
	ds_read_b128 v[216:219], v67 offset:36928
	ds_read_b128 v[220:223], v66 offset:96
	ds_read_b128 v[224:227], v67 offset:36960
	v_mfma_f32_32x32x16_bf16 v[50:65], v[236:239], v[232:235], v[50:65]
	ds_read_b128 v[228:231], v67 offset:41536
	ds_read_b128 v[232:235], v67 offset:41568
	s_waitcnt lgkmcnt(4)
	v_mfma_f32_32x32x16_bf16 v[2:17], v[212:215], v[216:219], v[2:17]
	s_waitcnt lgkmcnt(1)
	v_mfma_f32_32x32x16_bf16 v[18:33], v[212:215], v[228:231], v[18:33]
	ds_read_b128 v[212:215], v66 offset:4672
	ds_read_b128 v[236:239], v66 offset:4704
	s_waitcnt vmcnt(13)
	ds_write_b128 v1, v[156:159] offset:18432
	ds_write_b128 v1, v[148:151] offset:23040
	ds_write_b128 v1, v[152:155] offset:27648
	s_waitcnt vmcnt(11)
	ds_write_b128 v1, v[164:167] offset:32256
	ds_write_b128 v1, v[160:163] offset:55296
	s_waitcnt vmcnt(10)
	ds_write_b128 v1, v[168:171] offset:59904
	s_waitcnt vmcnt(9)
	ds_write_b128 v1, v[172:175] offset:64512
	s_waitcnt vmcnt(8)
	ds_write_b128 v92, v[176:179] offset:32256
	global_load_dwordx4 v[148:151], v[80:81], off offset:1152
	global_load_dwordx4 v[152:155], v[82:83], off offset:1152
	global_load_dwordx4 v[156:159], v[78:79], off offset:1152
	global_load_dwordx4 v[160:163], v[76:77], off offset:1152
	global_load_dwordx4 v[164:167], v[90:91], off offset:1152
	global_load_dwordx4 v[168:171], v[84:85], off offset:1152
	global_load_dwordx4 v[172:175], v[86:87], off offset:1152
	global_load_dwordx4 v[176:179], v[88:89], off offset:1152
	s_waitcnt lgkmcnt(0)
	s_barrier
	v_mfma_f32_32x32x16_bf16 v[34:49], v[212:215], v[216:219], v[34:49]
	v_mfma_f32_32x32x16_bf16 v[50:65], v[212:215], v[228:231], v[50:65]
	v_mfma_f32_32x32x16_bf16 v[2:17], v[220:223], v[224:227], v[2:17]
	v_mfma_f32_32x32x16_bf16 v[18:33], v[220:223], v[232:235], v[18:33]
	v_mfma_f32_32x32x16_bf16 v[34:49], v[236:239], v[224:227], v[34:49]
	v_mfma_f32_32x32x16_bf16 v[50:65], v[236:239], v[232:235], v[50:65]
	ds_read_b128 v[212:215], v66 offset:18432
	ds_read_b128 v[216:219], v67 offset:55296
	ds_read_b128 v[220:223], v66 offset:18464
	ds_read_b128 v[224:227], v67 offset:55328
	ds_read_b128 v[228:231], v67 offset:59904
	ds_read_b128 v[232:235], v67 offset:59936
	s_waitcnt lgkmcnt(4)
	v_mfma_f32_32x32x16_bf16 v[2:17], v[212:215], v[216:219], v[2:17]
	s_waitcnt lgkmcnt(1)
	v_mfma_f32_32x32x16_bf16 v[18:33], v[212:215], v[228:231], v[18:33]
	ds_read_b128 v[212:215], v66 offset:23040
	ds_read_b128 v[236:239], v66 offset:23072
	s_waitcnt lgkmcnt(1)
	v_mfma_f32_32x32x16_bf16 v[34:49], v[212:215], v[216:219], v[34:49]
	v_mfma_f32_32x32x16_bf16 v[50:65], v[212:215], v[228:231], v[50:65]
	v_mfma_f32_32x32x16_bf16 v[2:17], v[220:223], v[224:227], v[2:17]
	v_mfma_f32_32x32x16_bf16 v[18:33], v[220:223], v[232:235], v[18:33]
	s_waitcnt lgkmcnt(0)
	v_mfma_f32_32x32x16_bf16 v[34:49], v[236:239], v[224:227], v[34:49]
	ds_read_b128 v[212:215], v66 offset:18496
	ds_read_b128 v[216:219], v67 offset:55360
	ds_read_b128 v[220:223], v66 offset:18528
	ds_read_b128 v[224:227], v67 offset:55392
	v_mfma_f32_32x32x16_bf16 v[50:65], v[236:239], v[232:235], v[50:65]
	ds_read_b128 v[228:231], v67 offset:59968
	ds_read_b128 v[232:235], v67 offset:60000
	s_waitcnt lgkmcnt(4)
	v_mfma_f32_32x32x16_bf16 v[2:17], v[212:215], v[216:219], v[2:17]
	s_waitcnt lgkmcnt(1)
	v_mfma_f32_32x32x16_bf16 v[18:33], v[212:215], v[228:231], v[18:33]
	ds_read_b128 v[212:215], v66 offset:23104
	ds_read_b128 v[236:239], v66 offset:23136
	s_waitcnt vmcnt(13)
	ds_write_b128 v1, v[188:191]
	ds_write_b128 v1, v[180:183] offset:4608
	ds_write_b128 v1, v[184:187] offset:9216
	s_waitcnt vmcnt(11)
	ds_write_b128 v1, v[196:199] offset:13824
	ds_write_b128 v1, v[192:195] offset:36864
	s_waitcnt vmcnt(10)
	ds_write_b128 v1, v[200:203] offset:41472
	s_waitcnt vmcnt(9)
	ds_write_b128 v1, v[204:207] offset:46080
	s_waitcnt vmcnt(8)
	ds_write_b128 v1, v[208:211] offset:50688
	global_load_dwordx4 v[180:183], v[80:81], off offset:1280
	global_load_dwordx4 v[184:187], v[82:83], off offset:1280
	global_load_dwordx4 v[188:191], v[78:79], off offset:1280
	global_load_dwordx4 v[192:195], v[76:77], off offset:1280
	global_load_dwordx4 v[196:199], v[90:91], off offset:1280
	global_load_dwordx4 v[200:203], v[84:85], off offset:1280
	global_load_dwordx4 v[204:207], v[86:87], off offset:1280
	global_load_dwordx4 v[208:211], v[88:89], off offset:1280
	s_waitcnt lgkmcnt(0)
	s_barrier
	v_mfma_f32_32x32x16_bf16 v[34:49], v[212:215], v[216:219], v[34:49]
	v_mfma_f32_32x32x16_bf16 v[50:65], v[212:215], v[228:231], v[50:65]
	v_mfma_f32_32x32x16_bf16 v[2:17], v[220:223], v[224:227], v[2:17]
	v_mfma_f32_32x32x16_bf16 v[18:33], v[220:223], v[232:235], v[18:33]
	v_mfma_f32_32x32x16_bf16 v[34:49], v[236:239], v[224:227], v[34:49]
	v_mfma_f32_32x32x16_bf16 v[50:65], v[236:239], v[232:235], v[50:65]
	ds_read_b128 v[212:215], v66
	ds_read_b128 v[216:219], v67 offset:36864
	ds_read_b128 v[220:223], v66 offset:32
	ds_read_b128 v[224:227], v67 offset:36896
	ds_read_b128 v[228:231], v67 offset:41472
	ds_read_b128 v[232:235], v67 offset:41504
	s_waitcnt lgkmcnt(4)
	v_mfma_f32_32x32x16_bf16 v[2:17], v[212:215], v[216:219], v[2:17]
	s_waitcnt lgkmcnt(1)
	v_mfma_f32_32x32x16_bf16 v[18:33], v[212:215], v[228:231], v[18:33]
	ds_read_b128 v[212:215], v66 offset:4608
	ds_read_b128 v[236:239], v66 offset:4640
	s_waitcnt lgkmcnt(1)
	v_mfma_f32_32x32x16_bf16 v[34:49], v[212:215], v[216:219], v[34:49]
	v_mfma_f32_32x32x16_bf16 v[50:65], v[212:215], v[228:231], v[50:65]
	v_mfma_f32_32x32x16_bf16 v[2:17], v[220:223], v[224:227], v[2:17]
	v_mfma_f32_32x32x16_bf16 v[18:33], v[220:223], v[232:235], v[18:33]
	s_waitcnt lgkmcnt(0)
	v_mfma_f32_32x32x16_bf16 v[34:49], v[236:239], v[224:227], v[34:49]
	ds_read_b128 v[212:215], v66 offset:64
	ds_read_b128 v[216:219], v67 offset:36928
	ds_read_b128 v[220:223], v66 offset:96
	ds_read_b128 v[224:227], v67 offset:36960
	v_mfma_f32_32x32x16_bf16 v[50:65], v[236:239], v[232:235], v[50:65]
	ds_read_b128 v[228:231], v67 offset:41536
	ds_read_b128 v[232:235], v67 offset:41568
	s_waitcnt lgkmcnt(4)
	v_mfma_f32_32x32x16_bf16 v[2:17], v[212:215], v[216:219], v[2:17]
	s_waitcnt lgkmcnt(1)
	v_mfma_f32_32x32x16_bf16 v[18:33], v[212:215], v[228:231], v[18:33]
	ds_read_b128 v[212:215], v66 offset:4672
	ds_read_b128 v[236:239], v66 offset:4704
	s_waitcnt vmcnt(13)
	ds_write_b128 v1, v[156:159] offset:18432
	ds_write_b128 v1, v[148:151] offset:23040
	ds_write_b128 v1, v[152:155] offset:27648
	s_waitcnt vmcnt(11)
	ds_write_b128 v1, v[164:167] offset:32256
	ds_write_b128 v1, v[160:163] offset:55296
	s_waitcnt vmcnt(10)
	ds_write_b128 v1, v[168:171] offset:59904
	s_waitcnt vmcnt(9)
	ds_write_b128 v1, v[172:175] offset:64512
	s_waitcnt vmcnt(8)
	ds_write_b128 v92, v[176:179] offset:32256
	global_load_dwordx4 v[148:151], v[80:81], off offset:1408
	global_load_dwordx4 v[152:155], v[82:83], off offset:1408
	global_load_dwordx4 v[156:159], v[78:79], off offset:1408
	global_load_dwordx4 v[160:163], v[76:77], off offset:1408
	global_load_dwordx4 v[164:167], v[90:91], off offset:1408
	global_load_dwordx4 v[168:171], v[84:85], off offset:1408
	global_load_dwordx4 v[172:175], v[86:87], off offset:1408
	global_load_dwordx4 v[176:179], v[88:89], off offset:1408
	s_waitcnt lgkmcnt(0)
	s_barrier
	v_mfma_f32_32x32x16_bf16 v[34:49], v[212:215], v[216:219], v[34:49]
	v_mfma_f32_32x32x16_bf16 v[50:65], v[212:215], v[228:231], v[50:65]
	v_mfma_f32_32x32x16_bf16 v[2:17], v[220:223], v[224:227], v[2:17]
	v_mfma_f32_32x32x16_bf16 v[18:33], v[220:223], v[232:235], v[18:33]
	v_mfma_f32_32x32x16_bf16 v[34:49], v[236:239], v[224:227], v[34:49]
	v_mfma_f32_32x32x16_bf16 v[50:65], v[236:239], v[232:235], v[50:65]
	ds_read_b128 v[212:215], v66 offset:18432
	ds_read_b128 v[216:219], v67 offset:55296
	ds_read_b128 v[220:223], v66 offset:18464
	ds_read_b128 v[224:227], v67 offset:55328
	ds_read_b128 v[228:231], v67 offset:59904
	ds_read_b128 v[232:235], v67 offset:59936
	s_waitcnt lgkmcnt(4)
	v_mfma_f32_32x32x16_bf16 v[2:17], v[212:215], v[216:219], v[2:17]
	s_waitcnt lgkmcnt(1)
	v_mfma_f32_32x32x16_bf16 v[18:33], v[212:215], v[228:231], v[18:33]
	ds_read_b128 v[212:215], v66 offset:23040
	ds_read_b128 v[236:239], v66 offset:23072
	s_waitcnt lgkmcnt(1)
	v_mfma_f32_32x32x16_bf16 v[34:49], v[212:215], v[216:219], v[34:49]
	v_mfma_f32_32x32x16_bf16 v[50:65], v[212:215], v[228:231], v[50:65]
	v_mfma_f32_32x32x16_bf16 v[2:17], v[220:223], v[224:227], v[2:17]
	v_mfma_f32_32x32x16_bf16 v[18:33], v[220:223], v[232:235], v[18:33]
	s_waitcnt lgkmcnt(0)
	v_mfma_f32_32x32x16_bf16 v[34:49], v[236:239], v[224:227], v[34:49]
	ds_read_b128 v[212:215], v66 offset:18496
	ds_read_b128 v[216:219], v67 offset:55360
	ds_read_b128 v[220:223], v66 offset:18528
	ds_read_b128 v[224:227], v67 offset:55392
	v_mfma_f32_32x32x16_bf16 v[50:65], v[236:239], v[232:235], v[50:65]
	ds_read_b128 v[228:231], v67 offset:59968
	ds_read_b128 v[232:235], v67 offset:60000
	s_waitcnt lgkmcnt(4)
	v_mfma_f32_32x32x16_bf16 v[2:17], v[212:215], v[216:219], v[2:17]
	s_waitcnt lgkmcnt(1)
	v_mfma_f32_32x32x16_bf16 v[18:33], v[212:215], v[228:231], v[18:33]
	ds_read_b128 v[212:215], v66 offset:23104
	ds_read_b128 v[236:239], v66 offset:23136
	s_waitcnt vmcnt(13)
	ds_write_b128 v1, v[188:191]
	ds_write_b128 v1, v[180:183] offset:4608
	ds_write_b128 v1, v[184:187] offset:9216
	s_waitcnt vmcnt(11)
	ds_write_b128 v1, v[196:199] offset:13824
	ds_write_b128 v1, v[192:195] offset:36864
	s_waitcnt vmcnt(10)
	ds_write_b128 v1, v[200:203] offset:41472
	s_waitcnt vmcnt(9)
	ds_write_b128 v1, v[204:207] offset:46080
	s_waitcnt vmcnt(8)
	ds_write_b128 v1, v[208:211] offset:50688
	global_load_dwordx4 v[180:183], v[80:81], off offset:1536
	global_load_dwordx4 v[184:187], v[82:83], off offset:1536
	global_load_dwordx4 v[188:191], v[78:79], off offset:1536
	global_load_dwordx4 v[192:195], v[76:77], off offset:1536
	global_load_dwordx4 v[196:199], v[90:91], off offset:1536
	global_load_dwordx4 v[200:203], v[84:85], off offset:1536
	global_load_dwordx4 v[204:207], v[86:87], off offset:1536
	global_load_dwordx4 v[208:211], v[88:89], off offset:1536
	s_waitcnt lgkmcnt(0)
	s_barrier
	v_mfma_f32_32x32x16_bf16 v[34:49], v[212:215], v[216:219], v[34:49]
	v_mfma_f32_32x32x16_bf16 v[50:65], v[212:215], v[228:231], v[50:65]
	v_mfma_f32_32x32x16_bf16 v[2:17], v[220:223], v[224:227], v[2:17]
	v_mfma_f32_32x32x16_bf16 v[18:33], v[220:223], v[232:235], v[18:33]
	v_mfma_f32_32x32x16_bf16 v[34:49], v[236:239], v[224:227], v[34:49]
	v_mfma_f32_32x32x16_bf16 v[50:65], v[236:239], v[232:235], v[50:65]
	ds_read_b128 v[212:215], v66
	ds_read_b128 v[216:219], v67 offset:36864
	ds_read_b128 v[220:223], v66 offset:32
	ds_read_b128 v[224:227], v67 offset:36896
	ds_read_b128 v[228:231], v67 offset:41472
	ds_read_b128 v[232:235], v67 offset:41504
	s_waitcnt lgkmcnt(4)
	v_mfma_f32_32x32x16_bf16 v[2:17], v[212:215], v[216:219], v[2:17]
	s_waitcnt lgkmcnt(1)
	v_mfma_f32_32x32x16_bf16 v[18:33], v[212:215], v[228:231], v[18:33]
	ds_read_b128 v[212:215], v66 offset:4608
	ds_read_b128 v[236:239], v66 offset:4640
	s_waitcnt lgkmcnt(1)
	v_mfma_f32_32x32x16_bf16 v[34:49], v[212:215], v[216:219], v[34:49]
	v_mfma_f32_32x32x16_bf16 v[50:65], v[212:215], v[228:231], v[50:65]
	v_mfma_f32_32x32x16_bf16 v[2:17], v[220:223], v[224:227], v[2:17]
	v_mfma_f32_32x32x16_bf16 v[18:33], v[220:223], v[232:235], v[18:33]
	s_waitcnt lgkmcnt(0)
	v_mfma_f32_32x32x16_bf16 v[34:49], v[236:239], v[224:227], v[34:49]
	ds_read_b128 v[212:215], v66 offset:64
	ds_read_b128 v[216:219], v67 offset:36928
	ds_read_b128 v[220:223], v66 offset:96
	ds_read_b128 v[224:227], v67 offset:36960
	v_mfma_f32_32x32x16_bf16 v[50:65], v[236:239], v[232:235], v[50:65]
	ds_read_b128 v[228:231], v67 offset:41536
	ds_read_b128 v[232:235], v67 offset:41568
	s_waitcnt lgkmcnt(4)
	v_mfma_f32_32x32x16_bf16 v[2:17], v[212:215], v[216:219], v[2:17]
	s_waitcnt lgkmcnt(1)
	v_mfma_f32_32x32x16_bf16 v[18:33], v[212:215], v[228:231], v[18:33]
	ds_read_b128 v[212:215], v66 offset:4672
	ds_read_b128 v[236:239], v66 offset:4704
	s_waitcnt vmcnt(13)
	ds_write_b128 v1, v[156:159] offset:18432
	ds_write_b128 v1, v[148:151] offset:23040
	ds_write_b128 v1, v[152:155] offset:27648
	s_waitcnt vmcnt(11)
	ds_write_b128 v1, v[164:167] offset:32256
	ds_write_b128 v1, v[160:163] offset:55296
	s_waitcnt vmcnt(10)
	ds_write_b128 v1, v[168:171] offset:59904
	s_waitcnt vmcnt(9)
	ds_write_b128 v1, v[172:175] offset:64512
	s_waitcnt vmcnt(8)
	ds_write_b128 v92, v[176:179] offset:32256
	global_load_dwordx4 v[148:151], v[80:81], off offset:1664
	global_load_dwordx4 v[152:155], v[82:83], off offset:1664
	global_load_dwordx4 v[156:159], v[78:79], off offset:1664
	global_load_dwordx4 v[160:163], v[76:77], off offset:1664
	global_load_dwordx4 v[164:167], v[90:91], off offset:1664
	global_load_dwordx4 v[168:171], v[84:85], off offset:1664
	global_load_dwordx4 v[172:175], v[86:87], off offset:1664
	global_load_dwordx4 v[176:179], v[88:89], off offset:1664
	s_waitcnt lgkmcnt(0)
	s_barrier
	v_mfma_f32_32x32x16_bf16 v[34:49], v[212:215], v[216:219], v[34:49]
	v_mfma_f32_32x32x16_bf16 v[50:65], v[212:215], v[228:231], v[50:65]
	v_mfma_f32_32x32x16_bf16 v[2:17], v[220:223], v[224:227], v[2:17]
	v_mfma_f32_32x32x16_bf16 v[18:33], v[220:223], v[232:235], v[18:33]
	v_mfma_f32_32x32x16_bf16 v[34:49], v[236:239], v[224:227], v[34:49]
	v_mfma_f32_32x32x16_bf16 v[50:65], v[236:239], v[232:235], v[50:65]
	ds_read_b128 v[212:215], v66 offset:18432
	ds_read_b128 v[216:219], v67 offset:55296
	ds_read_b128 v[220:223], v66 offset:18464
	ds_read_b128 v[224:227], v67 offset:55328
	ds_read_b128 v[228:231], v67 offset:59904
	ds_read_b128 v[232:235], v67 offset:59936
	s_waitcnt lgkmcnt(4)
	v_mfma_f32_32x32x16_bf16 v[2:17], v[212:215], v[216:219], v[2:17]
	s_waitcnt lgkmcnt(1)
	v_mfma_f32_32x32x16_bf16 v[18:33], v[212:215], v[228:231], v[18:33]
	ds_read_b128 v[212:215], v66 offset:23040
	ds_read_b128 v[236:239], v66 offset:23072
	s_waitcnt lgkmcnt(1)
	v_mfma_f32_32x32x16_bf16 v[34:49], v[212:215], v[216:219], v[34:49]
	v_mfma_f32_32x32x16_bf16 v[50:65], v[212:215], v[228:231], v[50:65]
	v_mfma_f32_32x32x16_bf16 v[2:17], v[220:223], v[224:227], v[2:17]
	v_mfma_f32_32x32x16_bf16 v[18:33], v[220:223], v[232:235], v[18:33]
	s_waitcnt lgkmcnt(0)
	v_mfma_f32_32x32x16_bf16 v[34:49], v[236:239], v[224:227], v[34:49]
	ds_read_b128 v[212:215], v66 offset:18496
	ds_read_b128 v[216:219], v67 offset:55360
	ds_read_b128 v[220:223], v66 offset:18528
	ds_read_b128 v[224:227], v67 offset:55392
	v_mfma_f32_32x32x16_bf16 v[50:65], v[236:239], v[232:235], v[50:65]
	ds_read_b128 v[228:231], v67 offset:59968
	ds_read_b128 v[232:235], v67 offset:60000
	s_waitcnt lgkmcnt(4)
	v_mfma_f32_32x32x16_bf16 v[2:17], v[212:215], v[216:219], v[2:17]
	s_waitcnt lgkmcnt(1)
	v_mfma_f32_32x32x16_bf16 v[18:33], v[212:215], v[228:231], v[18:33]
	ds_read_b128 v[212:215], v66 offset:23104
	ds_read_b128 v[236:239], v66 offset:23136
	s_waitcnt vmcnt(13)
	ds_write_b128 v1, v[188:191]
	ds_write_b128 v1, v[180:183] offset:4608
	ds_write_b128 v1, v[184:187] offset:9216
	s_waitcnt vmcnt(11)
	ds_write_b128 v1, v[196:199] offset:13824
	ds_write_b128 v1, v[192:195] offset:36864
	s_waitcnt vmcnt(10)
	ds_write_b128 v1, v[200:203] offset:41472
	s_waitcnt vmcnt(9)
	ds_write_b128 v1, v[204:207] offset:46080
	s_waitcnt vmcnt(8)
	ds_write_b128 v1, v[208:211] offset:50688
	global_load_dwordx4 v[180:183], v[80:81], off offset:1792
	global_load_dwordx4 v[184:187], v[82:83], off offset:1792
	global_load_dwordx4 v[188:191], v[78:79], off offset:1792
	global_load_dwordx4 v[192:195], v[76:77], off offset:1792
	global_load_dwordx4 v[196:199], v[90:91], off offset:1792
	global_load_dwordx4 v[200:203], v[84:85], off offset:1792
	global_load_dwordx4 v[204:207], v[86:87], off offset:1792
	global_load_dwordx4 v[208:211], v[88:89], off offset:1792
	s_waitcnt lgkmcnt(0)
	s_barrier
	v_mfma_f32_32x32x16_bf16 v[34:49], v[212:215], v[216:219], v[34:49]
	v_mfma_f32_32x32x16_bf16 v[50:65], v[212:215], v[228:231], v[50:65]
	v_mfma_f32_32x32x16_bf16 v[2:17], v[220:223], v[224:227], v[2:17]
	v_mfma_f32_32x32x16_bf16 v[18:33], v[220:223], v[232:235], v[18:33]
	v_mfma_f32_32x32x16_bf16 v[34:49], v[236:239], v[224:227], v[34:49]
	v_mfma_f32_32x32x16_bf16 v[50:65], v[236:239], v[232:235], v[50:65]
	ds_read_b128 v[212:215], v66
	ds_read_b128 v[216:219], v67 offset:36864
	ds_read_b128 v[220:223], v66 offset:32
	ds_read_b128 v[224:227], v67 offset:36896
	ds_read_b128 v[228:231], v67 offset:41472
	ds_read_b128 v[232:235], v67 offset:41504
	s_waitcnt lgkmcnt(4)
	v_mfma_f32_32x32x16_bf16 v[2:17], v[212:215], v[216:219], v[2:17]
	s_waitcnt lgkmcnt(1)
	v_mfma_f32_32x32x16_bf16 v[18:33], v[212:215], v[228:231], v[18:33]
	ds_read_b128 v[212:215], v66 offset:4608
	ds_read_b128 v[236:239], v66 offset:4640
	s_waitcnt lgkmcnt(1)
	v_mfma_f32_32x32x16_bf16 v[34:49], v[212:215], v[216:219], v[34:49]
	v_mfma_f32_32x32x16_bf16 v[50:65], v[212:215], v[228:231], v[50:65]
	v_mfma_f32_32x32x16_bf16 v[2:17], v[220:223], v[224:227], v[2:17]
	v_mfma_f32_32x32x16_bf16 v[18:33], v[220:223], v[232:235], v[18:33]
	s_waitcnt lgkmcnt(0)
	v_mfma_f32_32x32x16_bf16 v[34:49], v[236:239], v[224:227], v[34:49]
	ds_read_b128 v[212:215], v66 offset:64
	ds_read_b128 v[216:219], v67 offset:36928
	ds_read_b128 v[220:223], v66 offset:96
	ds_read_b128 v[224:227], v67 offset:36960
	v_mfma_f32_32x32x16_bf16 v[50:65], v[236:239], v[232:235], v[50:65]
	ds_read_b128 v[228:231], v67 offset:41536
	ds_read_b128 v[232:235], v67 offset:41568
	s_waitcnt lgkmcnt(4)
	v_mfma_f32_32x32x16_bf16 v[2:17], v[212:215], v[216:219], v[2:17]
	s_waitcnt lgkmcnt(1)
	v_mfma_f32_32x32x16_bf16 v[18:33], v[212:215], v[228:231], v[18:33]
	ds_read_b128 v[212:215], v66 offset:4672
	ds_read_b128 v[236:239], v66 offset:4704
	s_waitcnt vmcnt(13)
	ds_write_b128 v1, v[156:159] offset:18432
	ds_write_b128 v1, v[148:151] offset:23040
	ds_write_b128 v1, v[152:155] offset:27648
	s_waitcnt vmcnt(11)
	ds_write_b128 v1, v[164:167] offset:32256
	ds_write_b128 v1, v[160:163] offset:55296
	s_waitcnt vmcnt(10)
	ds_write_b128 v1, v[168:171] offset:59904
	s_waitcnt vmcnt(9)
	ds_write_b128 v1, v[172:175] offset:64512
	s_waitcnt vmcnt(8)
	ds_write_b128 v92, v[176:179] offset:32256
	s_waitcnt lgkmcnt(0)
	s_barrier
	global_load_dwordx4 v[148:151], v[80:81], off offset:1920
	s_nop 0
	global_load_dwordx4 v[80:83], v[82:83], off offset:1920
	s_nop 0
	global_load_dwordx4 v[152:155], v[78:79], off offset:1920
	s_nop 0
	global_load_dwordx4 v[76:79], v[76:77], off offset:1920
	s_nop 0
	global_load_dwordx4 v[156:159], v[90:91], off offset:1920
	global_load_dwordx4 v[160:163], v[84:85], off offset:1920
	s_nop 0
	global_load_dwordx4 v[84:87], v[86:87], off offset:1920
	s_nop 0
	global_load_dwordx4 v[88:91], v[88:89], off offset:1920
	v_mfma_f32_32x32x16_bf16 v[34:49], v[212:215], v[216:219], v[34:49]
	v_mfma_f32_32x32x16_bf16 v[50:65], v[212:215], v[228:231], v[50:65]
	v_mfma_f32_32x32x16_bf16 v[2:17], v[220:223], v[224:227], v[2:17]
	v_mfma_f32_32x32x16_bf16 v[18:33], v[220:223], v[232:235], v[18:33]
	v_mfma_f32_32x32x16_bf16 v[34:49], v[236:239], v[224:227], v[34:49]
	v_mfma_f32_32x32x16_bf16 v[50:65], v[236:239], v[232:235], v[50:65]
	ds_read_b128 v[164:167], v66 offset:18432
	ds_read_b128 v[168:171], v67 offset:55296
	ds_read_b128 v[172:175], v66 offset:18464
	ds_read_b128 v[176:179], v67 offset:55328
	ds_read_b128 v[212:215], v67 offset:59904
	ds_read_b128 v[216:219], v67 offset:59936
	s_waitcnt lgkmcnt(4)
	v_mfma_f32_32x32x16_bf16 v[2:17], v[164:167], v[168:171], v[2:17]
	s_waitcnt lgkmcnt(1)
	v_mfma_f32_32x32x16_bf16 v[18:33], v[164:167], v[212:215], v[18:33]
	ds_read_b128 v[164:167], v66 offset:23040
	ds_read_b128 v[220:223], v66 offset:23072
	s_waitcnt lgkmcnt(1)
	v_mfma_f32_32x32x16_bf16 v[34:49], v[164:167], v[168:171], v[34:49]
	v_mfma_f32_32x32x16_bf16 v[50:65], v[164:167], v[212:215], v[50:65]
	v_mfma_f32_32x32x16_bf16 v[2:17], v[172:175], v[176:179], v[2:17]
	v_mfma_f32_32x32x16_bf16 v[18:33], v[172:175], v[216:219], v[18:33]
	s_waitcnt lgkmcnt(0)
	v_mfma_f32_32x32x16_bf16 v[34:49], v[220:223], v[176:179], v[34:49]
	ds_read_b128 v[164:167], v66 offset:18496
	ds_read_b128 v[168:171], v67 offset:55360
	ds_read_b128 v[172:175], v66 offset:18528
	ds_read_b128 v[176:179], v67 offset:55392
	v_mfma_f32_32x32x16_bf16 v[50:65], v[220:223], v[216:219], v[50:65]
	ds_read_b128 v[212:215], v67 offset:59968
	ds_read_b128 v[216:219], v67 offset:60000
	s_waitcnt lgkmcnt(4)
	v_mfma_f32_32x32x16_bf16 v[2:17], v[164:167], v[168:171], v[2:17]
	s_waitcnt lgkmcnt(1)
	v_mfma_f32_32x32x16_bf16 v[18:33], v[164:167], v[212:215], v[18:33]
	ds_read_b128 v[164:167], v66 offset:23104
	ds_read_b128 v[220:223], v66 offset:23136
	s_waitcnt vmcnt(13)
	ds_write_b128 v1, v[188:191]
	ds_write_b128 v1, v[180:183] offset:4608
	ds_write_b128 v1, v[184:187] offset:9216
	s_waitcnt vmcnt(11)
	ds_write_b128 v1, v[196:199] offset:13824
	ds_write_b128 v1, v[192:195] offset:36864
	s_waitcnt vmcnt(10)
	ds_write_b128 v1, v[200:203] offset:41472
	s_waitcnt vmcnt(9)
	ds_write_b128 v1, v[204:207] offset:46080
	s_waitcnt vmcnt(8)
	ds_write_b128 v1, v[208:211] offset:50688
	s_waitcnt lgkmcnt(0)
	s_barrier
	v_mfma_f32_32x32x16_bf16 v[34:49], v[164:167], v[168:171], v[34:49]
	v_mfma_f32_32x32x16_bf16 v[50:65], v[164:167], v[212:215], v[50:65]
	v_mfma_f32_32x32x16_bf16 v[2:17], v[172:175], v[176:179], v[2:17]
	v_mfma_f32_32x32x16_bf16 v[18:33], v[172:175], v[216:219], v[18:33]
	v_mfma_f32_32x32x16_bf16 v[34:49], v[220:223], v[176:179], v[34:49]
	v_mfma_f32_32x32x16_bf16 v[50:65], v[220:223], v[216:219], v[50:65]
	ds_read_b128 v[164:167], v66
	ds_read_b128 v[168:171], v67 offset:36864
	ds_read_b128 v[172:175], v66 offset:32
	ds_read_b128 v[176:179], v67 offset:36896
	ds_read_b128 v[180:183], v67 offset:41472
	ds_read_b128 v[184:187], v67 offset:41504
	s_waitcnt lgkmcnt(4)
	v_mfma_f32_32x32x16_bf16 v[2:17], v[164:167], v[168:171], v[2:17]
	s_waitcnt lgkmcnt(1)
	v_mfma_f32_32x32x16_bf16 v[18:33], v[164:167], v[180:183], v[18:33]
	ds_read_b128 v[164:167], v66 offset:4608
	ds_read_b128 v[188:191], v66 offset:4640
	s_waitcnt lgkmcnt(1)
	v_mfma_f32_32x32x16_bf16 v[34:49], v[164:167], v[168:171], v[34:49]
	v_mfma_f32_32x32x16_bf16 v[50:65], v[164:167], v[180:183], v[50:65]
	v_mfma_f32_32x32x16_bf16 v[2:17], v[172:175], v[176:179], v[2:17]
	v_mfma_f32_32x32x16_bf16 v[18:33], v[172:175], v[184:187], v[18:33]
	s_waitcnt lgkmcnt(0)
	v_mfma_f32_32x32x16_bf16 v[34:49], v[188:191], v[176:179], v[34:49]
	ds_read_b128 v[164:167], v66 offset:64
	ds_read_b128 v[168:171], v67 offset:36928
	ds_read_b128 v[172:175], v66 offset:96
	ds_read_b128 v[176:179], v67 offset:36960
	v_mfma_f32_32x32x16_bf16 v[50:65], v[188:191], v[184:187], v[50:65]
	ds_read_b128 v[180:183], v67 offset:41536
	ds_read_b128 v[184:187], v67 offset:41568
	s_waitcnt lgkmcnt(4)
	v_mfma_f32_32x32x16_bf16 v[2:17], v[164:167], v[168:171], v[2:17]
	s_waitcnt lgkmcnt(1)
	v_mfma_f32_32x32x16_bf16 v[18:33], v[164:167], v[180:183], v[18:33]
	ds_read_b128 v[164:167], v66 offset:4672
	ds_read_b128 v[188:191], v66 offset:4704
	s_waitcnt vmcnt(5)
	ds_write_b128 v1, v[152:155] offset:18432
	ds_write_b128 v1, v[148:151] offset:23040
	ds_write_b128 v1, v[80:83] offset:27648
	s_waitcnt vmcnt(3)
	ds_write_b128 v1, v[156:159] offset:32256
	ds_write_b128 v1, v[76:79] offset:55296
	s_waitcnt vmcnt(2)
	ds_write_b128 v1, v[160:163] offset:59904
	s_waitcnt vmcnt(1)
	ds_write_b128 v1, v[84:87] offset:64512
	s_waitcnt vmcnt(0)
	ds_write_b128 v92, v[88:91] offset:32256
	s_waitcnt lgkmcnt(0)
	s_barrier
	v_mfma_f32_32x32x16_bf16 v[34:49], v[164:167], v[168:171], v[34:49]
	v_mfma_f32_32x32x16_bf16 v[50:65], v[164:167], v[180:183], v[50:65]
	v_mfma_f32_32x32x16_bf16 v[2:17], v[172:175], v[176:179], v[2:17]
	v_mfma_f32_32x32x16_bf16 v[18:33], v[172:175], v[184:187], v[18:33]
	v_mfma_f32_32x32x16_bf16 v[34:49], v[188:191], v[176:179], v[34:49]
	v_mfma_f32_32x32x16_bf16 v[50:65], v[188:191], v[184:187], v[50:65]
	ds_read_b128 v[76:79], v66 offset:18432
	ds_read_b128 v[80:83], v67 offset:55296
	ds_read_b128 v[84:87], v66 offset:18464
	ds_read_b128 v[88:91], v67 offset:55328
	ds_read_b128 v[148:151], v67 offset:59904
	ds_read_b128 v[152:155], v67 offset:59936
	v_or_b32_e32 v68, s8, v94
	s_waitcnt lgkmcnt(4)
	v_mfma_f32_32x32x16_bf16 v[2:17], v[76:79], v[80:83], v[2:17]
	s_lshl_b32 s10, s10, 1
	s_mov_b32 s11, s9
	s_add_i32 s12, s12, s13
	s_add_i32 s14, s14, s15
	s_add_i32 s16, s16, s17
	s_cmpk_lt_u32 s12, 0x400
	s_waitcnt lgkmcnt(1)
	v_mfma_f32_32x32x16_bf16 v[18:33], v[76:79], v[148:151], v[18:33]
	ds_read_b128 v[76:79], v66 offset:23040
	ds_read_b128 v[156:159], v66 offset:23072
	s_waitcnt lgkmcnt(1)
	v_mfma_f32_32x32x16_bf16 v[34:49], v[76:79], v[80:83], v[34:49]
	v_mfma_f32_32x32x16_bf16 v[50:65], v[76:79], v[148:151], v[50:65]
	v_mfma_f32_32x32x16_bf16 v[2:17], v[84:87], v[88:91], v[2:17]
	v_mfma_f32_32x32x16_bf16 v[18:33], v[84:87], v[152:155], v[18:33]
	s_waitcnt lgkmcnt(0)
	v_mfma_f32_32x32x16_bf16 v[34:49], v[156:159], v[88:91], v[34:49]
	ds_read_b128 v[76:79], v66 offset:18496
	ds_read_b128 v[80:83], v67 offset:55360
	ds_read_b128 v[84:87], v66 offset:18528
	ds_read_b128 v[88:91], v67 offset:55392
	v_mfma_f32_32x32x16_bf16 v[50:65], v[156:159], v[152:155], v[50:65]
	ds_read_b128 v[148:151], v67 offset:59968
	ds_read_b128 v[152:155], v67 offset:60000
	s_waitcnt lgkmcnt(4)
	v_mfma_f32_32x32x16_bf16 v[2:17], v[76:79], v[80:83], v[2:17]
	s_waitcnt lgkmcnt(1)
	v_mfma_f32_32x32x16_bf16 v[18:33], v[76:79], v[148:151], v[18:33]
	ds_read_b128 v[76:79], v66 offset:23104
	ds_read_b128 v[156:159], v66 offset:23136
	s_waitcnt lgkmcnt(0)
	s_barrier
	v_mfma_f32_32x32x16_bf16 v[34:49], v[76:79], v[80:83], v[34:49]
	v_mfma_f32_32x32x16_bf16 v[50:65], v[76:79], v[148:151], v[50:65]
	v_mfma_f32_32x32x16_bf16 v[2:17], v[84:87], v[88:91], v[2:17]
	v_mfma_f32_32x32x16_bf16 v[18:33], v[84:87], v[152:155], v[18:33]
	v_mfma_f32_32x32x16_bf16 v[34:49], v[156:159], v[88:91], v[34:49]
	s_nop 10
	ds_write2_b32 v93, v2, v18 offset1:32
	v_mfma_f32_32x32x16_bf16 v[50:65], v[156:159], v[152:155], v[50:65]
	s_nop 11
	ds_write2_b32 v132, v34, v50 offset0:32 offset1:64
	ds_write2_b32 v93, v3, v19 offset0:129 offset1:161
	ds_write2_b32 v132, v35, v51 offset0:161 offset1:193
	ds_write2_b32 v133, v4, v20 offset0:2 offset1:34
	ds_write2_b32 v134, v36, v52 offset0:34 offset1:66
	ds_write2_b32 v133, v5, v21 offset0:131 offset1:163
	ds_write2_b32 v134, v37, v53 offset0:163 offset1:195
	ds_write2_b32 v135, v6, v22 offset0:8 offset1:40
	ds_write2_b32 v136, v38, v54 offset0:40 offset1:72
	ds_write2_b32 v135, v7, v23 offset0:137 offset1:169
	ds_write2_b32 v136, v39, v55 offset0:169 offset1:201
	ds_write2_b32 v137, v8, v24 offset0:10 offset1:42
	ds_write2_b32 v138, v40, v56 offset0:42 offset1:74
	ds_write2_b32 v137, v9, v25 offset0:139 offset1:171
	ds_write2_b32 v138, v41, v57 offset0:171 offset1:203
	ds_write2_b32 v139, v10, v26 offset0:16 offset1:48
	ds_write2_b32 v140, v42, v58 offset0:48 offset1:80
	ds_write2_b32 v139, v11, v27 offset0:145 offset1:177
	ds_write2_b32 v140, v43, v59 offset0:177 offset1:209
	ds_write2_b32 v141, v12, v28 offset0:18 offset1:50
	ds_write2_b32 v142, v44, v60 offset0:50 offset1:82
	ds_write2_b32 v141, v13, v29 offset0:147 offset1:179
	ds_write2_b32 v142, v45, v61 offset0:179 offset1:211
	ds_write2_b32 v143, v14, v30 offset0:24 offset1:56
	ds_write2_b32 v144, v46, v62 offset0:56 offset1:88
	ds_write2_b32 v143, v15, v31 offset0:153 offset1:185
	ds_write2_b32 v144, v47, v63 offset0:185 offset1:217
	ds_write2_b32 v145, v16, v32 offset0:26 offset1:58
	ds_write2_b32 v146, v48, v64 offset0:58 offset1:90
	ds_write2_b32 v145, v17, v33 offset0:155 offset1:187
	ds_write2_b32 v146, v49, v65 offset0:187 offset1:219
	v_lshl_add_u64 v[2:3], v[68:69], 2, s[6:7]
	s_waitcnt lgkmcnt(0)
	s_barrier
	v_mov_b32_e32 v2, v68
	v_lshlrev_b32_e32 v3, 2, v2
	global_load_dword v5, v3, s[6:7]
	global_load_dword v6, v3, s[6:7] offset:64
	global_load_dword v7, v3, s[6:7] offset:128
	global_load_dword v8, v3, s[6:7] offset:192
	global_load_dword v9, v3, s[6:7] offset:256
	global_load_dword v10, v3, s[6:7] offset:320
	global_load_dword v11, v3, s[6:7] offset:384
	global_load_dword v12, v3, s[6:7] offset:448
	v_lshlrev_b32_e32 v4, 13, v2
	v_add3_u32 v4, v4, v74, s10
	s_movk_i32 s24, 0x7fff
	v_mov_b32_e32 v59, 1
	v_mov_b32_e32 v13, 0x358637bd
	ds_read2_b32 v[14:15], v103 offset0:0 offset1:1
	ds_read2_b32 v[16:17], v103 offset0:2 offset1:3
	ds_read2_b32 v[18:19], v103 offset0:4 offset1:5
	ds_read2_b32 v[20:21], v103 offset0:6 offset1:7
	v_add_u32_e32 v56, 0x2040, v103
	ds_read2_b32 v[22:23], v56 offset0:0 offset1:1
	ds_read2_b32 v[24:25], v56 offset0:2 offset1:3
	ds_read2_b32 v[26:27], v56 offset0:4 offset1:5
	ds_read2_b32 v[28:29], v56 offset0:6 offset1:7
	s_waitcnt vmcnt(7) lgkmcnt(4)
	v_fmamk_f32 v54, v5, 0x3a800000, v13
	v_rsq_f32_e32 v54, v54
	s_nop 0
	v_mul_f32_e32 v14, v14, v54
	v_mul_f32_e32 v15, v15, v54
	v_mul_f32_e32 v16, v16, v54
	v_mul_f32_e32 v17, v17, v54
	v_mul_f32_e32 v18, v18, v54
	v_mul_f32_e32 v19, v19, v54
	v_mul_f32_e32 v20, v20, v54
	v_mul_f32_e32 v21, v21, v54
	v_max_f32_e32 v14, 0, v14
	v_max_f32_e32 v15, 0, v15
	v_max_f32_e32 v16, 0, v16
	v_max_f32_e32 v17, 0, v17
	v_max_f32_e32 v18, 0, v18
	v_max_f32_e32 v19, 0, v19
	v_max_f32_e32 v20, 0, v20
	v_max_f32_e32 v21, 0, v21
	v_pk_mul_f32 v[14:15], v[14:15], v[14:15]
	v_pk_mul_f32 v[16:17], v[16:17], v[16:17]
	v_pk_mul_f32 v[18:19], v[18:19], v[18:19]
	v_pk_mul_f32 v[20:21], v[20:21], v[20:21]
	v_and_b32_sdwa v46, v14, v59 dst_sel:DWORD dst_unused:UNUSED_PAD src0_sel:WORD_1 src1_sel:DWORD
	v_and_b32_sdwa v47, v15, v59 dst_sel:DWORD dst_unused:UNUSED_PAD src0_sel:WORD_1 src1_sel:DWORD
	v_and_b32_sdwa v48, v16, v59 dst_sel:DWORD dst_unused:UNUSED_PAD src0_sel:WORD_1 src1_sel:DWORD
	v_and_b32_sdwa v49, v17, v59 dst_sel:DWORD dst_unused:UNUSED_PAD src0_sel:WORD_1 src1_sel:DWORD
	v_and_b32_sdwa v50, v18, v59 dst_sel:DWORD dst_unused:UNUSED_PAD src0_sel:WORD_1 src1_sel:DWORD
	v_and_b32_sdwa v51, v19, v59 dst_sel:DWORD dst_unused:UNUSED_PAD src0_sel:WORD_1 src1_sel:DWORD
	v_and_b32_sdwa v52, v20, v59 dst_sel:DWORD dst_unused:UNUSED_PAD src0_sel:WORD_1 src1_sel:DWORD
	v_and_b32_sdwa v53, v21, v59 dst_sel:DWORD dst_unused:UNUSED_PAD src0_sel:WORD_1 src1_sel:DWORD
	v_add3_u32 v14, v14, v46, s24
	v_add3_u32 v15, v15, v47, s24
	v_add3_u32 v16, v16, v48, s24
	v_add3_u32 v17, v17, v49, s24
	v_add3_u32 v18, v18, v50, s24
	v_add3_u32 v19, v19, v51, s24
	v_add3_u32 v20, v20, v52, s24
	v_add3_u32 v21, v21, v53, s24
	v_and_b32_e32 v15, 0xffff0000, v15
	v_and_b32_e32 v17, 0xffff0000, v17
	v_and_b32_e32 v19, 0xffff0000, v19
	v_and_b32_e32 v21, 0xffff0000, v21
	v_or_b32_sdwa v60, v15, v14 dst_sel:DWORD dst_unused:UNUSED_PAD src0_sel:DWORD src1_sel:WORD_1
	v_or_b32_sdwa v61, v17, v16 dst_sel:DWORD dst_unused:UNUSED_PAD src0_sel:DWORD src1_sel:WORD_1
	v_or_b32_sdwa v62, v19, v18 dst_sel:DWORD dst_unused:UNUSED_PAD src0_sel:DWORD src1_sel:WORD_1
	v_or_b32_sdwa v63, v21, v20 dst_sel:DWORD dst_unused:UNUSED_PAD src0_sel:DWORD src1_sel:WORD_1
	global_store_dwordx4 v4, v[60:63], s[56:57] nt
	v_add_u32_e32 v55, 0x4080, v103
	ds_read2_b32 v[30:31], v55 offset0:0 offset1:1
	ds_read2_b32 v[32:33], v55 offset0:2 offset1:3
	ds_read2_b32 v[34:35], v55 offset0:4 offset1:5
	ds_read2_b32 v[36:37], v55 offset0:6 offset1:7
	v_add_u32_e32 v56, 0x60c0, v103
	ds_read2_b32 v[38:39], v56 offset0:0 offset1:1
	ds_read2_b32 v[40:41], v56 offset0:2 offset1:3
	ds_read2_b32 v[42:43], v56 offset0:4 offset1:5
	ds_read2_b32 v[44:45], v56 offset0:6 offset1:7
	s_waitcnt vmcnt(7) lgkmcnt(8)
	v_fmamk_f32 v54, v6, 0x3a800000, v13
	v_rsq_f32_e32 v54, v54
	v_add_u32_e32 v58, 0x20000, v4
	v_mul_f32_e32 v22, v22, v54
	v_mul_f32_e32 v23, v23, v54
	v_mul_f32_e32 v24, v24, v54
	v_mul_f32_e32 v25, v25, v54
	v_mul_f32_e32 v26, v26, v54
	v_mul_f32_e32 v27, v27, v54
	v_mul_f32_e32 v28, v28, v54
	v_mul_f32_e32 v29, v29, v54
	v_max_f32_e32 v22, 0, v22
	v_max_f32_e32 v23, 0, v23
	v_max_f32_e32 v24, 0, v24
	v_max_f32_e32 v25, 0, v25
	v_max_f32_e32 v26, 0, v26
	v_max_f32_e32 v27, 0, v27
	v_max_f32_e32 v28, 0, v28
	v_max_f32_e32 v29, 0, v29
	v_pk_mul_f32 v[22:23], v[22:23], v[22:23]
	v_pk_mul_f32 v[24:25], v[24:25], v[24:25]
	v_pk_mul_f32 v[26:27], v[26:27], v[26:27]
	v_pk_mul_f32 v[28:29], v[28:29], v[28:29]
	v_and_b32_sdwa v46, v22, v59 dst_sel:DWORD dst_unused:UNUSED_PAD src0_sel:WORD_1 src1_sel:DWORD
	v_and_b32_sdwa v47, v23, v59 dst_sel:DWORD dst_unused:UNUSED_PAD src0_sel:WORD_1 src1_sel:DWORD
	v_and_b32_sdwa v48, v24, v59 dst_sel:DWORD dst_unused:UNUSED_PAD src0_sel:WORD_1 src1_sel:DWORD
	v_and_b32_sdwa v49, v25, v59 dst_sel:DWORD dst_unused:UNUSED_PAD src0_sel:WORD_1 src1_sel:DWORD
	v_and_b32_sdwa v50, v26, v59 dst_sel:DWORD dst_unused:UNUSED_PAD src0_sel:WORD_1 src1_sel:DWORD
	v_and_b32_sdwa v51, v27, v59 dst_sel:DWORD dst_unused:UNUSED_PAD src0_sel:WORD_1 src1_sel:DWORD
	v_and_b32_sdwa v52, v28, v59 dst_sel:DWORD dst_unused:UNUSED_PAD src0_sel:WORD_1 src1_sel:DWORD
	v_and_b32_sdwa v53, v29, v59 dst_sel:DWORD dst_unused:UNUSED_PAD src0_sel:WORD_1 src1_sel:DWORD
	v_add3_u32 v22, v22, v46, s24
	v_add3_u32 v23, v23, v47, s24
	v_add3_u32 v24, v24, v48, s24
	v_add3_u32 v25, v25, v49, s24
	v_add3_u32 v26, v26, v50, s24
	v_add3_u32 v27, v27, v51, s24
	v_add3_u32 v28, v28, v52, s24
	v_add3_u32 v29, v29, v53, s24
	v_and_b32_e32 v23, 0xffff0000, v23
	v_and_b32_e32 v25, 0xffff0000, v25
	v_and_b32_e32 v27, 0xffff0000, v27
	v_and_b32_e32 v29, 0xffff0000, v29
	v_or_b32_sdwa v76, v23, v22 dst_sel:DWORD dst_unused:UNUSED_PAD src0_sel:DWORD src1_sel:WORD_1
	v_or_b32_sdwa v77, v25, v24 dst_sel:DWORD dst_unused:UNUSED_PAD src0_sel:DWORD src1_sel:WORD_1
	v_or_b32_sdwa v78, v27, v26 dst_sel:DWORD dst_unused:UNUSED_PAD src0_sel:DWORD src1_sel:WORD_1
	v_or_b32_sdwa v79, v29, v28 dst_sel:DWORD dst_unused:UNUSED_PAD src0_sel:DWORD src1_sel:WORD_1
	global_store_dwordx4 v58, v[76:79], s[56:57] nt
	s_waitcnt vmcnt(7) lgkmcnt(4)
	v_fmamk_f32 v54, v7, 0x3a800000, v13
	v_rsq_f32_e32 v54, v54
	v_add_u32_e32 v57, 0x40000, v4
	v_mul_f32_e32 v30, v30, v54
	v_mul_f32_e32 v31, v31, v54
	v_mul_f32_e32 v32, v32, v54
	v_mul_f32_e32 v33, v33, v54
	v_mul_f32_e32 v34, v34, v54
	v_mul_f32_e32 v35, v35, v54
	v_mul_f32_e32 v36, v36, v54
	v_mul_f32_e32 v37, v37, v54
	v_max_f32_e32 v30, 0, v30
	v_max_f32_e32 v31, 0, v31
	v_max_f32_e32 v32, 0, v32
	v_max_f32_e32 v33, 0, v33
	v_max_f32_e32 v34, 0, v34
	v_max_f32_e32 v35, 0, v35
	v_max_f32_e32 v36, 0, v36
	v_max_f32_e32 v37, 0, v37
	v_pk_mul_f32 v[30:31], v[30:31], v[30:31]
	v_pk_mul_f32 v[32:33], v[32:33], v[32:33]
	v_pk_mul_f32 v[34:35], v[34:35], v[34:35]
	v_pk_mul_f32 v[36:37], v[36:37], v[36:37]
	v_and_b32_sdwa v46, v30, v59 dst_sel:DWORD dst_unused:UNUSED_PAD src0_sel:WORD_1 src1_sel:DWORD
	v_and_b32_sdwa v47, v31, v59 dst_sel:DWORD dst_unused:UNUSED_PAD src0_sel:WORD_1 src1_sel:DWORD
	v_and_b32_sdwa v48, v32, v59 dst_sel:DWORD dst_unused:UNUSED_PAD src0_sel:WORD_1 src1_sel:DWORD
	v_and_b32_sdwa v49, v33, v59 dst_sel:DWORD dst_unused:UNUSED_PAD src0_sel:WORD_1 src1_sel:DWORD
	v_and_b32_sdwa v50, v34, v59 dst_sel:DWORD dst_unused:UNUSED_PAD src0_sel:WORD_1 src1_sel:DWORD
	v_and_b32_sdwa v51, v35, v59 dst_sel:DWORD dst_unused:UNUSED_PAD src0_sel:WORD_1 src1_sel:DWORD
	v_and_b32_sdwa v52, v36, v59 dst_sel:DWORD dst_unused:UNUSED_PAD src0_sel:WORD_1 src1_sel:DWORD
	v_and_b32_sdwa v53, v37, v59 dst_sel:DWORD dst_unused:UNUSED_PAD src0_sel:WORD_1 src1_sel:DWORD
	v_add3_u32 v30, v30, v46, s24
	v_add3_u32 v31, v31, v47, s24
	v_add3_u32 v32, v32, v48, s24
	v_add3_u32 v33, v33, v49, s24
	v_add3_u32 v34, v34, v50, s24
	v_add3_u32 v35, v35, v51, s24
	v_add3_u32 v36, v36, v52, s24
	v_add3_u32 v37, v37, v53, s24
	v_and_b32_e32 v31, 0xffff0000, v31
	v_and_b32_e32 v33, 0xffff0000, v33
	v_and_b32_e32 v35, 0xffff0000, v35
	v_and_b32_e32 v37, 0xffff0000, v37
	v_or_b32_sdwa v60, v31, v30 dst_sel:DWORD dst_unused:UNUSED_PAD src0_sel:DWORD src1_sel:WORD_1
	v_or_b32_sdwa v61, v33, v32 dst_sel:DWORD dst_unused:UNUSED_PAD src0_sel:DWORD src1_sel:WORD_1
	v_or_b32_sdwa v62, v35, v34 dst_sel:DWORD dst_unused:UNUSED_PAD src0_sel:DWORD src1_sel:WORD_1
	v_or_b32_sdwa v63, v37, v36 dst_sel:DWORD dst_unused:UNUSED_PAD src0_sel:DWORD src1_sel:WORD_1
	global_store_dwordx4 v57, v[60:63], s[56:57] nt
	v_add_u32_e32 v55, 0x8100, v103
	ds_read2_b32 v[14:15], v55 offset0:0 offset1:1
	ds_read2_b32 v[16:17], v55 offset0:2 offset1:3
	ds_read2_b32 v[18:19], v55 offset0:4 offset1:5
	ds_read2_b32 v[20:21], v55 offset0:6 offset1:7
	v_add_u32_e32 v56, 0xa140, v103
	ds_read2_b32 v[22:23], v56 offset0:0 offset1:1
	ds_read2_b32 v[24:25], v56 offset0:2 offset1:3
	ds_read2_b32 v[26:27], v56 offset0:4 offset1:5
	ds_read2_b32 v[28:29], v56 offset0:6 offset1:7
	s_waitcnt vmcnt(7) lgkmcnt(8)
	v_fmamk_f32 v54, v8, 0x3a800000, v13
	v_rsq_f32_e32 v54, v54
	v_add_u32_e32 v58, 0x60000, v4
	v_mul_f32_e32 v38, v38, v54
	v_mul_f32_e32 v39, v39, v54
	v_mul_f32_e32 v40, v40, v54
	v_mul_f32_e32 v41, v41, v54
	v_mul_f32_e32 v42, v42, v54
	v_mul_f32_e32 v43, v43, v54
	v_mul_f32_e32 v44, v44, v54
	v_mul_f32_e32 v45, v45, v54
	v_max_f32_e32 v38, 0, v38
	v_max_f32_e32 v39, 0, v39
	v_max_f32_e32 v40, 0, v40
	v_max_f32_e32 v41, 0, v41
	v_max_f32_e32 v42, 0, v42
	v_max_f32_e32 v43, 0, v43
	v_max_f32_e32 v44, 0, v44
	v_max_f32_e32 v45, 0, v45
	v_pk_mul_f32 v[38:39], v[38:39], v[38:39]
	v_pk_mul_f32 v[40:41], v[40:41], v[40:41]
	v_pk_mul_f32 v[42:43], v[42:43], v[42:43]
	v_pk_mul_f32 v[44:45], v[44:45], v[44:45]
	v_and_b32_sdwa v46, v38, v59 dst_sel:DWORD dst_unused:UNUSED_PAD src0_sel:WORD_1 src1_sel:DWORD
	v_and_b32_sdwa v47, v39, v59 dst_sel:DWORD dst_unused:UNUSED_PAD src0_sel:WORD_1 src1_sel:DWORD
	v_and_b32_sdwa v48, v40, v59 dst_sel:DWORD dst_unused:UNUSED_PAD src0_sel:WORD_1 src1_sel:DWORD
	v_and_b32_sdwa v49, v41, v59 dst_sel:DWORD dst_unused:UNUSED_PAD src0_sel:WORD_1 src1_sel:DWORD
	v_and_b32_sdwa v50, v42, v59 dst_sel:DWORD dst_unused:UNUSED_PAD src0_sel:WORD_1 src1_sel:DWORD
	v_and_b32_sdwa v51, v43, v59 dst_sel:DWORD dst_unused:UNUSED_PAD src0_sel:WORD_1 src1_sel:DWORD
	v_and_b32_sdwa v52, v44, v59 dst_sel:DWORD dst_unused:UNUSED_PAD src0_sel:WORD_1 src1_sel:DWORD
	v_and_b32_sdwa v53, v45, v59 dst_sel:DWORD dst_unused:UNUSED_PAD src0_sel:WORD_1 src1_sel:DWORD
	v_add3_u32 v38, v38, v46, s24
	v_add3_u32 v39, v39, v47, s24
	v_add3_u32 v40, v40, v48, s24
	v_add3_u32 v41, v41, v49, s24
	v_add3_u32 v42, v42, v50, s24
	v_add3_u32 v43, v43, v51, s24
	v_add3_u32 v44, v44, v52, s24
	v_add3_u32 v45, v45, v53, s24
	v_and_b32_e32 v39, 0xffff0000, v39
	v_and_b32_e32 v41, 0xffff0000, v41
	v_and_b32_e32 v43, 0xffff0000, v43
	v_and_b32_e32 v45, 0xffff0000, v45
	v_or_b32_sdwa v76, v39, v38 dst_sel:DWORD dst_unused:UNUSED_PAD src0_sel:DWORD src1_sel:WORD_1
	v_or_b32_sdwa v77, v41, v40 dst_sel:DWORD dst_unused:UNUSED_PAD src0_sel:DWORD src1_sel:WORD_1
	v_or_b32_sdwa v78, v43, v42 dst_sel:DWORD dst_unused:UNUSED_PAD src0_sel:DWORD src1_sel:WORD_1
	v_or_b32_sdwa v79, v45, v44 dst_sel:DWORD dst_unused:UNUSED_PAD src0_sel:DWORD src1_sel:WORD_1
	global_store_dwordx4 v58, v[76:79], s[56:57] nt
	s_waitcnt vmcnt(7) lgkmcnt(4)
	v_fmamk_f32 v54, v9, 0x3a800000, v13
	v_rsq_f32_e32 v54, v54
	v_add_u32_e32 v57, 0x80000, v4
	v_mul_f32_e32 v14, v14, v54
	v_mul_f32_e32 v15, v15, v54
	v_mul_f32_e32 v16, v16, v54
	v_mul_f32_e32 v17, v17, v54
	v_mul_f32_e32 v18, v18, v54
	v_mul_f32_e32 v19, v19, v54
	v_mul_f32_e32 v20, v20, v54
	v_mul_f32_e32 v21, v21, v54
	v_max_f32_e32 v14, 0, v14
	v_max_f32_e32 v15, 0, v15
	v_max_f32_e32 v16, 0, v16
	v_max_f32_e32 v17, 0, v17
	v_max_f32_e32 v18, 0, v18
	v_max_f32_e32 v19, 0, v19
	v_max_f32_e32 v20, 0, v20
	v_max_f32_e32 v21, 0, v21
	v_pk_mul_f32 v[14:15], v[14:15], v[14:15]
	v_pk_mul_f32 v[16:17], v[16:17], v[16:17]
	v_pk_mul_f32 v[18:19], v[18:19], v[18:19]
	v_pk_mul_f32 v[20:21], v[20:21], v[20:21]
	v_and_b32_sdwa v46, v14, v59 dst_sel:DWORD dst_unused:UNUSED_PAD src0_sel:WORD_1 src1_sel:DWORD
	v_and_b32_sdwa v47, v15, v59 dst_sel:DWORD dst_unused:UNUSED_PAD src0_sel:WORD_1 src1_sel:DWORD
	v_and_b32_sdwa v48, v16, v59 dst_sel:DWORD dst_unused:UNUSED_PAD src0_sel:WORD_1 src1_sel:DWORD
	v_and_b32_sdwa v49, v17, v59 dst_sel:DWORD dst_unused:UNUSED_PAD src0_sel:WORD_1 src1_sel:DWORD
	v_and_b32_sdwa v50, v18, v59 dst_sel:DWORD dst_unused:UNUSED_PAD src0_sel:WORD_1 src1_sel:DWORD
	v_and_b32_sdwa v51, v19, v59 dst_sel:DWORD dst_unused:UNUSED_PAD src0_sel:WORD_1 src1_sel:DWORD
	v_and_b32_sdwa v52, v20, v59 dst_sel:DWORD dst_unused:UNUSED_PAD src0_sel:WORD_1 src1_sel:DWORD
	v_and_b32_sdwa v53, v21, v59 dst_sel:DWORD dst_unused:UNUSED_PAD src0_sel:WORD_1 src1_sel:DWORD
	v_add3_u32 v14, v14, v46, s24
	v_add3_u32 v15, v15, v47, s24
	v_add3_u32 v16, v16, v48, s24
	v_add3_u32 v17, v17, v49, s24
	v_add3_u32 v18, v18, v50, s24
	v_add3_u32 v19, v19, v51, s24
	v_add3_u32 v20, v20, v52, s24
	v_add3_u32 v21, v21, v53, s24
	v_and_b32_e32 v15, 0xffff0000, v15
	v_and_b32_e32 v17, 0xffff0000, v17
	v_and_b32_e32 v19, 0xffff0000, v19
	v_and_b32_e32 v21, 0xffff0000, v21
	v_or_b32_sdwa v60, v15, v14 dst_sel:DWORD dst_unused:UNUSED_PAD src0_sel:DWORD src1_sel:WORD_1
	v_or_b32_sdwa v61, v17, v16 dst_sel:DWORD dst_unused:UNUSED_PAD src0_sel:DWORD src1_sel:WORD_1
	v_or_b32_sdwa v62, v19, v18 dst_sel:DWORD dst_unused:UNUSED_PAD src0_sel:DWORD src1_sel:WORD_1
	v_or_b32_sdwa v63, v21, v20 dst_sel:DWORD dst_unused:UNUSED_PAD src0_sel:DWORD src1_sel:WORD_1
	global_store_dwordx4 v57, v[60:63], s[56:57] nt
	v_add_u32_e32 v55, 0xc180, v103
	ds_read2_b32 v[30:31], v55 offset0:0 offset1:1
	ds_read2_b32 v[32:33], v55 offset0:2 offset1:3
	ds_read2_b32 v[34:35], v55 offset0:4 offset1:5
	ds_read2_b32 v[36:37], v55 offset0:6 offset1:7
	v_add_u32_e32 v56, 0xe1c0, v103
	ds_read2_b32 v[38:39], v56 offset0:0 offset1:1
	ds_read2_b32 v[40:41], v56 offset0:2 offset1:3
	ds_read2_b32 v[42:43], v56 offset0:4 offset1:5
	ds_read2_b32 v[44:45], v56 offset0:6 offset1:7
	s_waitcnt vmcnt(7) lgkmcnt(8)
	v_fmamk_f32 v54, v10, 0x3a800000, v13
	v_rsq_f32_e32 v54, v54
	v_add_u32_e32 v58, 0xa0000, v4
	v_mul_f32_e32 v22, v22, v54
	v_mul_f32_e32 v23, v23, v54
	v_mul_f32_e32 v24, v24, v54
	v_mul_f32_e32 v25, v25, v54
	v_mul_f32_e32 v26, v26, v54
	v_mul_f32_e32 v27, v27, v54
	v_mul_f32_e32 v28, v28, v54
	v_mul_f32_e32 v29, v29, v54
	v_max_f32_e32 v22, 0, v22
	v_max_f32_e32 v23, 0, v23
	v_max_f32_e32 v24, 0, v24
	v_max_f32_e32 v25, 0, v25
	v_max_f32_e32 v26, 0, v26
	v_max_f32_e32 v27, 0, v27
	v_max_f32_e32 v28, 0, v28
	v_max_f32_e32 v29, 0, v29
	v_pk_mul_f32 v[22:23], v[22:23], v[22:23]
	v_pk_mul_f32 v[24:25], v[24:25], v[24:25]
	v_pk_mul_f32 v[26:27], v[26:27], v[26:27]
	v_pk_mul_f32 v[28:29], v[28:29], v[28:29]
	v_and_b32_sdwa v46, v22, v59 dst_sel:DWORD dst_unused:UNUSED_PAD src0_sel:WORD_1 src1_sel:DWORD
	v_and_b32_sdwa v47, v23, v59 dst_sel:DWORD dst_unused:UNUSED_PAD src0_sel:WORD_1 src1_sel:DWORD
	v_and_b32_sdwa v48, v24, v59 dst_sel:DWORD dst_unused:UNUSED_PAD src0_sel:WORD_1 src1_sel:DWORD
	v_and_b32_sdwa v49, v25, v59 dst_sel:DWORD dst_unused:UNUSED_PAD src0_sel:WORD_1 src1_sel:DWORD
	v_and_b32_sdwa v50, v26, v59 dst_sel:DWORD dst_unused:UNUSED_PAD src0_sel:WORD_1 src1_sel:DWORD
	v_and_b32_sdwa v51, v27, v59 dst_sel:DWORD dst_unused:UNUSED_PAD src0_sel:WORD_1 src1_sel:DWORD
	v_and_b32_sdwa v52, v28, v59 dst_sel:DWORD dst_unused:UNUSED_PAD src0_sel:WORD_1 src1_sel:DWORD
	v_and_b32_sdwa v53, v29, v59 dst_sel:DWORD dst_unused:UNUSED_PAD src0_sel:WORD_1 src1_sel:DWORD
	v_add3_u32 v22, v22, v46, s24
	v_add3_u32 v23, v23, v47, s24
	v_add3_u32 v24, v24, v48, s24
	v_add3_u32 v25, v25, v49, s24
	v_add3_u32 v26, v26, v50, s24
	v_add3_u32 v27, v27, v51, s24
	v_add3_u32 v28, v28, v52, s24
	v_add3_u32 v29, v29, v53, s24
	v_and_b32_e32 v23, 0xffff0000, v23
	v_and_b32_e32 v25, 0xffff0000, v25
	v_and_b32_e32 v27, 0xffff0000, v27
	v_and_b32_e32 v29, 0xffff0000, v29
	v_or_b32_sdwa v76, v23, v22 dst_sel:DWORD dst_unused:UNUSED_PAD src0_sel:DWORD src1_sel:WORD_1
	v_or_b32_sdwa v77, v25, v24 dst_sel:DWORD dst_unused:UNUSED_PAD src0_sel:DWORD src1_sel:WORD_1
	v_or_b32_sdwa v78, v27, v26 dst_sel:DWORD dst_unused:UNUSED_PAD src0_sel:DWORD src1_sel:WORD_1
	v_or_b32_sdwa v79, v29, v28 dst_sel:DWORD dst_unused:UNUSED_PAD src0_sel:DWORD src1_sel:WORD_1
	global_store_dwordx4 v58, v[76:79], s[56:57] nt
	s_waitcnt vmcnt(7) lgkmcnt(4)
	v_fmamk_f32 v54, v11, 0x3a800000, v13
	v_rsq_f32_e32 v54, v54
	v_add_u32_e32 v57, 0xc0000, v4
	v_mul_f32_e32 v30, v30, v54
	v_mul_f32_e32 v31, v31, v54
	v_mul_f32_e32 v32, v32, v54
	v_mul_f32_e32 v33, v33, v54
	v_mul_f32_e32 v34, v34, v54
	v_mul_f32_e32 v35, v35, v54
	v_mul_f32_e32 v36, v36, v54
	v_mul_f32_e32 v37, v37, v54
	v_max_f32_e32 v30, 0, v30
	v_max_f32_e32 v31, 0, v31
	v_max_f32_e32 v32, 0, v32
	v_max_f32_e32 v33, 0, v33
	v_max_f32_e32 v34, 0, v34
	v_max_f32_e32 v35, 0, v35
	v_max_f32_e32 v36, 0, v36
	v_max_f32_e32 v37, 0, v37
	v_pk_mul_f32 v[30:31], v[30:31], v[30:31]
	v_pk_mul_f32 v[32:33], v[32:33], v[32:33]
	v_pk_mul_f32 v[34:35], v[34:35], v[34:35]
	v_pk_mul_f32 v[36:37], v[36:37], v[36:37]
	v_and_b32_sdwa v46, v30, v59 dst_sel:DWORD dst_unused:UNUSED_PAD src0_sel:WORD_1 src1_sel:DWORD
	v_and_b32_sdwa v47, v31, v59 dst_sel:DWORD dst_unused:UNUSED_PAD src0_sel:WORD_1 src1_sel:DWORD
	v_and_b32_sdwa v48, v32, v59 dst_sel:DWORD dst_unused:UNUSED_PAD src0_sel:WORD_1 src1_sel:DWORD
	v_and_b32_sdwa v49, v33, v59 dst_sel:DWORD dst_unused:UNUSED_PAD src0_sel:WORD_1 src1_sel:DWORD
	v_and_b32_sdwa v50, v34, v59 dst_sel:DWORD dst_unused:UNUSED_PAD src0_sel:WORD_1 src1_sel:DWORD
	v_and_b32_sdwa v51, v35, v59 dst_sel:DWORD dst_unused:UNUSED_PAD src0_sel:WORD_1 src1_sel:DWORD
	v_and_b32_sdwa v52, v36, v59 dst_sel:DWORD dst_unused:UNUSED_PAD src0_sel:WORD_1 src1_sel:DWORD
	v_and_b32_sdwa v53, v37, v59 dst_sel:DWORD dst_unused:UNUSED_PAD src0_sel:WORD_1 src1_sel:DWORD
	v_add3_u32 v30, v30, v46, s24
	v_add3_u32 v31, v31, v47, s24
	v_add3_u32 v32, v32, v48, s24
	v_add3_u32 v33, v33, v49, s24
	v_add3_u32 v34, v34, v50, s24
	v_add3_u32 v35, v35, v51, s24
	v_add3_u32 v36, v36, v52, s24
	v_add3_u32 v37, v37, v53, s24
	v_and_b32_e32 v31, 0xffff0000, v31
	v_and_b32_e32 v33, 0xffff0000, v33
	v_and_b32_e32 v35, 0xffff0000, v35
	v_and_b32_e32 v37, 0xffff0000, v37
	v_or_b32_sdwa v60, v31, v30 dst_sel:DWORD dst_unused:UNUSED_PAD src0_sel:DWORD src1_sel:WORD_1
	v_or_b32_sdwa v61, v33, v32 dst_sel:DWORD dst_unused:UNUSED_PAD src0_sel:DWORD src1_sel:WORD_1
	v_or_b32_sdwa v62, v35, v34 dst_sel:DWORD dst_unused:UNUSED_PAD src0_sel:DWORD src1_sel:WORD_1
	v_or_b32_sdwa v63, v37, v36 dst_sel:DWORD dst_unused:UNUSED_PAD src0_sel:DWORD src1_sel:WORD_1
	global_store_dwordx4 v57, v[60:63], s[56:57] nt
	s_waitcnt vmcnt(7) lgkmcnt(0)
	v_fmamk_f32 v54, v12, 0x3a800000, v13
	v_rsq_f32_e32 v54, v54
	v_add_u32_e32 v58, 0xe0000, v4
	v_mul_f32_e32 v38, v38, v54
	v_mul_f32_e32 v39, v39, v54
	v_mul_f32_e32 v40, v40, v54
	v_mul_f32_e32 v41, v41, v54
	v_mul_f32_e32 v42, v42, v54
	v_mul_f32_e32 v43, v43, v54
	v_mul_f32_e32 v44, v44, v54
	v_mul_f32_e32 v45, v45, v54
	v_max_f32_e32 v38, 0, v38
	v_max_f32_e32 v39, 0, v39
	v_max_f32_e32 v40, 0, v40
	v_max_f32_e32 v41, 0, v41
	v_max_f32_e32 v42, 0, v42
	v_max_f32_e32 v43, 0, v43
	v_max_f32_e32 v44, 0, v44
	v_max_f32_e32 v45, 0, v45
	v_pk_mul_f32 v[38:39], v[38:39], v[38:39]
	v_pk_mul_f32 v[40:41], v[40:41], v[40:41]
	v_pk_mul_f32 v[42:43], v[42:43], v[42:43]
	v_pk_mul_f32 v[44:45], v[44:45], v[44:45]
	v_and_b32_sdwa v46, v38, v59 dst_sel:DWORD dst_unused:UNUSED_PAD src0_sel:WORD_1 src1_sel:DWORD
	v_and_b32_sdwa v47, v39, v59 dst_sel:DWORD dst_unused:UNUSED_PAD src0_sel:WORD_1 src1_sel:DWORD
	v_and_b32_sdwa v48, v40, v59 dst_sel:DWORD dst_unused:UNUSED_PAD src0_sel:WORD_1 src1_sel:DWORD
	v_and_b32_sdwa v49, v41, v59 dst_sel:DWORD dst_unused:UNUSED_PAD src0_sel:WORD_1 src1_sel:DWORD
	v_and_b32_sdwa v50, v42, v59 dst_sel:DWORD dst_unused:UNUSED_PAD src0_sel:WORD_1 src1_sel:DWORD
	v_and_b32_sdwa v51, v43, v59 dst_sel:DWORD dst_unused:UNUSED_PAD src0_sel:WORD_1 src1_sel:DWORD
	v_and_b32_sdwa v52, v44, v59 dst_sel:DWORD dst_unused:UNUSED_PAD src0_sel:WORD_1 src1_sel:DWORD
	v_and_b32_sdwa v53, v45, v59 dst_sel:DWORD dst_unused:UNUSED_PAD src0_sel:WORD_1 src1_sel:DWORD
	v_add3_u32 v38, v38, v46, s24
	v_add3_u32 v39, v39, v47, s24
	v_add3_u32 v40, v40, v48, s24
	v_add3_u32 v41, v41, v49, s24
	v_add3_u32 v42, v42, v50, s24
	v_add3_u32 v43, v43, v51, s24
	v_add3_u32 v44, v44, v52, s24
	v_add3_u32 v45, v45, v53, s24
	v_and_b32_e32 v39, 0xffff0000, v39
	v_and_b32_e32 v41, 0xffff0000, v41
	v_and_b32_e32 v43, 0xffff0000, v43
	v_and_b32_e32 v45, 0xffff0000, v45
	v_or_b32_sdwa v76, v39, v38 dst_sel:DWORD dst_unused:UNUSED_PAD src0_sel:DWORD src1_sel:WORD_1
	v_or_b32_sdwa v77, v41, v40 dst_sel:DWORD dst_unused:UNUSED_PAD src0_sel:DWORD src1_sel:WORD_1
	v_or_b32_sdwa v78, v43, v42 dst_sel:DWORD dst_unused:UNUSED_PAD src0_sel:DWORD src1_sel:WORD_1
	v_or_b32_sdwa v79, v45, v44 dst_sel:DWORD dst_unused:UNUSED_PAD src0_sel:DWORD src1_sel:WORD_1
	global_store_dwordx4 v58, v[76:79], s[56:57] nt
	s_cmpk_lt_u32 s12, 0x400
	s_barrier
	s_cbranch_scc1 .LBB0_590
